# K-loop LDS-read rebalancing 12/4/8/0 -> 8/4/8/4 in 7 GEMM loops (B0 fragment quad issued one phase earlier, vmcnt(10) guard), plus Mx rewrite
# speedup vs baseline: 1.0067x; 1.0067x over previous
; #define PG8_STAGE_A(bufoff, ptr, half, rev) do { if (REVA && (rev)) { const char* _p = (ptr) - ((half) ? hstepA : 0); PG8_STAGE(bufoff, _p, voffAr); } else { const char* _p = (ptr) + ((half) ? hstepA : 0); PG8_STAGE(bufoff, _p, voffA); } } while (0)
; #define PG8_LDA(dst, b, h) do { _Pragma("unroll") for (int m = 0; m < 4; ++m) _Pragma("unroll") for (int k = 0; k < 2; ++k) dst[m][k] = *(const LAS bf16x8*)(lds + PG8_SA(b, h) + aoff + m * 2048 + k * 1024); } while (0)
; #define PG8_LDB(dst, b, h) do { _Pragma("unroll") for (int n = 0; n < 2; ++n) _Pragma("unroll") for (int k = 0; k < 2; ++k) dst[n][k] = *(const LAS bf16x8*)(lds + PG8_SB(b, h) + boff + n * 2048 + k * 1024); } while (0)
; #define PG8_WAIT_L(n) asm volatile("s_waitcnt lgkmcnt(" #n ")" ::: "memory")
; #define PG8_BAR __builtin_amdgcn_s_barrier()
; #define PG8_SCHED __builtin_amdgcn_sched_barrier(0)
;     ...
;     for (;;) {
;         const bool has_next = next_unit(ui + 1, nM, nN, MP, nxt, rot);
;         const char* nA = has_next ? nxt.a : cA; const char* nB = has_next ? nxt.b : cB; const char* nAr = has_next ? nxt.ar : cAr; const size_t nHb = has_next ? nxt.hb : cHb;
;         for (int t = 0; t < nt; t += 2) {
;             const bool last = (t == nt - 2);
;             const char* a1 = PG8_APTR(cA, cAr, t + 1); const bool r1 = REVA && ((t + 1) & 4);
;             const char* a2 = last ? nA : PG8_APTR(cA, cAr, t + 2); const bool r2 = REVA && !last && ((t + 2) & 4);
;             const char* a3 = last ? nA + kstep : PG8_APTR(cA, cAr, t + 3); const bool r3 = REVA && !last && ((t + 3) & 4);
;             const char* b2 = last ? nB : cB + (size_t)(t + 2) * kstep; const char* b3 = b2 + kstep; const size_t hb2 = last ? nHb : cHb;
;             PG8_LDB(B0, 0, 0); PG8_SCHED; PG8_LDA(At, 0, 0); PG8_STAGE_A(PG8_SA(1, 1), a1, 1, r1);
;             PG8_WAIT_L(8); PG8_BAR; PG8_WAIT_L(0); PG8_MMA(0, 0, At, B0); PG8_BAR; PG8_SCHED;
;     ...
; #pragma unroll
;         for (int a = 0; a < 2; ++a)
; #pragma unroll
;             for (int b = 0; b < 2; ++b)
; #pragma unroll
;                 for (int m = 0; m < 4; ++m)
; #pragma unroll
;                     for (int n = 0; n < 2; ++n) acc[a][b][m][n] = (f32x4){0.f, 0.f, 0.f, 0.f};
;         cur = nxt; cA = nA; cB = nB; cAr = nAr; cHb = nHb; ++ui;
.LBB0_233:
	s_add_u32 s3, s0, 0x80
	s_addc_u32 s6, s1, 0
	s_add_u32 s8, s38, 0x80080
	s_addc_u32 s9, s39, 0
	s_add_u32 s7, s20, 0x100
	v_mov_b32_e32 v0, 0
	v_lshl_add_u64 v[88:89], s[8:9], 0, v[150:151]
	v_lshl_add_u64 v[90:91], s[8:9], 0, v[152:153]
	s_addc_u32 s8, s21, 0
	s_mov_b32 s9, -2
	s_mov_b64 vcc, 0
	v_mov_b32_e32 v1, v0
	v_mov_b32_e32 v2, v0
	v_mov_b32_e32 v3, v0
	v_mov_b32_e32 v32, v0
	v_mov_b32_e32 v33, v0
	v_mov_b32_e32 v34, v0
	v_mov_b32_e32 v35, v0
	v_mov_b32_e32 v8, v0
	v_mov_b32_e32 v9, v0
	v_mov_b32_e32 v10, v0
	v_mov_b32_e32 v11, v0
	v_mov_b32_e32 v40, v0
	v_mov_b32_e32 v41, v0
	v_mov_b32_e32 v42, v0
	v_mov_b32_e32 v43, v0
	v_mov_b32_e32 v16, v0
	v_mov_b32_e32 v17, v0
	v_mov_b32_e32 v18, v0
	v_mov_b32_e32 v19, v0
	v_mov_b32_e32 v48, v0
	v_mov_b32_e32 v49, v0
	v_mov_b32_e32 v50, v0
	v_mov_b32_e32 v51, v0
	v_mov_b32_e32 v24, v0
	v_mov_b32_e32 v25, v0
	v_mov_b32_e32 v26, v0
	v_mov_b32_e32 v27, v0
	v_mov_b32_e32 v56, v0
	v_mov_b32_e32 v57, v0
	v_mov_b32_e32 v58, v0
	v_mov_b32_e32 v59, v0
	v_mov_b32_e32 v36, v0
	v_mov_b32_e32 v37, v0
	v_mov_b32_e32 v38, v0
	v_mov_b32_e32 v39, v0
	v_mov_b32_e32 v4, v0
	v_mov_b32_e32 v5, v0
	v_mov_b32_e32 v6, v0
	v_mov_b32_e32 v7, v0
	v_mov_b32_e32 v44, v0
	v_mov_b32_e32 v45, v0
	v_mov_b32_e32 v46, v0
	v_mov_b32_e32 v47, v0
	v_mov_b32_e32 v12, v0
	v_mov_b32_e32 v13, v0
	v_mov_b32_e32 v14, v0
	v_mov_b32_e32 v15, v0
	v_mov_b32_e32 v52, v0
	v_mov_b32_e32 v53, v0
	v_mov_b32_e32 v54, v0
	v_mov_b32_e32 v55, v0
	v_mov_b32_e32 v20, v0
	v_mov_b32_e32 v21, v0
	v_mov_b32_e32 v22, v0
	v_mov_b32_e32 v23, v0
	v_mov_b32_e32 v60, v0
	v_mov_b32_e32 v61, v0
	v_mov_b32_e32 v62, v0
	v_mov_b32_e32 v63, v0
	v_mov_b32_e32 v28, v0
	v_mov_b32_e32 v29, v0
	v_mov_b32_e32 v30, v0
	v_mov_b32_e32 v31, v0
	v_mov_b32_e32 v64, v0
	v_mov_b32_e32 v65, v0
	v_mov_b32_e32 v66, v0
	v_mov_b32_e32 v67, v0
	v_mov_b32_e32 v108, v0
	v_mov_b32_e32 v109, v0
	v_mov_b32_e32 v110, v0
	v_mov_b32_e32 v111, v0
	v_mov_b32_e32 v72, v0
	v_mov_b32_e32 v73, v0
	v_mov_b32_e32 v74, v0
	v_mov_b32_e32 v75, v0
	v_mov_b32_e32 v116, v0
	v_mov_b32_e32 v117, v0
	v_mov_b32_e32 v118, v0
	v_mov_b32_e32 v119, v0
	v_mov_b32_e32 v80, v0
	v_mov_b32_e32 v81, v0
	v_mov_b32_e32 v82, v0
	v_mov_b32_e32 v83, v0
	v_mov_b32_e32 v124, v0
	v_mov_b32_e32 v125, v0
	v_mov_b32_e32 v126, v0
	v_mov_b32_e32 v127, v0
	v_mov_b32_e32 v100, v0
	v_mov_b32_e32 v101, v0
	v_mov_b32_e32 v102, v0
	v_mov_b32_e32 v103, v0
	v_mov_b32_e32 v132, v0
	v_mov_b32_e32 v133, v0
	v_mov_b32_e32 v134, v0
	v_mov_b32_e32 v135, v0
	v_mov_b32_e32 v112, v0
	v_mov_b32_e32 v113, v0
	v_mov_b32_e32 v114, v0
	v_mov_b32_e32 v115, v0
	v_mov_b32_e32 v68, v0
	v_mov_b32_e32 v69, v0
	v_mov_b32_e32 v70, v0
	v_mov_b32_e32 v71, v0
	v_mov_b32_e32 v120, v0
	v_mov_b32_e32 v121, v0
	v_mov_b32_e32 v122, v0
	v_mov_b32_e32 v123, v0
	v_mov_b32_e32 v76, v0
	v_mov_b32_e32 v77, v0
	v_mov_b32_e32 v78, v0
	v_mov_b32_e32 v79, v0
	v_mov_b32_e32 v128, v0
	v_mov_b32_e32 v129, v0
	v_mov_b32_e32 v130, v0
	v_mov_b32_e32 v131, v0
	v_mov_b32_e32 v84, v0
	v_mov_b32_e32 v85, v0
	v_mov_b32_e32 v86, v0
	v_mov_b32_e32 v87, v0
	v_mov_b32_e32 v136, v0
	v_mov_b32_e32 v137, v0
	v_mov_b32_e32 v138, v0
	v_mov_b32_e32 v139, v0
	v_mov_b32_e32 v104, v0
	v_mov_b32_e32 v105, v0
	v_mov_b32_e32 v106, v0
	v_mov_b32_e32 v107, v0
	v_add_u32_e32 v154, 0x10000, v156
	ds_read_b128 v[92:95], v154
	ds_read_b128 v[96:99], v154 offset:1024
	ds_read_b128 v[172:175], v154 offset:2048
	ds_read_b128 v[176:179], v154 offset:3072
.LBB0_234:
	s_add_u32 s10, s38, vcc_lo
	s_addc_u32 s11, s39, vcc_hi
	s_add_u32 s16, s10, 0x100
	s_addc_u32 s17, s11, 0
	s_add_u32 s10, s10, 0x180
	s_addc_u32 s11, s11, 0
	s_add_u32 s14, s7, vcc_lo
	s_addc_u32 s15, s8, vcc_hi
	s_add_i32 s27, 0, 0x10000
	s_cmpk_eq_i32 vcc_lo, 0xf00
	s_cselect_b32 s15, s71, s15
	s_cselect_b32 s14, s70, s14
	s_cselect_b32 s21, s1, s17
	s_cselect_b32 s20, s0, s16
	s_cselect_b32 s17, s6, s11
	s_cselect_b32 s16, s3, s10
	v_lshl_add_u64 v[154:155], v[88:89], 0, vcc
	s_add_i32 m0, s91, 0xc000
	ds_read_b128 v[180:183], v171
	ds_read_b128 v[204:207], v171 offset:1024
	ds_read_b128 v[208:211], v171 offset:2048
	ds_read_b128 v[212:215], v171 offset:3072
	ds_read_b128 v[216:219], v171 offset:4096
	ds_read_b128 v[220:223], v171 offset:5120
	ds_read_b128 v[224:227], v171 offset:6144
	ds_read_b128 v[228:231], v171 offset:7168
	global_load_lds_dwordx4 v[154:155], off
	v_lshl_add_u64 v[154:155], v[90:91], 0, vcc
	s_add_i32 m0, s91, 0xe000
	s_nop 0
	global_load_lds_dwordx4 v[154:155], off
	s_waitcnt lgkmcnt(8)
	s_barrier
	s_waitcnt lgkmcnt(0)
	s_setprio 1
	s_waitcnt lgkmcnt(0)
	v_mfma_f32_16x16x32_bf16 v[104:107], v[92:95], v[180:183], v[104:107]
	v_mfma_f32_16x16x32_bf16 v[136:139], v[172:175], v[180:183], v[136:139]
	v_mfma_f32_16x16x32_bf16 v[84:87], v[92:95], v[208:211], v[84:87]
	v_mfma_f32_16x16x32_bf16 v[128:131], v[172:175], v[208:211], v[128:131]
	v_mfma_f32_16x16x32_bf16 v[76:79], v[92:95], v[216:219], v[76:79]
	v_mfma_f32_16x16x32_bf16 v[120:123], v[172:175], v[216:219], v[120:123]
	v_mfma_f32_16x16x32_bf16 v[68:71], v[92:95], v[224:227], v[68:71]
	v_mfma_f32_16x16x32_bf16 v[112:115], v[172:175], v[224:227], v[112:115]
	v_mfma_f32_16x16x32_bf16 v[104:107], v[96:99], v[204:207], v[104:107]
	v_mfma_f32_16x16x32_bf16 v[136:139], v[176:179], v[204:207], v[136:139]
	v_mfma_f32_16x16x32_bf16 v[84:87], v[96:99], v[212:215], v[84:87]
	v_mfma_f32_16x16x32_bf16 v[128:131], v[176:179], v[212:215], v[128:131]
	v_mfma_f32_16x16x32_bf16 v[76:79], v[96:99], v[220:223], v[76:79]
	v_mfma_f32_16x16x32_bf16 v[120:123], v[176:179], v[220:223], v[120:123]
	v_mfma_f32_16x16x32_bf16 v[68:71], v[96:99], v[228:231], v[68:71]
	v_mfma_f32_16x16x32_bf16 v[112:115], v[176:179], v[228:231], v[112:115]
	s_setprio 0
	s_barrier
; #define PG8_STAGE(bufoff, gbase, voff) do { _Pragma("unroll") for (int _i = 0; _i < 2; ++_i) \
;         __builtin_amdgcn_global_load_lds((const unsigned*)((const char*)(gbase) + (voff)[_i]), (LAS unsigned*)(lds + (bufoff) + ldsw + _i * 8192), 16, 0, 0); } while (0)
; #define PG8_STAGE_A(bufoff, ptr, half, rev) do { if (REVA && (rev)) { const char* _p = (ptr) - ((half) ? hstepA : 0); PG8_STAGE(bufoff, _p, voffAr); } else { const char* _p = (ptr) + ((half) ? hstepA : 0); PG8_STAGE(bufoff, _p, voffA); } } while (0)
; #define PG8_LDA(dst, b, h) do { _Pragma("unroll") for (int m = 0; m < 4; ++m) _Pragma("unroll") for (int k = 0; k < 2; ++k) dst[m][k] = *(const LAS bf16x8*)(lds + PG8_SA(b, h) + aoff + m * 2048 + k * 1024); } while (0)
; #define PG8_LDB(dst, b, h) do { _Pragma("unroll") for (int n = 0; n < 2; ++n) _Pragma("unroll") for (int k = 0; k < 2; ++k) dst[n][k] = *(const LAS bf16x8*)(lds + PG8_SB(b, h) + boff + n * 2048 + k * 1024); } while (0)
; #define PG8_MMA(ai, bj, At, Bt) do { __builtin_amdgcn_s_setprio(1); _Pragma("unroll") for (int m = 0; m < 4; ++m) _Pragma("unroll") for (int n = 0; n < 2; ++n) _Pragma("unroll") for (int k = 0; k < 2; ++k) \
;         acc[ai][bj][m][n] = __builtin_amdgcn_mfma_f32_16x16x32_bf16(Bt[n][k], At[m][k], acc[ai][bj][m][n], 0, 0, 0); __builtin_amdgcn_s_setprio(0); } while (0)
; #define PG8_WAIT_V(n) asm volatile("s_waitcnt vmcnt(" #n ")" ::: "memory")
; #define PG8_WAIT_L(n) asm volatile("s_waitcnt lgkmcnt(" #n ")" ::: "memory")
; #define PG8_BAR __builtin_amdgcn_s_barrier()
; #define PG8_SCHED __builtin_amdgcn_sched_barrier(0)
;     ...
;             PG8_LDB(B1, 0, 1); PG8_STAGE(PG8_SB(0, 0), b2, voffB);
;             PG8_BAR; PG8_WAIT_L(0); PG8_MMA(0, 1, At, B1); PG8_BAR;
;             PG8_LDA(At, 0, 1); PG8_STAGE_A(PG8_SA(0, 0), a2, 0, r2);
;             PG8_BAR; PG8_WAIT_L(0); PG8_MMA(1, 0, At, B0); PG8_BAR; PG8_SCHED;
;             PG8_STAGE(PG8_SB(0, 1), b2 + hb2, voffB);
;             PG8_WAIT_V(6); PG8_BAR; PG8_MMA(1, 1, At, B1); PG8_BAR;
;             PG8_LDB(B0, 1, 0); PG8_SCHED; PG8_LDA(At, 1, 0); PG8_STAGE_A(PG8_SA(0, 1), a2, 1, r2);
	s_add_i32 s37, 0, 0x14000
	v_add_u32_e32 v154, s37, v156
	s_add_i32 s10, s27, s90
	ds_read_b128 v[232:235], v154
	ds_read_b128 v[236:239], v154 offset:1024
	ds_read_b128 v[240:243], v154 offset:2048
	ds_read_b128 v[244:247], v154 offset:3072
	v_lshl_add_u64 v[154:155], s[14:15], 0, v[160:161]
	s_mov_b32 m0, s10
	v_lshl_add_u64 v[184:185], s[14:15], 0, v[140:141]
	global_load_lds_dwordx4 v[154:155], off
	s_add_i32 m0, s10, 0x2000
	s_nop 0
	global_load_lds_dwordx4 v[184:185], off
	s_barrier
	s_waitcnt lgkmcnt(0)
	s_setprio 1
	s_waitcnt lgkmcnt(0)
	v_mfma_f32_16x16x32_bf16 v[132:135], v[232:235], v[180:183], v[132:135]
	v_mfma_f32_16x16x32_bf16 v[100:103], v[240:243], v[180:183], v[100:103]
	v_mfma_f32_16x16x32_bf16 v[124:127], v[232:235], v[208:211], v[124:127]
	v_mfma_f32_16x16x32_bf16 v[80:83], v[240:243], v[208:211], v[80:83]
	v_mfma_f32_16x16x32_bf16 v[116:119], v[232:235], v[216:219], v[116:119]
	v_mfma_f32_16x16x32_bf16 v[72:75], v[240:243], v[216:219], v[72:75]
	v_mfma_f32_16x16x32_bf16 v[108:111], v[232:235], v[224:227], v[108:111]
	v_mfma_f32_16x16x32_bf16 v[64:67], v[240:243], v[224:227], v[64:67]
	v_mfma_f32_16x16x32_bf16 v[132:135], v[236:239], v[204:207], v[132:135]
	v_mfma_f32_16x16x32_bf16 v[100:103], v[244:247], v[204:207], v[100:103]
	v_mfma_f32_16x16x32_bf16 v[124:127], v[236:239], v[212:215], v[124:127]
	v_mfma_f32_16x16x32_bf16 v[80:83], v[244:247], v[212:215], v[80:83]
	v_mfma_f32_16x16x32_bf16 v[116:119], v[236:239], v[220:223], v[116:119]
	v_mfma_f32_16x16x32_bf16 v[72:75], v[244:247], v[220:223], v[72:75]
	v_mfma_f32_16x16x32_bf16 v[108:111], v[236:239], v[228:231], v[108:111]
	v_mfma_f32_16x16x32_bf16 v[64:67], v[244:247], v[228:231], v[64:67]
	s_setprio 0
	s_mov_b32 m0, s91
	v_lshl_add_u64 v[190:191], s[20:21], 0, v[160:161]
	s_barrier
	ds_read_b128 v[180:183], v171 offset:16384
	ds_read_b128 v[204:207], v171 offset:17408
	ds_read_b128 v[208:211], v171 offset:18432
	ds_read_b128 v[212:215], v171 offset:19456
	ds_read_b128 v[216:219], v171 offset:20480
	ds_read_b128 v[220:223], v171 offset:21504
	ds_read_b128 v[224:227], v171 offset:22528
	ds_read_b128 v[228:231], v171 offset:23552
	global_load_lds_dwordx4 v[190:191], off
	v_lshl_add_u64 v[190:191], s[20:21], 0, v[140:141]
	s_mov_b32 m0, s92
	s_nop 0
	global_load_lds_dwordx4 v[190:191], off
	s_waitcnt vmcnt(10)
	s_barrier
	s_waitcnt lgkmcnt(0)
	s_setprio 1
	s_waitcnt lgkmcnt(0)
	v_mfma_f32_16x16x32_bf16 v[28:31], v[92:95], v[180:183], v[28:31]
	v_mfma_f32_16x16x32_bf16 v[60:63], v[172:175], v[180:183], v[60:63]
	v_mfma_f32_16x16x32_bf16 v[20:23], v[92:95], v[208:211], v[20:23]
	v_mfma_f32_16x16x32_bf16 v[52:55], v[172:175], v[208:211], v[52:55]
	v_mfma_f32_16x16x32_bf16 v[12:15], v[92:95], v[216:219], v[12:15]
	v_mfma_f32_16x16x32_bf16 v[44:47], v[172:175], v[216:219], v[44:47]
	v_mfma_f32_16x16x32_bf16 v[4:7], v[92:95], v[224:227], v[4:7]
	v_mfma_f32_16x16x32_bf16 v[36:39], v[172:175], v[224:227], v[36:39]
	v_mfma_f32_16x16x32_bf16 v[28:31], v[96:99], v[204:207], v[28:31]
	v_mfma_f32_16x16x32_bf16 v[60:63], v[176:179], v[204:207], v[60:63]
	v_mfma_f32_16x16x32_bf16 v[20:23], v[96:99], v[212:215], v[20:23]
	v_mfma_f32_16x16x32_bf16 v[52:55], v[176:179], v[212:215], v[52:55]
	v_mfma_f32_16x16x32_bf16 v[12:15], v[96:99], v[220:223], v[12:15]
	v_mfma_f32_16x16x32_bf16 v[44:47], v[176:179], v[220:223], v[44:47]
	v_mfma_f32_16x16x32_bf16 v[4:7], v[96:99], v[228:231], v[4:7]
	v_mfma_f32_16x16x32_bf16 v[36:39], v[176:179], v[228:231], v[36:39]
	s_setprio 0
	s_barrier
	s_add_u32 s10, s14, 0x80000
	s_addc_u32 s11, s15, 0
	s_add_i32 s27, s37, s90
	v_lshl_add_u64 v[92:93], s[10:11], 0, v[160:161]
	s_mov_b32 m0, s27
	s_nop 0
	global_load_lds_dwordx4 v[92:93], off
	v_lshl_add_u64 v[92:93], s[10:11], 0, v[140:141]
	s_add_i32 m0, s27, 0x2000
	s_nop 0
	global_load_lds_dwordx4 v[92:93], off
	v_add_u32_e32 v176, 0x18000, v156
	ds_read_b128 v[92:95], v176
	ds_read_b128 v[96:99], v176 offset:1024
	ds_read_b128 v[172:175], v176 offset:2048
	ds_read_b128 v[176:179], v176 offset:3072
	s_waitcnt vmcnt(6)
	s_barrier
	s_setprio 1
	v_mfma_f32_16x16x32_bf16 v[56:59], v[232:235], v[180:183], v[56:59]
	v_mfma_f32_16x16x32_bf16 v[24:27], v[240:243], v[180:183], v[24:27]
	v_mfma_f32_16x16x32_bf16 v[48:51], v[232:235], v[208:211], v[48:51]
	v_mfma_f32_16x16x32_bf16 v[16:19], v[240:243], v[208:211], v[16:19]
	v_mfma_f32_16x16x32_bf16 v[40:43], v[232:235], v[216:219], v[40:43]
	v_mfma_f32_16x16x32_bf16 v[8:11], v[240:243], v[216:219], v[8:11]
	v_mfma_f32_16x16x32_bf16 v[32:35], v[232:235], v[224:227], v[32:35]
	v_mfma_f32_16x16x32_bf16 v[0:3], v[240:243], v[224:227], v[0:3]
	v_mfma_f32_16x16x32_bf16 v[56:59], v[236:239], v[204:207], v[56:59]
	v_mfma_f32_16x16x32_bf16 v[24:27], v[244:247], v[204:207], v[24:27]
	v_mfma_f32_16x16x32_bf16 v[48:51], v[236:239], v[212:215], v[48:51]
	v_mfma_f32_16x16x32_bf16 v[16:19], v[244:247], v[212:215], v[16:19]
	v_mfma_f32_16x16x32_bf16 v[40:43], v[236:239], v[220:223], v[40:43]
	v_mfma_f32_16x16x32_bf16 v[8:11], v[244:247], v[220:223], v[8:11]
	v_mfma_f32_16x16x32_bf16 v[32:35], v[236:239], v[228:231], v[32:35]
	v_mfma_f32_16x16x32_bf16 v[0:3], v[244:247], v[228:231], v[0:3]
	s_setprio 0
	s_add_i32 s27, 0, 0x18000
	s_barrier
	s_add_u32 s10, s20, 0x80000
	s_addc_u32 s11, s21, 0
	s_mov_b32 m0, s93
	v_lshl_add_u64 v[190:191], s[10:11], 0, v[160:161]
	ds_read_b128 v[180:183], v171 offset:32768
	ds_read_b128 v[204:207], v171 offset:33792
	ds_read_b128 v[208:211], v171 offset:34816
	ds_read_b128 v[212:215], v171 offset:35840
	ds_read_b128 v[216:219], v171 offset:36864
	ds_read_b128 v[220:223], v171 offset:37888
	ds_read_b128 v[224:227], v171 offset:38912
	ds_read_b128 v[228:231], v171 offset:39936
	global_load_lds_dwordx4 v[190:191], off
	v_lshl_add_u64 v[190:191], s[10:11], 0, v[140:141]
	s_mov_b32 m0, s94
	s_nop 0
	global_load_lds_dwordx4 v[190:191], off
	s_waitcnt lgkmcnt(8)
	s_barrier
; #define PG8_STAGE(bufoff, gbase, voff) do { _Pragma("unroll") for (int _i = 0; _i < 2; ++_i) \
;         __builtin_amdgcn_global_load_lds((const unsigned*)((const char*)(gbase) + (voff)[_i]), (LAS unsigned*)(lds + (bufoff) + ldsw + _i * 8192), 16, 0, 0); } while (0)
; #define PG8_STAGE_A(bufoff, ptr, half, rev) do { if (REVA && (rev)) { const char* _p = (ptr) - ((half) ? hstepA : 0); PG8_STAGE(bufoff, _p, voffAr); } else { const char* _p = (ptr) + ((half) ? hstepA : 0); PG8_STAGE(bufoff, _p, voffA); } } while (0)
; #define PG8_LDA(dst, b, h) do { _Pragma("unroll") for (int m = 0; m < 4; ++m) _Pragma("unroll") for (int k = 0; k < 2; ++k) dst[m][k] = *(const LAS bf16x8*)(lds + PG8_SA(b, h) + aoff + m * 2048 + k * 1024); } while (0)
; #define PG8_LDB(dst, b, h) do { _Pragma("unroll") for (int n = 0; n < 2; ++n) _Pragma("unroll") for (int k = 0; k < 2; ++k) dst[n][k] = *(const LAS bf16x8*)(lds + PG8_SB(b, h) + boff + n * 2048 + k * 1024); } while (0)
; #define PG8_MMA(ai, bj, At, Bt) do { __builtin_amdgcn_s_setprio(1); _Pragma("unroll") for (int m = 0; m < 4; ++m) _Pragma("unroll") for (int n = 0; n < 2; ++n) _Pragma("unroll") for (int k = 0; k < 2; ++k) \
;         acc[ai][bj][m][n] = __builtin_amdgcn_mfma_f32_16x16x32_bf16(Bt[n][k], At[m][k], acc[ai][bj][m][n], 0, 0, 0); __builtin_amdgcn_s_setprio(0); } while (0)
; #define PG8_WAIT_V(n) asm volatile("s_waitcnt vmcnt(" #n ")" ::: "memory")
; #define PG8_WAIT_L(n) asm volatile("s_waitcnt lgkmcnt(" #n ")" ::: "memory")
; #define PG8_BAR __builtin_amdgcn_s_barrier()
; #define PG8_SCHED __builtin_amdgcn_sched_barrier(0)
;     ...
;             PG8_LDB(B0, 1, 0); PG8_SCHED; PG8_LDA(At, 1, 0); PG8_STAGE_A(PG8_SA(0, 1), a2, 1, r2);
;             PG8_WAIT_L(8); PG8_BAR; PG8_WAIT_L(0); PG8_MMA(0, 0, At, B0); PG8_BAR; PG8_SCHED;
;             PG8_LDB(B1, 1, 1); PG8_STAGE(PG8_SB(1, 0), b3, voffB);
;             PG8_BAR; PG8_WAIT_L(0); PG8_MMA(0, 1, At, B1); PG8_BAR;
;             PG8_LDA(At, 1, 1); PG8_STAGE_A(PG8_SA(1, 0), a3, 0, r3);
;             PG8_BAR; PG8_WAIT_L(0); PG8_MMA(1, 0, At, B0); PG8_BAR; PG8_SCHED;
;             PG8_STAGE(PG8_SB(1, 1), b3 + hb2, voffB);
;             PG8_WAIT_V(6); PG8_BAR; PG8_MMA(1, 1, At, B1); PG8_BAR;
	s_waitcnt lgkmcnt(0)
	s_setprio 1
	s_waitcnt lgkmcnt(0)
	v_mfma_f32_16x16x32_bf16 v[104:107], v[92:95], v[180:183], v[104:107]
	v_mfma_f32_16x16x32_bf16 v[136:139], v[172:175], v[180:183], v[136:139]
	v_mfma_f32_16x16x32_bf16 v[84:87], v[92:95], v[208:211], v[84:87]
	v_mfma_f32_16x16x32_bf16 v[128:131], v[172:175], v[208:211], v[128:131]
	v_mfma_f32_16x16x32_bf16 v[76:79], v[92:95], v[216:219], v[76:79]
	v_mfma_f32_16x16x32_bf16 v[120:123], v[172:175], v[216:219], v[120:123]
	v_mfma_f32_16x16x32_bf16 v[68:71], v[92:95], v[224:227], v[68:71]
	v_mfma_f32_16x16x32_bf16 v[112:115], v[172:175], v[224:227], v[112:115]
	v_mfma_f32_16x16x32_bf16 v[104:107], v[96:99], v[204:207], v[104:107]
	v_mfma_f32_16x16x32_bf16 v[136:139], v[176:179], v[204:207], v[136:139]
	v_mfma_f32_16x16x32_bf16 v[84:87], v[96:99], v[212:215], v[84:87]
	v_mfma_f32_16x16x32_bf16 v[128:131], v[176:179], v[212:215], v[128:131]
	v_mfma_f32_16x16x32_bf16 v[76:79], v[96:99], v[220:223], v[76:79]
	v_mfma_f32_16x16x32_bf16 v[120:123], v[176:179], v[220:223], v[120:123]
	v_mfma_f32_16x16x32_bf16 v[68:71], v[96:99], v[228:231], v[68:71]
	v_mfma_f32_16x16x32_bf16 v[112:115], v[176:179], v[228:231], v[112:115]
	s_setprio 0
	s_barrier
	s_add_i32 s20, 0, 0x1c000
	s_add_i32 s10, s27, s90
	v_add_u32_e32 v190, s20, v156
	v_lshl_add_u64 v[154:155], v[154:155], 0, s[28:29]
	s_mov_b32 m0, s10
	ds_read_b128 v[232:235], v190
	ds_read_b128 v[236:239], v190 offset:1024
	ds_read_b128 v[240:243], v190 offset:2048
	ds_read_b128 v[244:247], v190 offset:3072
	global_load_lds_dwordx4 v[154:155], off
	v_lshl_add_u64 v[154:155], v[184:185], 0, s[28:29]
	s_add_i32 m0, s10, 0x2000
	s_nop 0
	global_load_lds_dwordx4 v[154:155], off
	s_barrier
	s_waitcnt lgkmcnt(0)
	s_setprio 1
	s_waitcnt lgkmcnt(0)
	v_mfma_f32_16x16x32_bf16 v[132:135], v[232:235], v[180:183], v[132:135]
	v_mfma_f32_16x16x32_bf16 v[100:103], v[240:243], v[180:183], v[100:103]
	v_mfma_f32_16x16x32_bf16 v[124:127], v[232:235], v[208:211], v[124:127]
	v_mfma_f32_16x16x32_bf16 v[80:83], v[240:243], v[208:211], v[80:83]
	v_mfma_f32_16x16x32_bf16 v[116:119], v[232:235], v[216:219], v[116:119]
	v_mfma_f32_16x16x32_bf16 v[72:75], v[240:243], v[216:219], v[72:75]
	v_mfma_f32_16x16x32_bf16 v[108:111], v[232:235], v[224:227], v[108:111]
	v_mfma_f32_16x16x32_bf16 v[64:67], v[240:243], v[224:227], v[64:67]
	v_mfma_f32_16x16x32_bf16 v[132:135], v[236:239], v[204:207], v[132:135]
	v_mfma_f32_16x16x32_bf16 v[100:103], v[244:247], v[204:207], v[100:103]
	v_mfma_f32_16x16x32_bf16 v[124:127], v[236:239], v[212:215], v[124:127]
	v_mfma_f32_16x16x32_bf16 v[80:83], v[244:247], v[212:215], v[80:83]
	v_mfma_f32_16x16x32_bf16 v[116:119], v[236:239], v[220:223], v[116:119]
	v_mfma_f32_16x16x32_bf16 v[72:75], v[244:247], v[220:223], v[72:75]
	v_mfma_f32_16x16x32_bf16 v[108:111], v[236:239], v[228:231], v[108:111]
	v_mfma_f32_16x16x32_bf16 v[64:67], v[244:247], v[228:231], v[64:67]
	s_setprio 0
	s_mov_b32 m0, s95
	v_lshl_add_u64 v[154:155], s[16:17], 0, v[160:161]
	s_barrier
	ds_read_b128 v[180:183], v171 offset:49152
	ds_read_b128 v[204:207], v171 offset:50176
	ds_read_b128 v[208:211], v171 offset:51200
	ds_read_b128 v[212:215], v171 offset:52224
	ds_read_b128 v[216:219], v171 offset:53248
	ds_read_b128 v[220:223], v171 offset:54272
	ds_read_b128 v[224:227], v171 offset:55296
	ds_read_b128 v[228:231], v171 offset:56320
	global_load_lds_dwordx4 v[154:155], off
	v_lshl_add_u64 v[154:155], s[16:17], 0, v[140:141]
	s_mov_b32 m0, s96
	s_nop 0
	global_load_lds_dwordx4 v[154:155], off
	s_waitcnt vmcnt(10)
	s_barrier
	s_waitcnt lgkmcnt(0)
	s_setprio 1
	s_waitcnt lgkmcnt(0)
	v_mfma_f32_16x16x32_bf16 v[28:31], v[92:95], v[180:183], v[28:31]
	v_mfma_f32_16x16x32_bf16 v[60:63], v[172:175], v[180:183], v[60:63]
	v_mfma_f32_16x16x32_bf16 v[20:23], v[92:95], v[208:211], v[20:23]
	v_mfma_f32_16x16x32_bf16 v[52:55], v[172:175], v[208:211], v[52:55]
	v_mfma_f32_16x16x32_bf16 v[12:15], v[92:95], v[216:219], v[12:15]
	v_mfma_f32_16x16x32_bf16 v[44:47], v[172:175], v[216:219], v[44:47]
	v_mfma_f32_16x16x32_bf16 v[4:7], v[92:95], v[224:227], v[4:7]
	v_mfma_f32_16x16x32_bf16 v[36:39], v[172:175], v[224:227], v[36:39]
	v_mfma_f32_16x16x32_bf16 v[28:31], v[96:99], v[204:207], v[28:31]
	v_mfma_f32_16x16x32_bf16 v[60:63], v[176:179], v[204:207], v[60:63]
	v_mfma_f32_16x16x32_bf16 v[20:23], v[96:99], v[212:215], v[20:23]
	v_mfma_f32_16x16x32_bf16 v[52:55], v[176:179], v[212:215], v[52:55]
	v_mfma_f32_16x16x32_bf16 v[12:15], v[96:99], v[220:223], v[12:15]
	v_mfma_f32_16x16x32_bf16 v[44:47], v[176:179], v[220:223], v[44:47]
	v_mfma_f32_16x16x32_bf16 v[4:7], v[96:99], v[228:231], v[4:7]
	v_mfma_f32_16x16x32_bf16 v[36:39], v[176:179], v[228:231], v[36:39]
	s_setprio 0
	s_barrier
	s_add_u32 s10, s14, 0x80080
	s_addc_u32 s11, s15, 0
	s_add_i32 s14, s20, s90
	v_lshl_add_u64 v[92:93], s[10:11], 0, v[160:161]
	s_mov_b32 m0, s14
	s_nop 0
	global_load_lds_dwordx4 v[92:93], off
	v_lshl_add_u64 v[92:93], s[10:11], 0, v[140:141]
	s_add_i32 m0, s14, 0x2000
	s_nop 0
	global_load_lds_dwordx4 v[92:93], off
	v_add_u32_e32 v154, 0x10000, v156
	ds_read_b128 v[92:95], v154
	ds_read_b128 v[96:99], v154 offset:1024
	ds_read_b128 v[172:175], v154 offset:2048
	ds_read_b128 v[176:179], v154 offset:3072
	s_waitcnt vmcnt(6)
	s_barrier
;     __device__ __forceinline__ void operator()(const f32x4 (&acc)[2][2][4][2], const Unit& u, int wr, int wc, int fr, int fq, int lane) const {
;         const int ch = u.pn * 64 + wc * 16 + 4 * fq;
;         const f32x4 w0 = *(const f32x4*)(cw + ch), w1 = *(const f32x4*)(cw + 4096 + ch), w2 = *(const f32x4*)(cw + 8192 + ch);
; #pragma unroll
;         for (int ai = 0; ai < 2; ++ai) {
;             f32x4 z[4], up[4], dn[4];
; #pragma unroll
;             for (int m = 0; m < 4; ++m) {
;                 z[m] = acc[ai][0][m][1] * acc[ai][1][m][0];
; #pragma unroll
;                 for (int j = 0; j < 4; ++j) { up[m][j] = __int_as_float(__builtin_amdgcn_update_dpp(0, __float_as_int(z[m][j]), 0x121, 0xF, 0xF, false));
;                                               dn[m][j] = __int_as_float(__builtin_amdgcn_update_dpp(0, __float_as_int(z[m][j]), 0x12F, 0xF, 0xF, false)); }
;             }
;             u32x2 wv[4];
; #pragma unroll
;             for (int m = 0; m < 4; ++m) {
;                 f32x4 zp, zn;
; #pragma unroll
;                 for (int j = 0; j < 4; ++j) {
;                     zp[j] = (fr > 0) ? up[m][j] : (m > 0 ? up[m > 0 ? m - 1 : 0][j] : 0.f);
;                     zn[j] = (fr < 15) ? dn[m][j] : (m < 3 ? dn[m < 3 ? m + 1 : 3][j] : 0.f);
;                 }
;                 f32x4 y = w0 * zp + w1 * z[m] + w2 * zn;
	s_setprio 1
	v_mfma_f32_16x16x32_bf16 v[56:59], v[232:235], v[180:183], v[56:59]
	v_mfma_f32_16x16x32_bf16 v[24:27], v[240:243], v[180:183], v[24:27]
	v_mfma_f32_16x16x32_bf16 v[48:51], v[232:235], v[208:211], v[48:51]
	v_mfma_f32_16x16x32_bf16 v[16:19], v[240:243], v[208:211], v[16:19]
	v_mfma_f32_16x16x32_bf16 v[40:43], v[232:235], v[216:219], v[40:43]
	v_mfma_f32_16x16x32_bf16 v[8:11], v[240:243], v[216:219], v[8:11]
	v_mfma_f32_16x16x32_bf16 v[32:35], v[232:235], v[224:227], v[32:35]
	v_mfma_f32_16x16x32_bf16 v[0:3], v[240:243], v[224:227], v[0:3]
	v_mfma_f32_16x16x32_bf16 v[56:59], v[236:239], v[204:207], v[56:59]
	v_mfma_f32_16x16x32_bf16 v[24:27], v[244:247], v[204:207], v[24:27]
	v_mfma_f32_16x16x32_bf16 v[48:51], v[236:239], v[212:215], v[48:51]
	v_mfma_f32_16x16x32_bf16 v[16:19], v[244:247], v[212:215], v[16:19]
	v_mfma_f32_16x16x32_bf16 v[40:43], v[236:239], v[220:223], v[40:43]
	v_mfma_f32_16x16x32_bf16 v[8:11], v[244:247], v[220:223], v[8:11]
	v_mfma_f32_16x16x32_bf16 v[32:35], v[236:239], v[228:231], v[32:35]
	v_mfma_f32_16x16x32_bf16 v[0:3], v[244:247], v[228:231], v[0:3]
	s_setprio 0
	s_add_i32 s9, s9, 2
	s_add_u32 vcc_lo, vcc_lo, 0x100
	s_addc_u32 vcc_hi, vcc_hi, 0
	s_cmp_gt_u32 s9, 29
	s_barrier
	s_cbranch_scc0 .LBB0_234
	s_waitcnt lgkmcnt(0)
	v_lshl_or_b32 v154, s5, 6, v158
	v_ashrrev_i32_e32 v155, 31, v154
	v_lshlrev_b64 v[92:93], 2, v[154:155]
	v_lshl_add_u64 v[88:89], v[142:143], 0, v[92:93]
	v_lshl_add_u64 v[90:91], v[144:145], 0, v[92:93]
	global_load_dwordx4 v[96:99], v[88:89], off
	s_nop 0
	global_load_dwordx4 v[88:91], v[90:91], off
	v_lshl_add_u64 v[92:93], v[146:147], 0, v[92:93]
	global_load_dwordx4 v[92:95], v[92:93], off
	v_pk_mul_f32 v[134:135], v[138:139], v[134:135]
	v_mov_b32_e32 v172, v161
	v_mov_b32_e32 v174, v161
	v_mov_b32_e32 v173, v161
	v_mov_b32_dpp v172, v134 row_ror:1 row_mask:0xf bank_mask:0xf
	v_mov_b32_dpp v174, v135 row_ror:1 row_mask:0xf bank_mask:0xf
	v_mov_b32_e32 v175, v161
	v_pk_mul_f32 v[126:127], v[130:131], v[126:127]
	v_mov_b32_e32 v177, v161
	v_mov_b32_e32 v179, v161
	v_pk_mul_f32 v[116:117], v[120:121], v[116:117]
	v_cndmask_b32_e64 v120, v172, 0, s[42:43]
	v_cndmask_b32_e64 v121, v174, 0, s[42:43]
	v_mov_b32_dpp v173, v134 row_ror:15 row_mask:0xf bank_mask:0xf
	v_mov_b32_dpp v175, v135 row_ror:15 row_mask:0xf bank_mask:0xf
	v_mov_b32_dpp v177, v126 row_ror:15 row_mask:0xf bank_mask:0xf
	v_mov_b32_dpp v179, v127 row_ror:15 row_mask:0xf bank_mask:0xf
	v_pk_mul_f32 v[132:133], v[136:137], v[132:133]
	v_mov_b32_e32 v136, v161
	v_mov_b32_e32 v138, v161
	v_pk_mul_f32 v[118:119], v[122:123], v[118:119]
	v_cndmask_b32_e64 v122, v173, v177, s[44:45]
	v_cndmask_b32_e64 v123, v175, v179, s[44:45]
	v_mov_b32_dpp v136, v132 row_ror:1 row_mask:0xf bank_mask:0xf
	v_mov_b32_dpp v138, v133 row_ror:1 row_mask:0xf bank_mask:0xf
	v_mov_b32_e32 v137, v161
	v_mov_b32_e32 v139, v161
	v_pk_mul_f32 v[124:125], v[128:129], v[124:125]
	v_mov_b32_e32 v129, v161
	v_mov_b32_e32 v131, v161
	v_pk_mul_f32 v[108:109], v[112:113], v[108:109]
	v_cndmask_b32_e64 v112, v136, 0, s[42:43]
	v_cndmask_b32_e64 v113, v138, 0, s[42:43]
	v_mov_b32_dpp v137, v132 row_ror:15 row_mask:0xf bank_mask:0xf
	v_mov_b32_dpp v139, v133 row_ror:15 row_mask:0xf bank_mask:0xf
	v_mov_b32_dpp v129, v124 row_ror:15 row_mask:0xf bank_mask:0xf
	v_mov_b32_dpp v131, v125 row_ror:15 row_mask:0xf bank_mask:0xf
	v_pk_mul_f32 v[110:111], v[114:115], v[110:111]
	v_cndmask_b32_e64 v114, v137, v129, s[44:45]
	v_cndmask_b32_e64 v115, v139, v131, s[44:45]
	v_mov_b32_e32 v176, v161
	v_mov_b32_e32 v178, v161
	v_mov_b32_e32 v185, v161
	v_mov_b32_dpp v176, v126 row_ror:1 row_mask:0xf bank_mask:0xf
	v_mov_b32_dpp v178, v127 row_ror:1 row_mask:0xf bank_mask:0xf
	v_mov_b32_e32 v191, v161
	v_mov_b32_dpp v185, v118 row_ror:15 row_mask:0xf bank_mask:0xf
	v_mov_b32_e32 v128, v161
	v_mov_b32_dpp v191, v119 row_ror:15 row_mask:0xf bank_mask:0xf
	v_mov_b32_e32 v130, v161
	v_mov_b32_dpp v128, v124 row_ror:1 row_mask:0xf bank_mask:0xf
	v_mov_b32_e32 v181, v161
	v_mov_b32_dpp v130, v125 row_ror:1 row_mask:0xf bank_mask:0xf
	v_mov_b32_e32 v183, v161
	v_mov_b32_dpp v181, v116 row_ror:15 row_mask:0xf bank_mask:0xf
	v_mov_b32_e32 v184, v161
	v_mov_b32_dpp v183, v117 row_ror:15 row_mask:0xf bank_mask:0xf
	v_mov_b32_e32 v190, v161
	v_mov_b32_dpp v184, v118 row_ror:1 row_mask:0xf bank_mask:0xf
	v_mov_b32_e32 v209, v161
	v_mov_b32_dpp v190, v119 row_ror:1 row_mask:0xf bank_mask:0xf
	v_mov_b32_e32 v211, v161
	v_mov_b32_dpp v209, v110 row_ror:15 row_mask:0xf bank_mask:0xf
	v_mov_b32_e32 v180, v161
	v_mov_b32_dpp v211, v111 row_ror:15 row_mask:0xf bank_mask:0xf
	v_mov_b32_e32 v182, v161
	v_mov_b32_dpp v180, v116 row_ror:1 row_mask:0xf bank_mask:0xf
	v_mov_b32_e32 v205, v161
	v_mov_b32_dpp v182, v117 row_ror:1 row_mask:0xf bank_mask:0xf
	v_mov_b32_e32 v207, v161
	v_mov_b32_dpp v205, v108 row_ror:15 row_mask:0xf bank_mask:0xf
	v_mov_b32_e32 v208, v161
	v_mov_b32_dpp v207, v109 row_ror:15 row_mask:0xf bank_mask:0xf
	v_mov_b32_e32 v210, v161
	v_mov_b32_dpp v208, v110 row_ror:1 row_mask:0xf bank_mask:0xf
	v_mov_b32_e32 v204, v161
	s_waitcnt vmcnt(0)
; __device__ __forceinline__ unsigned cvt_pk_bf16(float lo, float hi) { unsigned r; asm volatile("v_cvt_pk_bf16_f32 %0, %1, %2" : "=v"(r) : "v"(lo), "v"(hi)); return r; }
; __device__ __forceinline__ float silu_f(float x) { return x * __builtin_amdgcn_rcpf(1.f + __expf(-x)); }
;     __device__ __forceinline__ void operator()(const f32x4 (&acc)[2][2][4][2], const Unit& u, int wr, int wc, int fr, int fq, int lane) const {
;     ...
;             for (int m = 0; m < 4; ++m) {
;                 f32x4 zp, zn;
; #pragma unroll
;                 for (int j = 0; j < 4; ++j) {
;                     zp[j] = (fr > 0) ? up[m][j] : (m > 0 ? up[m > 0 ? m - 1 : 0][j] : 0.f);
;                     zn[j] = (fr < 15) ? dn[m][j] : (m < 3 ? dn[m < 3 ? m + 1 : 3][j] : 0.f);
;                 }
;                 f32x4 y = w0 * zp + w1 * z[m] + w2 * zn;
;                 const f32x4 bg = acc[ai][0][m][0], g = acc[ai][1][m][1];
; #pragma unroll
;                 for (int j = 0; j < 4; ++j) y[j] = y[j] * bg[j] * silu_f(g[j]);
;                 wv[m].x = cvt_pk_bf16(y[0], y[1]); wv[m].y = cvt_pk_bf16(y[2], y[3]);
;             }
;             if (u.pm < 128) {
	v_pk_mul_f32 v[120:121], v[98:99], v[120:121]
	v_pk_mul_f32 v[112:113], v[96:97], v[112:113]
	v_pk_fma_f32 v[120:121], v[134:135], v[90:91], v[120:121]
	v_mul_f32_e32 v134, 0xbfb8aa3b, v100
	v_exp_f32_e32 v134, v134
	v_pk_fma_f32 v[120:121], v[94:95], v[122:123], v[120:121]
	v_mov_b32_e32 v122, v100
	v_mul_f32_e32 v100, 0xbfb8aa3b, v101
	v_exp_f32_e32 v100, v100
	v_pk_fma_f32 v[112:113], v[132:133], v[88:89], v[112:113]
	v_mov_b32_e32 v123, v104
	v_pk_fma_f32 v[112:113], v[92:93], v[114:115], v[112:113]
	v_add_f32_e32 v114, 1.0, v134
	v_rcp_f32_e32 v114, v114
	v_add_f32_e32 v100, 1.0, v100
	v_mov_b32_e32 v115, v112
	v_rcp_f32_e32 v112, v100
	v_pk_mul_f32 v[114:115], v[122:123], v[114:115]
	v_mul_f32_e32 v100, 0xbfb8aa3b, v102
	v_mov_b32_e32 v104, v101
	v_mul_f32_e32 v114, v114, v115
	v_exp_f32_e32 v115, v100
	v_pk_mul_f32 v[100:101], v[104:105], v[112:113]
	v_mov_b32_e32 v104, v102
	v_mul_f32_e32 v112, v100, v101
	v_mul_f32_e32 v101, 0xbfb8aa3b, v103
	v_exp_f32_e32 v113, v101
	v_add_f32_e32 v100, 1.0, v115
	v_rcp_f32_e32 v100, v100
	v_mov_b32_e32 v101, v120
	v_add_f32_e32 v102, 1.0, v113
	v_rcp_f32_e32 v120, v102
	v_mov_b32_e32 v105, v106
	v_pk_mul_f32 v[100:101], v[104:105], v[100:101]
	v_mov_b32_e32 v106, v103
	v_mul_f32_e32 v102, v100, v101
	v_pk_mul_f32 v[100:101], v[106:107], v[120:121]
	v_cndmask_b32_e64 v106, v176, v172, s[42:43]
	v_cndmask_b32_e64 v107, v178, v174, s[42:43]
	v_pk_mul_f32 v[106:107], v[98:99], v[106:107]
	v_mul_f32_e32 v101, v100, v101
	v_cvt_pk_bf16_f32 v100, v114, v112
	v_cndmask_b32_e64 v112, v177, v185, s[44:45]
	v_cndmask_b32_e64 v113, v179, v191, s[44:45]
	v_pk_fma_f32 v[106:107], v[126:127], v[90:91], v[106:107]
	v_mul_f32_e32 v114, 0xbfb8aa3b, v80
	v_exp_f32_e32 v114, v114
	v_pk_fma_f32 v[106:107], v[94:95], v[112:113], v[106:107]
	v_mov_b32_e32 v112, v80
	v_mul_f32_e32 v80, 0xbfb8aa3b, v81
	v_cvt_pk_bf16_f32 v101, v102, v101
	v_cndmask_b32_e64 v102, v128, v136, s[42:43]
	v_cndmask_b32_e64 v103, v130, v138, s[42:43]
	v_exp_f32_e32 v80, v80
	v_pk_mul_f32 v[102:103], v[96:97], v[102:103]
	v_cndmask_b32_e64 v104, v129, v181, s[44:45]
	v_cndmask_b32_e64 v105, v131, v183, s[44:45]
	v_pk_fma_f32 v[102:103], v[124:125], v[88:89], v[102:103]
	v_add_f32_e32 v80, 1.0, v80
	v_pk_fma_f32 v[102:103], v[92:93], v[104:105], v[102:103]
	v_add_f32_e32 v104, 1.0, v114
	v_rcp_f32_e32 v104, v104
	v_mov_b32_e32 v105, v102
	v_rcp_f32_e32 v102, v80
	v_mov_b32_e32 v113, v84
	v_pk_mul_f32 v[104:105], v[112:113], v[104:105]
	v_mul_f32_e32 v80, 0xbfb8aa3b, v82
	v_mov_b32_e32 v84, v81
	v_mul_f32_e32 v104, v104, v105
	v_exp_f32_e32 v105, v80
	v_pk_mul_f32 v[80:81], v[84:85], v[102:103]
	v_mov_b32_e32 v84, v82
	v_mul_f32_e32 v102, v80, v81
	v_mul_f32_e32 v81, 0xbfb8aa3b, v83
	v_exp_f32_e32 v103, v81
	v_add_f32_e32 v80, 1.0, v105
	v_rcp_f32_e32 v80, v80
	v_mov_b32_e32 v81, v106
	v_add_f32_e32 v82, 1.0, v103
	v_rcp_f32_e32 v106, v82
	v_mov_b32_e32 v85, v86
	v_pk_mul_f32 v[80:81], v[84:85], v[80:81]
	v_mov_b32_e32 v86, v83
	v_mul_f32_e32 v82, v80, v81
	v_pk_mul_f32 v[80:81], v[86:87], v[106:107]
	v_cndmask_b32_e64 v86, v184, v176, s[42:43]
	v_cndmask_b32_e64 v87, v190, v178, s[42:43]
	v_pk_mul_f32 v[86:87], v[98:99], v[86:87]
	v_mul_f32_e32 v81, v80, v81
	v_cvt_pk_bf16_f32 v80, v104, v102
	v_cndmask_b32_e64 v102, v185, v209, s[44:45]
	v_cndmask_b32_e64 v103, v191, v211, s[44:45]
	v_pk_fma_f32 v[86:87], v[118:119], v[90:91], v[86:87]
	v_mul_f32_e32 v104, 0xbfb8aa3b, v72
	v_exp_f32_e32 v104, v104
	v_pk_fma_f32 v[86:87], v[94:95], v[102:103], v[86:87]
	v_mov_b32_e32 v102, v72
	v_mul_f32_e32 v72, 0xbfb8aa3b, v73
	v_cvt_pk_bf16_f32 v81, v82, v81
	v_cndmask_b32_e64 v82, v180, v128, s[42:43]
	v_cndmask_b32_e64 v83, v182, v130, s[42:43]
	v_exp_f32_e32 v72, v72
	v_pk_mul_f32 v[82:83], v[96:97], v[82:83]
	v_cndmask_b32_e64 v84, v181, v205, s[44:45]
	v_cndmask_b32_e64 v85, v183, v207, s[44:45]
	v_pk_fma_f32 v[82:83], v[116:117], v[88:89], v[82:83]
	v_add_f32_e32 v72, 1.0, v72
	v_pk_fma_f32 v[82:83], v[92:93], v[84:85], v[82:83]
	v_add_f32_e32 v84, 1.0, v104
	v_rcp_f32_e32 v84, v84
	v_mov_b32_e32 v85, v82
	v_rcp_f32_e32 v82, v72
	v_mov_b32_e32 v103, v76
	v_pk_mul_f32 v[84:85], v[102:103], v[84:85]
	v_mul_f32_e32 v72, 0xbfb8aa3b, v74
	v_mov_b32_e32 v76, v73
	v_mul_f32_e32 v84, v84, v85
	v_exp_f32_e32 v85, v72
	v_pk_mul_f32 v[72:73], v[76:77], v[82:83]
	v_mov_b32_e32 v76, v74
	v_mul_f32_e32 v82, v72, v73
	v_mul_f32_e32 v73, 0xbfb8aa3b, v75
	v_exp_f32_e32 v83, v73
	v_add_f32_e32 v72, 1.0, v85
	v_rcp_f32_e32 v72, v72
	v_mov_b32_e32 v73, v86
	v_add_f32_e32 v74, 1.0, v83
	v_rcp_f32_e32 v86, v74
	v_mov_b32_e32 v77, v78
	v_mov_b32_dpp v210, v111 row_ror:1 row_mask:0xf bank_mask:0xf
	v_pk_mul_f32 v[72:73], v[76:77], v[72:73]
	v_mov_b32_e32 v78, v75
	v_mul_f32_e32 v74, v72, v73
	v_pk_mul_f32 v[72:73], v[78:79], v[86:87]
	v_cndmask_b32_e64 v78, v208, v184, s[42:43]
	v_cndmask_b32_e64 v79, v210, v190, s[42:43]
	v_pk_mul_f32 v[78:79], v[98:99], v[78:79]
	v_mov_b32_e32 v206, v161
	v_mul_f32_e32 v73, v72, v73
	v_cvt_pk_bf16_f32 v72, v84, v82
	v_cndmask_b32_e64 v82, v209, 0, s[44:45]
	v_cndmask_b32_e64 v83, v211, 0, s[44:45]
	v_pk_fma_f32 v[78:79], v[110:111], v[90:91], v[78:79]
	v_mul_f32_e32 v84, 0xbfb8aa3b, v64
	v_mov_b32_dpp v204, v108 row_ror:1 row_mask:0xf bank_mask:0xf
	v_mov_b32_dpp v206, v109 row_ror:1 row_mask:0xf bank_mask:0xf
	v_exp_f32_e32 v84, v84
	v_pk_fma_f32 v[78:79], v[94:95], v[82:83], v[78:79]
	v_mov_b32_e32 v82, v64
	v_mul_f32_e32 v64, 0xbfb8aa3b, v65
	v_cvt_pk_bf16_f32 v73, v74, v73
	v_cndmask_b32_e64 v74, v204, v180, s[42:43]
	v_cndmask_b32_e64 v75, v206, v182, s[42:43]
	v_exp_f32_e32 v64, v64
	v_pk_mul_f32 v[74:75], v[96:97], v[74:75]
	v_cndmask_b32_e64 v76, v205, 0, s[44:45]
	v_cndmask_b32_e64 v77, v207, 0, s[44:45]
	v_pk_fma_f32 v[74:75], v[108:109], v[88:89], v[74:75]
	v_add_f32_e32 v64, 1.0, v64
	v_pk_fma_f32 v[74:75], v[92:93], v[76:77], v[74:75]
	v_add_f32_e32 v76, 1.0, v84
	v_rcp_f32_e32 v76, v76
	v_mov_b32_e32 v77, v74
	v_rcp_f32_e32 v74, v64
	v_mov_b32_e32 v83, v68
	v_pk_mul_f32 v[76:77], v[82:83], v[76:77]
	v_mul_f32_e32 v64, 0xbfb8aa3b, v66
	v_mov_b32_e32 v68, v65
	v_mul_f32_e32 v76, v76, v77
	v_exp_f32_e32 v77, v64
	v_pk_mul_f32 v[64:65], v[68:69], v[74:75]
	v_mov_b32_e32 v68, v66
	v_mul_f32_e32 v74, v64, v65
	v_mul_f32_e32 v65, 0xbfb8aa3b, v67
	v_exp_f32_e32 v75, v65
	v_add_f32_e32 v64, 1.0, v77
	v_rcp_f32_e32 v64, v64
	v_mov_b32_e32 v65, v78
	v_add_f32_e32 v66, 1.0, v75
	v_rcp_f32_e32 v78, v66
	s_cmpk_gt_i32 s36, 0x7f
	v_mov_b32_e32 v69, v70
	s_cselect_b64 s[38:39], -1, 0
	s_lshl_b32 s3, s36, 2
	v_pk_mul_f32 v[64:65], v[68:69], v[64:65]
	v_mov_b32_e32 v70, v67
	s_add_i32 s3, s4, s3
	v_mul_f32_e32 v68, v64, v65
	v_pk_mul_f32 v[64:65], v[70:71], v[78:79]
	s_and_b64 vcc, exec, s[38:39]
	v_mul_f32_e32 v64, v64, v65
	v_cvt_pk_bf16_f32 v66, v76, v74
	v_cvt_pk_bf16_f32 v67, v68, v64
	s_cbranch_vccz .LBB0_241
;     __device__ __forceinline__ void operator()(const f32x4 (&acc)[2][2][4][2], const Unit& u, int wr, int wc, int fr, int fq, int lane) const {
;     ...
;             } else {
;                 const int gidx = (u.pm - 128) * 4 + ai * 2 + wr, b = gidx / 5, g5 = gidx - b * 5, t0 = 62 * g5 - 1;
;                 bf16_t* p = O + ((size_t)(TL + b * 256 + t0 + fr)) * 4096 + ch;
; #pragma unroll
;                 for (int m = 0; m < 4; ++m) { const int i2 = m * 16 + fr; if (i2 >= 1 && i2 <= 62 && t0 + i2 < 256) *(u32x2*)(p + (size_t)(m * 16) * 4096) = wv[m]; }
;             }
	s_mul_hi_i32 s5, s3, 0x66666667
	s_lshr_b32 s6, s5, 31
	s_ashr_i32 s5, s5, 1
	s_add_i32 s6, s5, s6
	s_mul_i32 s5, s6, -5
	s_add_i32 s5, s5, s3
	s_mul_i32 s5, s5, 62
	s_lshl_b32 s6, s6, 8
	s_add_i32 s6, s5, s6
	v_add_u32_e32 v64, s6, v170
	v_ashrrev_i32_e32 v65, 31, v64
	v_lshlrev_b64 v[68:69], 13, v[64:65]
	v_lshl_add_u64 v[64:65], s[24:25], 0, v[68:69]
	v_cmp_le_i32_e32 vcc, s5, v157
	v_lshl_add_u64 v[64:65], v[154:155], 1, v[64:65]
	s_and_b64 s[6:7], s[46:47], vcc
	s_and_saveexec_b64 s[14:15], s[6:7]
	s_cbranch_execnz .LBB0_256
	s_or_b64 exec, exec, s[14:15]
	v_cmp_le_i32_e32 vcc, s5, v159
	s_and_saveexec_b64 s[14:15], vcc
	s_cbranch_execnz .LBB0_257

; #define PG8_STAGE_A(bufoff, ptr, half, rev) do { if (REVA && (rev)) { const char* _p = (ptr) - ((half) ? hstepA : 0); PG8_STAGE(bufoff, _p, voffAr); } else { const char* _p = (ptr) + ((half) ? hstepA : 0); PG8_STAGE(bufoff, _p, voffA); } } while (0)
; #define PG8_LDA(dst, b, h) do { _Pragma("unroll") for (int m = 0; m < 4; ++m) _Pragma("unroll") for (int k = 0; k < 2; ++k) dst[m][k] = *(const LAS bf16x8*)(lds + PG8_SA(b, h) + aoff + m * 2048 + k * 1024); } while (0)
; #define PG8_LDB(dst, b, h) do { _Pragma("unroll") for (int n = 0; n < 2; ++n) _Pragma("unroll") for (int k = 0; k < 2; ++k) dst[n][k] = *(const LAS bf16x8*)(lds + PG8_SB(b, h) + boff + n * 2048 + k * 1024); } while (0)
; #define PG8_WAIT_L(n) asm volatile("s_waitcnt lgkmcnt(" #n ")" ::: "memory")
; #define PG8_BAR __builtin_amdgcn_s_barrier()
; #define PG8_SCHED __builtin_amdgcn_sched_barrier(0)
;     ...
;     for (;;) {
;         const bool has_next = next_unit(ui + 1, nM, nN, MP, nxt, rot);
;         const char* nA = has_next ? nxt.a : cA; const char* nB = has_next ? nxt.b : cB; const char* nAr = has_next ? nxt.ar : cAr; const size_t nHb = has_next ? nxt.hb : cHb;
;         for (int t = 0; t < nt; t += 2) {
;             const bool last = (t == nt - 2);
;             const char* a1 = PG8_APTR(cA, cAr, t + 1); const bool r1 = REVA && ((t + 1) & 4);
;             const char* a2 = last ? nA : PG8_APTR(cA, cAr, t + 2); const bool r2 = REVA && !last && ((t + 2) & 4);
;             const char* a3 = last ? nA + kstep : PG8_APTR(cA, cAr, t + 3); const bool r3 = REVA && !last && ((t + 3) & 4);
;             const char* b2 = last ? nB : cB + (size_t)(t + 2) * kstep; const char* b3 = b2 + kstep; const size_t hb2 = last ? nHb : cHb;
;             PG8_LDB(B0, 0, 0); PG8_SCHED; PG8_LDA(At, 0, 0); PG8_STAGE_A(PG8_SA(1, 1), a1, 1, r1);
;             PG8_WAIT_L(8); PG8_BAR; PG8_WAIT_L(0); PG8_MMA(0, 0, At, B0); PG8_BAR; PG8_SCHED;
;     ...
; #pragma unroll
;         for (int a = 0; a < 2; ++a)
; #pragma unroll
;             for (int b = 0; b < 2; ++b)
; #pragma unroll
;                 for (int m = 0; m < 4; ++m)
; #pragma unroll
;                     for (int n = 0; n < 2; ++n) acc[a][b][m][n] = (f32x4){0.f, 0.f, 0.f, 0.f};
;         cur = nxt; cA = nA; cB = nB; cAr = nAr; cHb = nHb; ++ui;
.LBB0_334:
	s_add_u32 s3, s36, 0x80
	s_addc_u32 s9, s37, 0
	s_add_u32 s10, s44, 0x100080
	s_addc_u32 s11, s45, 0
	s_add_u32 s27, s20, 0x100
	v_mov_b32_e32 v0, 0
	v_lshl_add_u64 v[128:129], s[10:11], 0, v[150:151]
	v_lshl_add_u64 v[130:131], s[10:11], 0, v[152:153]
	s_addc_u32 s91, s21, 0
	s_mov_b32 s92, -2
	s_mov_b64 s[46:47], 0
	v_mov_b32_e32 v1, v0
	v_mov_b32_e32 v2, v0
	v_mov_b32_e32 v3, v0
	v_mov_b32_e32 v4, v0
	v_mov_b32_e32 v5, v0
	v_mov_b32_e32 v6, v0
	v_mov_b32_e32 v7, v0
	v_mov_b32_e32 v8, v0
	v_mov_b32_e32 v9, v0
	v_mov_b32_e32 v10, v0
	v_mov_b32_e32 v11, v0
	v_mov_b32_e32 v16, v0
	v_mov_b32_e32 v17, v0
	v_mov_b32_e32 v18, v0
	v_mov_b32_e32 v19, v0
	v_mov_b32_e32 v32, v0
	v_mov_b32_e32 v33, v0
	v_mov_b32_e32 v34, v0
	v_mov_b32_e32 v35, v0
	v_mov_b32_e32 v36, v0
	v_mov_b32_e32 v37, v0
	v_mov_b32_e32 v38, v0
	v_mov_b32_e32 v39, v0
	v_mov_b32_e32 v40, v0
	v_mov_b32_e32 v41, v0
	v_mov_b32_e32 v42, v0
	v_mov_b32_e32 v43, v0
	v_mov_b32_e32 v48, v0
	v_mov_b32_e32 v49, v0
	v_mov_b32_e32 v50, v0
	v_mov_b32_e32 v51, v0
	v_mov_b32_e32 v12, v0
	v_mov_b32_e32 v13, v0
	v_mov_b32_e32 v14, v0
	v_mov_b32_e32 v15, v0
	v_mov_b32_e32 v20, v0
	v_mov_b32_e32 v21, v0
	v_mov_b32_e32 v22, v0
	v_mov_b32_e32 v23, v0
	v_mov_b32_e32 v24, v0
	v_mov_b32_e32 v25, v0
	v_mov_b32_e32 v26, v0
	v_mov_b32_e32 v27, v0
	v_mov_b32_e32 v28, v0
	v_mov_b32_e32 v29, v0
	v_mov_b32_e32 v30, v0
	v_mov_b32_e32 v31, v0
	v_mov_b32_e32 v44, v0
	v_mov_b32_e32 v45, v0
	v_mov_b32_e32 v46, v0
	v_mov_b32_e32 v47, v0
	v_mov_b32_e32 v52, v0
	v_mov_b32_e32 v53, v0
	v_mov_b32_e32 v54, v0
	v_mov_b32_e32 v55, v0
	v_mov_b32_e32 v56, v0
	v_mov_b32_e32 v57, v0
	v_mov_b32_e32 v58, v0
	v_mov_b32_e32 v59, v0
	v_mov_b32_e32 v60, v0
	v_mov_b32_e32 v61, v0
	v_mov_b32_e32 v62, v0
	v_mov_b32_e32 v63, v0
	v_mov_b32_e32 v64, v0
	v_mov_b32_e32 v65, v0
	v_mov_b32_e32 v66, v0
	v_mov_b32_e32 v67, v0
	v_mov_b32_e32 v68, v0
	v_mov_b32_e32 v69, v0
	v_mov_b32_e32 v70, v0
	v_mov_b32_e32 v71, v0
	v_mov_b32_e32 v72, v0
	v_mov_b32_e32 v73, v0
	v_mov_b32_e32 v74, v0
	v_mov_b32_e32 v75, v0
	v_mov_b32_e32 v80, v0
	v_mov_b32_e32 v81, v0
	v_mov_b32_e32 v82, v0
	v_mov_b32_e32 v83, v0
	v_mov_b32_e32 v96, v0
	v_mov_b32_e32 v97, v0
	v_mov_b32_e32 v98, v0
	v_mov_b32_e32 v99, v0
	v_mov_b32_e32 v100, v0
	v_mov_b32_e32 v101, v0
	v_mov_b32_e32 v102, v0
	v_mov_b32_e32 v103, v0
	v_mov_b32_e32 v104, v0
	v_mov_b32_e32 v105, v0
	v_mov_b32_e32 v106, v0
	v_mov_b32_e32 v107, v0
	v_mov_b32_e32 v112, v0
	v_mov_b32_e32 v113, v0
	v_mov_b32_e32 v114, v0
	v_mov_b32_e32 v115, v0
	v_mov_b32_e32 v76, v0
	v_mov_b32_e32 v77, v0
	v_mov_b32_e32 v78, v0
	v_mov_b32_e32 v79, v0
	v_mov_b32_e32 v84, v0
	v_mov_b32_e32 v85, v0
	v_mov_b32_e32 v86, v0
	v_mov_b32_e32 v87, v0
	v_mov_b32_e32 v88, v0
	v_mov_b32_e32 v89, v0
	v_mov_b32_e32 v90, v0
	v_mov_b32_e32 v91, v0
	v_mov_b32_e32 v92, v0
	v_mov_b32_e32 v93, v0
	v_mov_b32_e32 v94, v0
	v_mov_b32_e32 v95, v0
	v_mov_b32_e32 v108, v0
	v_mov_b32_e32 v109, v0
	v_mov_b32_e32 v110, v0
	v_mov_b32_e32 v111, v0
	v_mov_b32_e32 v116, v0
	v_mov_b32_e32 v117, v0
	v_mov_b32_e32 v118, v0
	v_mov_b32_e32 v119, v0
	v_mov_b32_e32 v120, v0
	v_mov_b32_e32 v121, v0
	v_mov_b32_e32 v122, v0
	v_mov_b32_e32 v123, v0
	v_mov_b32_e32 v124, v0
	v_mov_b32_e32 v125, v0
	v_mov_b32_e32 v126, v0
	v_mov_b32_e32 v127, v0
	v_add_u32_e32 v154, 0x10000, v157
	ds_read_b128 v[132:135], v154
	ds_read_b128 v[136:139], v154 offset:1024
	ds_read_b128 v[140:143], v154 offset:2048
	ds_read_b128 v[168:171], v154 offset:3072
.LBB0_335:
	s_add_u32 s10, s44, s46
	s_addc_u32 s11, s45, s47
	s_add_u32 s16, s10, 0x100
	s_addc_u32 s17, s11, 0
	s_add_u32 s10, s10, 0x180
	s_addc_u32 s11, s11, 0
	s_add_u32 s14, s27, s46
	s_addc_u32 s15, s91, s47
	s_add_i32 s93, 0, 0x10000
	s_cmpk_eq_i32 s46, 0x1f00
	s_cselect_b32 s15, s39, s15
	s_cselect_b32 s14, s38, s14
	s_cselect_b32 s21, s37, s17
	s_cselect_b32 s20, s36, s16
	s_cselect_b32 s17, s9, s11
	s_cselect_b32 s16, s3, s10
	v_lshl_add_u64 v[154:155], v[128:129], 0, s[46:47]
	s_add_i32 m0, s1, 0xc000
	ds_read_b128 v[172:175], v158
	ds_read_b128 v[176:179], v158 offset:1024
	ds_read_b128 v[180:183], v158 offset:2048
	ds_read_b128 v[204:207], v158 offset:3072
	ds_read_b128 v[208:211], v158 offset:4096
	ds_read_b128 v[212:215], v158 offset:5120
	ds_read_b128 v[216:219], v158 offset:6144
	ds_read_b128 v[220:223], v158 offset:7168
	global_load_lds_dwordx4 v[154:155], off
	v_lshl_add_u64 v[154:155], v[130:131], 0, s[46:47]
	s_add_i32 m0, s1, 0xe000
	s_nop 0
	global_load_lds_dwordx4 v[154:155], off
	s_waitcnt lgkmcnt(8)
	s_barrier
	s_waitcnt lgkmcnt(0)
	s_setprio 1
	s_waitcnt lgkmcnt(0)
	v_mfma_f32_16x16x32_bf16 v[124:127], v[132:135], v[172:175], v[124:127]
	v_mfma_f32_16x16x32_bf16 v[120:123], v[140:143], v[172:175], v[120:123]
	v_mfma_f32_16x16x32_bf16 v[116:119], v[132:135], v[180:183], v[116:119]
	v_mfma_f32_16x16x32_bf16 v[108:111], v[140:143], v[180:183], v[108:111]
	v_mfma_f32_16x16x32_bf16 v[92:95], v[132:135], v[208:211], v[92:95]
	v_mfma_f32_16x16x32_bf16 v[88:91], v[140:143], v[208:211], v[88:91]
	v_mfma_f32_16x16x32_bf16 v[84:87], v[132:135], v[216:219], v[84:87]
	v_mfma_f32_16x16x32_bf16 v[76:79], v[140:143], v[216:219], v[76:79]
	v_mfma_f32_16x16x32_bf16 v[124:127], v[136:139], v[176:179], v[124:127]
	v_mfma_f32_16x16x32_bf16 v[120:123], v[168:171], v[176:179], v[120:123]
	v_mfma_f32_16x16x32_bf16 v[116:119], v[136:139], v[204:207], v[116:119]
	v_mfma_f32_16x16x32_bf16 v[108:111], v[168:171], v[204:207], v[108:111]
	v_mfma_f32_16x16x32_bf16 v[92:95], v[136:139], v[212:215], v[92:95]
	v_mfma_f32_16x16x32_bf16 v[88:91], v[168:171], v[212:215], v[88:91]
	v_mfma_f32_16x16x32_bf16 v[84:87], v[136:139], v[220:223], v[84:87]
	v_mfma_f32_16x16x32_bf16 v[76:79], v[168:171], v[220:223], v[76:79]
	s_setprio 0
	s_barrier
; #define PG8_STAGE(bufoff, gbase, voff) do { _Pragma("unroll") for (int _i = 0; _i < 2; ++_i) \
;         __builtin_amdgcn_global_load_lds((const unsigned*)((const char*)(gbase) + (voff)[_i]), (LAS unsigned*)(lds + (bufoff) + ldsw + _i * 8192), 16, 0, 0); } while (0)
; #define PG8_STAGE_A(bufoff, ptr, half, rev) do { if (REVA && (rev)) { const char* _p = (ptr) - ((half) ? hstepA : 0); PG8_STAGE(bufoff, _p, voffAr); } else { const char* _p = (ptr) + ((half) ? hstepA : 0); PG8_STAGE(bufoff, _p, voffA); } } while (0)
; #define PG8_LDA(dst, b, h) do { _Pragma("unroll") for (int m = 0; m < 4; ++m) _Pragma("unroll") for (int k = 0; k < 2; ++k) dst[m][k] = *(const LAS bf16x8*)(lds + PG8_SA(b, h) + aoff + m * 2048 + k * 1024); } while (0)
; #define PG8_LDB(dst, b, h) do { _Pragma("unroll") for (int n = 0; n < 2; ++n) _Pragma("unroll") for (int k = 0; k < 2; ++k) dst[n][k] = *(const LAS bf16x8*)(lds + PG8_SB(b, h) + boff + n * 2048 + k * 1024); } while (0)
; #define PG8_MMA(ai, bj, At, Bt) do { __builtin_amdgcn_s_setprio(1); _Pragma("unroll") for (int m = 0; m < 4; ++m) _Pragma("unroll") for (int n = 0; n < 2; ++n) _Pragma("unroll") for (int k = 0; k < 2; ++k) \
;         acc[ai][bj][m][n] = __builtin_amdgcn_mfma_f32_16x16x32_bf16(Bt[n][k], At[m][k], acc[ai][bj][m][n], 0, 0, 0); __builtin_amdgcn_s_setprio(0); } while (0)
; #define PG8_WAIT_V(n) asm volatile("s_waitcnt vmcnt(" #n ")" ::: "memory")
; #define PG8_WAIT_L(n) asm volatile("s_waitcnt lgkmcnt(" #n ")" ::: "memory")
; #define PG8_BAR __builtin_amdgcn_s_barrier()
; #define PG8_SCHED __builtin_amdgcn_sched_barrier(0)
;     ...
;             PG8_LDB(B1, 0, 1); PG8_STAGE(PG8_SB(0, 0), b2, voffB);
;             PG8_BAR; PG8_WAIT_L(0); PG8_MMA(0, 1, At, B1); PG8_BAR;
;             PG8_LDA(At, 0, 1); PG8_STAGE_A(PG8_SA(0, 0), a2, 0, r2);
;             PG8_BAR; PG8_WAIT_L(0); PG8_MMA(1, 0, At, B0); PG8_BAR; PG8_SCHED;
;             PG8_STAGE(PG8_SB(0, 1), b2 + hb2, voffB);
;             PG8_WAIT_V(6); PG8_BAR; PG8_MMA(1, 1, At, B1); PG8_BAR;
;             PG8_LDB(B0, 1, 0); PG8_SCHED; PG8_LDA(At, 1, 0); PG8_STAGE_A(PG8_SA(0, 1), a2, 1, r2);
	s_add_i32 s94, 0, 0x14000
	v_add_u32_e32 v154, s94, v157
	s_add_i32 s10, s93, s52
	ds_read_b128 v[224:227], v154
	ds_read_b128 v[228:231], v154 offset:1024
	ds_read_b128 v[232:235], v154 offset:2048
	ds_read_b128 v[236:239], v154 offset:3072
	v_lshl_add_u64 v[154:155], s[14:15], 0, v[146:147]
	s_mov_b32 m0, s10
	v_lshl_add_u64 v[184:185], s[14:15], 0, v[144:145]
	global_load_lds_dwordx4 v[154:155], off
	s_add_i32 m0, s10, 0x2000
	s_nop 0
	global_load_lds_dwordx4 v[184:185], off
	s_barrier
	s_waitcnt lgkmcnt(0)
	s_setprio 1
	s_waitcnt lgkmcnt(0)
	v_mfma_f32_16x16x32_bf16 v[112:115], v[224:227], v[172:175], v[112:115]
	v_mfma_f32_16x16x32_bf16 v[104:107], v[232:235], v[172:175], v[104:107]
	v_mfma_f32_16x16x32_bf16 v[100:103], v[224:227], v[180:183], v[100:103]
	v_mfma_f32_16x16x32_bf16 v[96:99], v[232:235], v[180:183], v[96:99]
	v_mfma_f32_16x16x32_bf16 v[80:83], v[224:227], v[208:211], v[80:83]
	v_mfma_f32_16x16x32_bf16 v[72:75], v[232:235], v[208:211], v[72:75]
	v_mfma_f32_16x16x32_bf16 v[68:71], v[224:227], v[216:219], v[68:71]
	v_mfma_f32_16x16x32_bf16 v[64:67], v[232:235], v[216:219], v[64:67]
	v_mfma_f32_16x16x32_bf16 v[112:115], v[228:231], v[176:179], v[112:115]
	v_mfma_f32_16x16x32_bf16 v[104:107], v[236:239], v[176:179], v[104:107]
	v_mfma_f32_16x16x32_bf16 v[100:103], v[228:231], v[204:207], v[100:103]
	v_mfma_f32_16x16x32_bf16 v[96:99], v[236:239], v[204:207], v[96:99]
	v_mfma_f32_16x16x32_bf16 v[80:83], v[228:231], v[212:215], v[80:83]
	v_mfma_f32_16x16x32_bf16 v[72:75], v[236:239], v[212:215], v[72:75]
	v_mfma_f32_16x16x32_bf16 v[68:71], v[228:231], v[220:223], v[68:71]
	v_mfma_f32_16x16x32_bf16 v[64:67], v[236:239], v[220:223], v[64:67]
	s_setprio 0
	s_mov_b32 m0, s1
	v_lshl_add_u64 v[190:191], s[20:21], 0, v[146:147]
	s_barrier
	ds_read_b128 v[172:175], v158 offset:16384
	ds_read_b128 v[176:179], v158 offset:17408
	ds_read_b128 v[180:183], v158 offset:18432
	ds_read_b128 v[204:207], v158 offset:19456
	ds_read_b128 v[208:211], v158 offset:20480
	ds_read_b128 v[212:215], v158 offset:21504
	ds_read_b128 v[216:219], v158 offset:22528
	ds_read_b128 v[220:223], v158 offset:23552
	global_load_lds_dwordx4 v[190:191], off
	v_lshl_add_u64 v[190:191], s[20:21], 0, v[144:145]
	s_mov_b32 m0, s53
	s_nop 0
	global_load_lds_dwordx4 v[190:191], off
	s_waitcnt vmcnt(10)
	s_barrier
	s_waitcnt lgkmcnt(0)
	s_setprio 1
	s_waitcnt lgkmcnt(0)
	v_mfma_f32_16x16x32_bf16 v[60:63], v[132:135], v[172:175], v[60:63]
	v_mfma_f32_16x16x32_bf16 v[56:59], v[140:143], v[172:175], v[56:59]
	v_mfma_f32_16x16x32_bf16 v[52:55], v[132:135], v[180:183], v[52:55]
	v_mfma_f32_16x16x32_bf16 v[44:47], v[140:143], v[180:183], v[44:47]
	v_mfma_f32_16x16x32_bf16 v[28:31], v[132:135], v[208:211], v[28:31]
	v_mfma_f32_16x16x32_bf16 v[24:27], v[140:143], v[208:211], v[24:27]
	v_mfma_f32_16x16x32_bf16 v[20:23], v[132:135], v[216:219], v[20:23]
	v_mfma_f32_16x16x32_bf16 v[12:15], v[140:143], v[216:219], v[12:15]
	v_mfma_f32_16x16x32_bf16 v[60:63], v[136:139], v[176:179], v[60:63]
	v_mfma_f32_16x16x32_bf16 v[56:59], v[168:171], v[176:179], v[56:59]
	v_mfma_f32_16x16x32_bf16 v[52:55], v[136:139], v[204:207], v[52:55]
	v_mfma_f32_16x16x32_bf16 v[44:47], v[168:171], v[204:207], v[44:47]
	v_mfma_f32_16x16x32_bf16 v[28:31], v[136:139], v[212:215], v[28:31]
	v_mfma_f32_16x16x32_bf16 v[24:27], v[168:171], v[212:215], v[24:27]
	v_mfma_f32_16x16x32_bf16 v[20:23], v[136:139], v[220:223], v[20:23]
	v_mfma_f32_16x16x32_bf16 v[12:15], v[168:171], v[220:223], v[12:15]
	s_setprio 0
	s_barrier
	s_add_u32 s10, s14, 0x100000
	s_addc_u32 s11, s15, 0
	s_add_i32 s93, s94, s52
	v_lshl_add_u64 v[132:133], s[10:11], 0, v[146:147]
	s_mov_b32 m0, s93
	s_nop 0
	global_load_lds_dwordx4 v[132:133], off
	v_lshl_add_u64 v[132:133], s[10:11], 0, v[144:145]
	s_add_i32 m0, s93, 0x2000
	s_nop 0
	global_load_lds_dwordx4 v[132:133], off
	v_add_u32_e32 v159, 0x18000, v157
	ds_read_b128 v[132:135], v159
	ds_read_b128 v[136:139], v159 offset:1024
	ds_read_b128 v[140:143], v159 offset:2048
	ds_read_b128 v[168:171], v159 offset:3072
	s_waitcnt vmcnt(6)
	s_barrier
	s_setprio 1
	v_mfma_f32_16x16x32_bf16 v[48:51], v[224:227], v[172:175], v[48:51]
	v_mfma_f32_16x16x32_bf16 v[40:43], v[232:235], v[172:175], v[40:43]
	v_mfma_f32_16x16x32_bf16 v[36:39], v[224:227], v[180:183], v[36:39]
	v_mfma_f32_16x16x32_bf16 v[32:35], v[232:235], v[180:183], v[32:35]
	v_mfma_f32_16x16x32_bf16 v[16:19], v[224:227], v[208:211], v[16:19]
	v_mfma_f32_16x16x32_bf16 v[8:11], v[232:235], v[208:211], v[8:11]
	v_mfma_f32_16x16x32_bf16 v[4:7], v[224:227], v[216:219], v[4:7]
	v_mfma_f32_16x16x32_bf16 v[0:3], v[232:235], v[216:219], v[0:3]
	v_mfma_f32_16x16x32_bf16 v[48:51], v[228:231], v[176:179], v[48:51]
	v_mfma_f32_16x16x32_bf16 v[40:43], v[236:239], v[176:179], v[40:43]
	v_mfma_f32_16x16x32_bf16 v[36:39], v[228:231], v[204:207], v[36:39]
	v_mfma_f32_16x16x32_bf16 v[32:35], v[236:239], v[204:207], v[32:35]
	v_mfma_f32_16x16x32_bf16 v[16:19], v[228:231], v[212:215], v[16:19]
	v_mfma_f32_16x16x32_bf16 v[8:11], v[236:239], v[212:215], v[8:11]
	v_mfma_f32_16x16x32_bf16 v[4:7], v[228:231], v[220:223], v[4:7]
	v_mfma_f32_16x16x32_bf16 v[0:3], v[236:239], v[220:223], v[0:3]
	s_setprio 0
	s_add_i32 s93, 0, 0x18000
	s_barrier
	s_add_u32 s10, s20, 0x100000
	s_addc_u32 s11, s21, 0
	s_mov_b32 m0, s6
	v_lshl_add_u64 v[190:191], s[10:11], 0, v[146:147]
	ds_read_b128 v[172:175], v158 offset:32768
	ds_read_b128 v[176:179], v158 offset:33792
	ds_read_b128 v[180:183], v158 offset:34816
	ds_read_b128 v[204:207], v158 offset:35840
	ds_read_b128 v[208:211], v158 offset:36864
	ds_read_b128 v[212:215], v158 offset:37888
	ds_read_b128 v[216:219], v158 offset:38912
	ds_read_b128 v[220:223], v158 offset:39936
	global_load_lds_dwordx4 v[190:191], off
	v_lshl_add_u64 v[190:191], s[10:11], 0, v[144:145]
	s_mov_b32 m0, s7
	s_nop 0
	global_load_lds_dwordx4 v[190:191], off
	s_waitcnt lgkmcnt(8)
	s_barrier
; #define PG8_STAGE(bufoff, gbase, voff) do { _Pragma("unroll") for (int _i = 0; _i < 2; ++_i) \
;         __builtin_amdgcn_global_load_lds((const unsigned*)((const char*)(gbase) + (voff)[_i]), (LAS unsigned*)(lds + (bufoff) + ldsw + _i * 8192), 16, 0, 0); } while (0)
; #define PG8_STAGE_A(bufoff, ptr, half, rev) do { if (REVA && (rev)) { const char* _p = (ptr) - ((half) ? hstepA : 0); PG8_STAGE(bufoff, _p, voffAr); } else { const char* _p = (ptr) + ((half) ? hstepA : 0); PG8_STAGE(bufoff, _p, voffA); } } while (0)
; #define PG8_LDA(dst, b, h) do { _Pragma("unroll") for (int m = 0; m < 4; ++m) _Pragma("unroll") for (int k = 0; k < 2; ++k) dst[m][k] = *(const LAS bf16x8*)(lds + PG8_SA(b, h) + aoff + m * 2048 + k * 1024); } while (0)
; #define PG8_LDB(dst, b, h) do { _Pragma("unroll") for (int n = 0; n < 2; ++n) _Pragma("unroll") for (int k = 0; k < 2; ++k) dst[n][k] = *(const LAS bf16x8*)(lds + PG8_SB(b, h) + boff + n * 2048 + k * 1024); } while (0)
; #define PG8_MMA(ai, bj, At, Bt) do { __builtin_amdgcn_s_setprio(1); _Pragma("unroll") for (int m = 0; m < 4; ++m) _Pragma("unroll") for (int n = 0; n < 2; ++n) _Pragma("unroll") for (int k = 0; k < 2; ++k) \
;         acc[ai][bj][m][n] = __builtin_amdgcn_mfma_f32_16x16x32_bf16(Bt[n][k], At[m][k], acc[ai][bj][m][n], 0, 0, 0); __builtin_amdgcn_s_setprio(0); } while (0)
; #define PG8_WAIT_V(n) asm volatile("s_waitcnt vmcnt(" #n ")" ::: "memory")
; #define PG8_WAIT_L(n) asm volatile("s_waitcnt lgkmcnt(" #n ")" ::: "memory")
; #define PG8_BAR __builtin_amdgcn_s_barrier()
; #define PG8_SCHED __builtin_amdgcn_sched_barrier(0)
;     ...
;             PG8_LDB(B0, 1, 0); PG8_SCHED; PG8_LDA(At, 1, 0); PG8_STAGE_A(PG8_SA(0, 1), a2, 1, r2);
;             PG8_WAIT_L(8); PG8_BAR; PG8_WAIT_L(0); PG8_MMA(0, 0, At, B0); PG8_BAR; PG8_SCHED;
;             PG8_LDB(B1, 1, 1); PG8_STAGE(PG8_SB(1, 0), b3, voffB);
;             PG8_BAR; PG8_WAIT_L(0); PG8_MMA(0, 1, At, B1); PG8_BAR;
;             PG8_LDA(At, 1, 1); PG8_STAGE_A(PG8_SA(1, 0), a3, 0, r3);
;             PG8_BAR; PG8_WAIT_L(0); PG8_MMA(1, 0, At, B0); PG8_BAR; PG8_SCHED;
;             PG8_STAGE(PG8_SB(1, 1), b3 + hb2, voffB);
;             PG8_WAIT_V(6); PG8_BAR; PG8_MMA(1, 1, At, B1); PG8_BAR;
	s_waitcnt lgkmcnt(0)
	s_setprio 1
	s_waitcnt lgkmcnt(0)
	v_mfma_f32_16x16x32_bf16 v[124:127], v[132:135], v[172:175], v[124:127]
	v_mfma_f32_16x16x32_bf16 v[120:123], v[140:143], v[172:175], v[120:123]
	v_mfma_f32_16x16x32_bf16 v[116:119], v[132:135], v[180:183], v[116:119]
	v_mfma_f32_16x16x32_bf16 v[108:111], v[140:143], v[180:183], v[108:111]
	v_mfma_f32_16x16x32_bf16 v[92:95], v[132:135], v[208:211], v[92:95]
	v_mfma_f32_16x16x32_bf16 v[88:91], v[140:143], v[208:211], v[88:91]
	v_mfma_f32_16x16x32_bf16 v[84:87], v[132:135], v[216:219], v[84:87]
	v_mfma_f32_16x16x32_bf16 v[76:79], v[140:143], v[216:219], v[76:79]
	v_mfma_f32_16x16x32_bf16 v[124:127], v[136:139], v[176:179], v[124:127]
	v_mfma_f32_16x16x32_bf16 v[120:123], v[168:171], v[176:179], v[120:123]
	v_mfma_f32_16x16x32_bf16 v[116:119], v[136:139], v[204:207], v[116:119]
	v_mfma_f32_16x16x32_bf16 v[108:111], v[168:171], v[204:207], v[108:111]
	v_mfma_f32_16x16x32_bf16 v[92:95], v[136:139], v[212:215], v[92:95]
	v_mfma_f32_16x16x32_bf16 v[88:91], v[168:171], v[212:215], v[88:91]
	v_mfma_f32_16x16x32_bf16 v[84:87], v[136:139], v[220:223], v[84:87]
	v_mfma_f32_16x16x32_bf16 v[76:79], v[168:171], v[220:223], v[76:79]
	s_setprio 0
	s_barrier
	s_add_i32 s20, 0, 0x1c000
	s_add_i32 s10, s93, s52
	v_add_u32_e32 v159, s20, v157
	v_lshl_add_u64 v[154:155], v[154:155], 0, s[28:29]
	s_mov_b32 m0, s10
	ds_read_b128 v[224:227], v159
	ds_read_b128 v[228:231], v159 offset:1024
	ds_read_b128 v[232:235], v159 offset:2048
	ds_read_b128 v[236:239], v159 offset:3072
	global_load_lds_dwordx4 v[154:155], off
	v_lshl_add_u64 v[154:155], v[184:185], 0, s[28:29]
	s_add_i32 m0, s10, 0x2000
	s_nop 0
	global_load_lds_dwordx4 v[154:155], off
	s_barrier
	s_waitcnt lgkmcnt(0)
	s_setprio 1
	s_waitcnt lgkmcnt(0)
	v_mfma_f32_16x16x32_bf16 v[112:115], v[224:227], v[172:175], v[112:115]
	v_mfma_f32_16x16x32_bf16 v[104:107], v[232:235], v[172:175], v[104:107]
	v_mfma_f32_16x16x32_bf16 v[100:103], v[224:227], v[180:183], v[100:103]
	v_mfma_f32_16x16x32_bf16 v[96:99], v[232:235], v[180:183], v[96:99]
	v_mfma_f32_16x16x32_bf16 v[80:83], v[224:227], v[208:211], v[80:83]
	v_mfma_f32_16x16x32_bf16 v[72:75], v[232:235], v[208:211], v[72:75]
	v_mfma_f32_16x16x32_bf16 v[68:71], v[224:227], v[216:219], v[68:71]
	v_mfma_f32_16x16x32_bf16 v[64:67], v[232:235], v[216:219], v[64:67]
	v_mfma_f32_16x16x32_bf16 v[112:115], v[228:231], v[176:179], v[112:115]
	v_mfma_f32_16x16x32_bf16 v[104:107], v[236:239], v[176:179], v[104:107]
	v_mfma_f32_16x16x32_bf16 v[100:103], v[228:231], v[204:207], v[100:103]
	v_mfma_f32_16x16x32_bf16 v[96:99], v[236:239], v[204:207], v[96:99]
	v_mfma_f32_16x16x32_bf16 v[80:83], v[228:231], v[212:215], v[80:83]
	v_mfma_f32_16x16x32_bf16 v[72:75], v[236:239], v[212:215], v[72:75]
	v_mfma_f32_16x16x32_bf16 v[68:71], v[228:231], v[220:223], v[68:71]
	v_mfma_f32_16x16x32_bf16 v[64:67], v[236:239], v[220:223], v[64:67]
	s_setprio 0
	s_mov_b32 m0, s70
	v_lshl_add_u64 v[154:155], s[16:17], 0, v[146:147]
	s_barrier
	ds_read_b128 v[172:175], v158 offset:49152
	ds_read_b128 v[176:179], v158 offset:50176
	ds_read_b128 v[180:183], v158 offset:51200
	ds_read_b128 v[204:207], v158 offset:52224
	ds_read_b128 v[208:211], v158 offset:53248
	ds_read_b128 v[212:215], v158 offset:54272
	ds_read_b128 v[216:219], v158 offset:55296
	ds_read_b128 v[220:223], v158 offset:56320
	global_load_lds_dwordx4 v[154:155], off
	v_lshl_add_u64 v[154:155], s[16:17], 0, v[144:145]
	s_mov_b32 m0, s71
	s_nop 0
	global_load_lds_dwordx4 v[154:155], off
	s_waitcnt vmcnt(10)
	s_barrier
	s_waitcnt lgkmcnt(0)
	s_setprio 1
	s_waitcnt lgkmcnt(0)
	v_mfma_f32_16x16x32_bf16 v[60:63], v[132:135], v[172:175], v[60:63]
	v_mfma_f32_16x16x32_bf16 v[56:59], v[140:143], v[172:175], v[56:59]
	v_mfma_f32_16x16x32_bf16 v[52:55], v[132:135], v[180:183], v[52:55]
	v_mfma_f32_16x16x32_bf16 v[44:47], v[140:143], v[180:183], v[44:47]
	v_mfma_f32_16x16x32_bf16 v[28:31], v[132:135], v[208:211], v[28:31]
	v_mfma_f32_16x16x32_bf16 v[24:27], v[140:143], v[208:211], v[24:27]
	v_mfma_f32_16x16x32_bf16 v[20:23], v[132:135], v[216:219], v[20:23]
	v_mfma_f32_16x16x32_bf16 v[12:15], v[140:143], v[216:219], v[12:15]
	v_mfma_f32_16x16x32_bf16 v[60:63], v[136:139], v[176:179], v[60:63]
	v_mfma_f32_16x16x32_bf16 v[56:59], v[168:171], v[176:179], v[56:59]
	v_mfma_f32_16x16x32_bf16 v[52:55], v[136:139], v[204:207], v[52:55]
	v_mfma_f32_16x16x32_bf16 v[44:47], v[168:171], v[204:207], v[44:47]
	v_mfma_f32_16x16x32_bf16 v[28:31], v[136:139], v[212:215], v[28:31]
	v_mfma_f32_16x16x32_bf16 v[24:27], v[168:171], v[212:215], v[24:27]
	v_mfma_f32_16x16x32_bf16 v[20:23], v[136:139], v[220:223], v[20:23]
	v_mfma_f32_16x16x32_bf16 v[12:15], v[168:171], v[220:223], v[12:15]
	s_setprio 0
	s_barrier
	s_add_u32 s10, s14, 0x100080
	s_addc_u32 s11, s15, 0
	s_add_i32 s14, s20, s52
	v_lshl_add_u64 v[132:133], s[10:11], 0, v[146:147]
	s_mov_b32 m0, s14
	s_nop 0
	global_load_lds_dwordx4 v[132:133], off
	v_lshl_add_u64 v[132:133], s[10:11], 0, v[144:145]
	s_add_i32 m0, s14, 0x2000
	s_nop 0
	global_load_lds_dwordx4 v[132:133], off
	v_add_u32_e32 v154, 0x10000, v157
	ds_read_b128 v[132:135], v154
	ds_read_b128 v[136:139], v154 offset:1024
	ds_read_b128 v[140:143], v154 offset:2048
	ds_read_b128 v[168:171], v154 offset:3072
	s_waitcnt vmcnt(6)
	s_barrier
;     __device__ __forceinline__ void operator()(const f32x4 (&acc)[2][2][4][2], const Unit& u, int wr, int wc, int fr, int fq, int lane) const {
;         const bool lat = u.pm < 128;
;         const int s = lat ? (u.pm >> 4) : 8;
;         const float* gate = modi + s * 6144 + 4096 + u.pn * BM + wc * 32 + 4 * fq;
;         const size_t r0 = lat ? (size_t)u.pm * BM : (size_t)(u.pm - 128) * BM;
;         const float* base = (lat ? baseL : baseC) + u.pn * BM + wc * 32 + 4 * fq;
;         float* out = (lat ? outL : outC) + u.pn * BM + wc * 32 + 4 * fq;
;         f32x4 gv[2][2];
; #pragma unroll
;         for (int bj = 0; bj < 2; ++bj)
; #pragma unroll
;             for (int n = 0; n < 2; ++n) gv[bj][n] = *(const f32x4*)(gate + bj * HALF + n * 16);
; #pragma unroll
;         for (int ai = 0; ai < 2; ++ai)
; #pragma unroll
;           for (int mh = 0; mh < 2; ++mh) {
;             f32x4 bs[2][2][2];
; #pragma unroll
;             for (int m2 = 0; m2 < 2; ++m2) {
;                 const size_t ro = (r0 + ai * HALF + wr * 64 + (mh * 2 + m2) * 16 + fr) * (size_t)D;
; #pragma unroll
;                 for (int bj = 0; bj < 2; ++bj)
; #pragma unroll
;                     for (int n = 0; n < 2; ++n) bs[m2][bj][n] = *(const f32x4*)(base + ro + bj * HALF + n * 16);
;             }
;             __builtin_amdgcn_sched_barrier(0);
; #pragma unroll
;             for (int m2 = 0; m2 < 2; ++m2) {
;                 const size_t ro = (r0 + ai * HALF + wr * 64 + (mh * 2 + m2) * 16 + fr) * (size_t)D;
; #pragma unroll
;                 for (int bj = 0; bj < 2; ++bj)
; #pragma unroll
;                     for (int n = 0; n < 2; ++n) *(f32x4*)(out + ro + bj * HALF + n * 16) = bs[m2][bj][n] + gv[bj][n] * acc[ai][bj][mh * 2 + m2][n];
;             }
;             __builtin_amdgcn_sched_barrier(0);
;           }
	s_setprio 1
	v_mfma_f32_16x16x32_bf16 v[48:51], v[224:227], v[172:175], v[48:51]
	v_mfma_f32_16x16x32_bf16 v[40:43], v[232:235], v[172:175], v[40:43]
	v_mfma_f32_16x16x32_bf16 v[36:39], v[224:227], v[180:183], v[36:39]
	v_mfma_f32_16x16x32_bf16 v[32:35], v[232:235], v[180:183], v[32:35]
	v_mfma_f32_16x16x32_bf16 v[16:19], v[224:227], v[208:211], v[16:19]
	v_mfma_f32_16x16x32_bf16 v[8:11], v[232:235], v[208:211], v[8:11]
	v_mfma_f32_16x16x32_bf16 v[4:7], v[224:227], v[216:219], v[4:7]
	v_mfma_f32_16x16x32_bf16 v[0:3], v[232:235], v[216:219], v[0:3]
	v_mfma_f32_16x16x32_bf16 v[48:51], v[228:231], v[176:179], v[48:51]
	v_mfma_f32_16x16x32_bf16 v[40:43], v[236:239], v[176:179], v[40:43]
	v_mfma_f32_16x16x32_bf16 v[36:39], v[228:231], v[204:207], v[36:39]
	v_mfma_f32_16x16x32_bf16 v[32:35], v[236:239], v[204:207], v[32:35]
	v_mfma_f32_16x16x32_bf16 v[16:19], v[228:231], v[212:215], v[16:19]
	v_mfma_f32_16x16x32_bf16 v[8:11], v[236:239], v[212:215], v[8:11]
	v_mfma_f32_16x16x32_bf16 v[4:7], v[228:231], v[220:223], v[4:7]
	v_mfma_f32_16x16x32_bf16 v[0:3], v[236:239], v[220:223], v[0:3]
	s_setprio 0
	s_add_i32 s92, s92, 2
	s_add_u32 s46, s46, 0x100
	s_addc_u32 s47, s47, 0
	s_cmp_gt_u32 s92, 61
	s_barrier
	s_cbranch_scc0 .LBB0_335
	s_waitcnt lgkmcnt(0)
	s_cmpk_lt_i32 s0, 0x80
	s_cselect_b32 s3, s61, s67
	s_cselect_b32 s16, s60, s66
	s_add_i32 s9, s0, 0xffffff80
	s_cmpk_lt_i32 s0, 0x80
	s_cselect_b32 s10, s0, s9
	s_lshr_b32 s9, s0, 4
	s_cmpk_lt_i32 s0, 0x80
	s_mulk_i32 s9, 0x1800
	s_cselect_b32 s14, s9, 0xc000
	s_ashr_i32 s15, s14, 31
	s_lshl_b64 s[14:15], s[14:15], 2
	s_add_u32 s0, s68, s14
	s_addc_u32 s11, s69, s15
	s_lshl_b32 s8, s8, 8
	s_ashr_i32 s9, s8, 31
	s_lshl_b64 s[8:9], s[8:9], 2
	s_add_u32 s0, s0, s8
	s_addc_u32 s11, s11, s9
	s_add_u32 s14, s0, s90
	s_addc_u32 s15, s11, 0
	s_ashr_i32 s11, s10, 31
	s_add_u32 s0, s16, s8
	s_addc_u32 s3, s3, s9
	s_add_u32 s8, s0, s90
	s_addc_u32 s9, s3, 0
	v_lshl_add_u64 v[128:129], s[14:15], 0, v[160:161]
	s_mov_b64 s[14:15], 0x704000
	s_mov_b32 s0, 0x704000
	v_lshl_add_u64 v[154:155], s[8:9], 0, v[160:161]
	s_lshl_b64 s[8:9], s[10:11], 21
	v_lshl_add_u64 v[130:131], v[128:129], 0, s[14:15]
	v_add_co_u32_e32 v128, vcc, s0, v128
	v_lshl_add_u64 v[154:155], v[154:155], 0, s[8:9]
	s_nop 0
	v_addc_co_u32_e32 v129, vcc, 0, v129, vcc
	v_lshl_add_u64 v[154:155], v[154:155], 0, v[148:149]
	s_mov_b32 s0, 0x20000
	v_add_co_u32_e32 v184, vcc, s0, v154
	global_load_dwordx4 v[136:139], v[130:131], off offset:64
	global_load_dwordx4 v[132:135], v[130:131], off offset:512
	global_load_dwordx4 v[140:143], v[128:129], off
	s_nop 0
	global_load_dwordx4 v[128:131], v[130:131], off offset:576
	v_addc_co_u32_e32 v185, vcc, 0, v155, vcc
	global_load_dwordx4 v[168:171], v[154:155], off
	global_load_dwordx4 v[172:175], v[154:155], off offset:64
	global_load_dwordx4 v[176:179], v[154:155], off offset:512
	global_load_dwordx4 v[180:183], v[154:155], off offset:576
	global_load_dwordx4 v[204:207], v[184:185], off
	global_load_dwordx4 v[208:211], v[184:185], off offset:64
	global_load_dwordx4 v[212:215], v[184:185], off offset:512
	global_load_dwordx4 v[216:219], v[184:185], off offset:576
	s_waitcnt vmcnt(0)
	v_pk_fma_f32 v[106:107], v[106:107], v[130:131], v[182:183]
	v_pk_fma_f32 v[104:105], v[104:105], v[128:129], v[180:181]
	global_store_dwordx4 v[154:155], v[104:107], off offset:576
	v_pk_fma_f32 v[126:127], v[126:127], v[142:143], v[170:171]
	v_pk_fma_f32 v[124:125], v[124:125], v[140:141], v[168:169]
	v_pk_fma_f32 v[106:107], v[118:119], v[142:143], v[206:207]
	v_pk_fma_f32 v[104:105], v[116:117], v[140:141], v[204:205]
	v_pk_fma_f32 v[122:123], v[122:123], v[138:139], v[174:175]
	v_pk_fma_f32 v[120:121], v[120:121], v[136:137], v[172:173]
	v_pk_fma_f32 v[114:115], v[114:115], v[134:135], v[178:179]
	v_pk_fma_f32 v[112:113], v[112:113], v[132:133], v[176:177]
	global_store_dwordx4 v[184:185], v[104:107], off
	v_pk_fma_f32 v[102:103], v[102:103], v[134:135], v[214:215]
	v_pk_fma_f32 v[100:101], v[100:101], v[132:133], v[212:213]
	v_pk_fma_f32 v[106:107], v[110:111], v[138:139], v[210:211]
	v_pk_fma_f32 v[104:105], v[108:109], v[136:137], v[208:209]
	v_pk_fma_f32 v[98:99], v[98:99], v[130:131], v[218:219]
	v_pk_fma_f32 v[96:97], v[96:97], v[128:129], v[216:217]
	global_store_dwordx4 v[154:155], v[124:127], off
	global_store_dwordx4 v[154:155], v[120:123], off offset:64
	global_store_dwordx4 v[154:155], v[112:115], off offset:512
	global_store_dwordx4 v[184:185], v[104:107], off offset:64
	global_store_dwordx4 v[184:185], v[100:103], off offset:512
	global_store_dwordx4 v[184:185], v[96:99], off offset:576
	s_mov_b32 s0, 0x40000
	v_add_co_u32_e32 v168, vcc, s0, v154
	s_mov_b32 s0, 0x60000
	s_nop 0
	v_addc_co_u32_e32 v169, vcc, 0, v155, vcc
	v_add_co_u32_e32 v170, vcc, s0, v154
	global_load_dwordx4 v[96:99], v[168:169], off
	global_load_dwordx4 v[100:103], v[168:169], off offset:64
	global_load_dwordx4 v[104:107], v[168:169], off offset:512
	global_load_dwordx4 v[108:111], v[168:169], off offset:576
	v_addc_co_u32_e32 v171, vcc, 0, v155, vcc
	global_load_dwordx4 v[112:115], v[170:171], off
	global_load_dwordx4 v[116:119], v[170:171], off offset:64
	global_load_dwordx4 v[120:123], v[170:171], off offset:512
	global_load_dwordx4 v[124:127], v[170:171], off offset:576
	s_waitcnt vmcnt(0)
; #define PG8_WAIT_V(n) asm volatile("s_waitcnt vmcnt(" #n ")" ::: "memory")
; #define PG8_BAR __builtin_amdgcn_s_barrier()
;     ...
;     PG8_WAIT_V(0);
;     if (wr == 0) PG8_BAR;
;     PG8_BAR;
;     __device__ __forceinline__ void operator()(const f32x4 (&acc)[2][2][4][2], const Unit& u, int wr, int wc, int fr, int fq, int lane) const {
;     ...
; #pragma unroll
;         for (int ai = 0; ai < 2; ++ai)
; #pragma unroll
;           for (int mh = 0; mh < 2; ++mh) {
;             f32x4 bs[2][2][2];
; #pragma unroll
;             for (int m2 = 0; m2 < 2; ++m2) {
;                 const size_t ro = (r0 + ai * HALF + wr * 64 + (mh * 2 + m2) * 16 + fr) * (size_t)D;
; #pragma unroll
;                 for (int bj = 0; bj < 2; ++bj)
; #pragma unroll
;                     for (int n = 0; n < 2; ++n) bs[m2][bj][n] = *(const f32x4*)(base + ro + bj * HALF + n * 16);
;             }
;             __builtin_amdgcn_sched_barrier(0);
; #pragma unroll
;             for (int m2 = 0; m2 < 2; ++m2) {
;                 const size_t ro = (r0 + ai * HALF + wr * 64 + (mh * 2 + m2) * 16 + fr) * (size_t)D;
; #pragma unroll
;                 for (int bj = 0; bj < 2; ++bj)
; #pragma unroll
;                     for (int n = 0; n < 2; ++n) *(f32x4*)(out + ro + bj * HALF + n * 16) = bs[m2][bj][n] + gv[bj][n] * acc[ai][bj][mh * 2 + m2][n];
;             }
;             __builtin_amdgcn_sched_barrier(0);
;           }
	v_pk_fma_f32 v[74:75], v[74:75], v[130:131], v[110:111]
	v_pk_fma_f32 v[72:73], v[72:73], v[128:129], v[108:109]
	global_store_dwordx4 v[168:169], v[72:75], off offset:576
	v_pk_fma_f32 v[94:95], v[94:95], v[142:143], v[98:99]
	v_pk_fma_f32 v[92:93], v[92:93], v[140:141], v[96:97]
	v_pk_fma_f32 v[74:75], v[86:87], v[142:143], v[114:115]
	v_pk_fma_f32 v[72:73], v[84:85], v[140:141], v[112:113]
	v_pk_fma_f32 v[90:91], v[90:91], v[138:139], v[102:103]
	v_pk_fma_f32 v[88:89], v[88:89], v[136:137], v[100:101]
	v_pk_fma_f32 v[82:83], v[82:83], v[134:135], v[106:107]
	v_pk_fma_f32 v[80:81], v[80:81], v[132:133], v[104:105]
	global_store_dwordx4 v[170:171], v[72:75], off
	v_pk_fma_f32 v[70:71], v[70:71], v[134:135], v[122:123]
	v_pk_fma_f32 v[68:69], v[68:69], v[132:133], v[120:121]
	v_pk_fma_f32 v[74:75], v[78:79], v[138:139], v[118:119]
	v_pk_fma_f32 v[72:73], v[76:77], v[136:137], v[116:117]
	v_pk_fma_f32 v[66:67], v[66:67], v[130:131], v[126:127]
	v_pk_fma_f32 v[64:65], v[64:65], v[128:129], v[124:125]
	global_store_dwordx4 v[168:169], v[92:95], off
	global_store_dwordx4 v[168:169], v[88:91], off offset:64
	global_store_dwordx4 v[168:169], v[80:83], off offset:512
	global_store_dwordx4 v[170:171], v[72:75], off offset:64
	global_store_dwordx4 v[170:171], v[68:71], off offset:512
	global_store_dwordx4 v[170:171], v[64:67], off offset:576
	v_add_co_u32_e32 v96, vcc, s76, v154
	s_nop 1
	v_addc_co_u32_e32 v97, vcc, 0, v155, vcc
	v_add_co_u32_e32 v98, vcc, s77, v154
	global_load_dwordx4 v[64:67], v[96:97], off
	global_load_dwordx4 v[68:71], v[96:97], off offset:64
	global_load_dwordx4 v[72:75], v[96:97], off offset:512
	global_load_dwordx4 v[76:79], v[96:97], off offset:576
	v_addc_co_u32_e32 v99, vcc, 0, v155, vcc
	global_load_dwordx4 v[80:83], v[98:99], off
	global_load_dwordx4 v[84:87], v[98:99], off offset:64
	global_load_dwordx4 v[88:91], v[98:99], off offset:512
	global_load_dwordx4 v[92:95], v[98:99], off offset:576
	s_waitcnt vmcnt(0)
	v_pk_fma_f32 v[42:43], v[42:43], v[130:131], v[78:79]
	v_pk_fma_f32 v[40:41], v[40:41], v[128:129], v[76:77]
	global_store_dwordx4 v[96:97], v[40:43], off offset:576
	v_pk_fma_f32 v[62:63], v[62:63], v[142:143], v[66:67]
	v_pk_fma_f32 v[60:61], v[60:61], v[140:141], v[64:65]
	v_pk_fma_f32 v[42:43], v[54:55], v[142:143], v[82:83]
	v_pk_fma_f32 v[40:41], v[52:53], v[140:141], v[80:81]
	v_pk_fma_f32 v[58:59], v[58:59], v[138:139], v[70:71]
	v_pk_fma_f32 v[56:57], v[56:57], v[136:137], v[68:69]
	v_pk_fma_f32 v[50:51], v[50:51], v[134:135], v[74:75]
	v_pk_fma_f32 v[48:49], v[48:49], v[132:133], v[72:73]
	global_store_dwordx4 v[98:99], v[40:43], off
	v_pk_fma_f32 v[38:39], v[38:39], v[134:135], v[90:91]
	v_pk_fma_f32 v[36:37], v[36:37], v[132:133], v[88:89]
	v_pk_fma_f32 v[42:43], v[46:47], v[138:139], v[86:87]
	v_pk_fma_f32 v[40:41], v[44:45], v[136:137], v[84:85]
	v_pk_fma_f32 v[34:35], v[34:35], v[130:131], v[94:95]
	v_pk_fma_f32 v[32:33], v[32:33], v[128:129], v[92:93]
	global_store_dwordx4 v[96:97], v[60:63], off
	global_store_dwordx4 v[96:97], v[56:59], off offset:64
	global_store_dwordx4 v[96:97], v[48:51], off offset:512
	global_store_dwordx4 v[98:99], v[40:43], off offset:64
	global_store_dwordx4 v[98:99], v[36:39], off offset:512
	global_store_dwordx4 v[98:99], v[32:35], off offset:576
	v_add_co_u32_e32 v64, vcc, s18, v154
	s_nop 1
	v_addc_co_u32_e32 v65, vcc, 0, v155, vcc
	v_add_co_u32_e32 v66, vcc, s54, v154
	global_load_dwordx4 v[32:35], v[64:65], off
	global_load_dwordx4 v[36:39], v[64:65], off offset:64
	global_load_dwordx4 v[40:43], v[64:65], off offset:512
	global_load_dwordx4 v[44:47], v[64:65], off offset:576
	v_addc_co_u32_e32 v67, vcc, 0, v155, vcc
	global_load_dwordx4 v[48:51], v[66:67], off
	global_load_dwordx4 v[52:55], v[66:67], off offset:64
	global_load_dwordx4 v[56:59], v[66:67], off offset:512
	global_load_dwordx4 v[60:63], v[66:67], off offset:576
	s_waitcnt vmcnt(0)
	v_pk_fma_f32 v[10:11], v[10:11], v[130:131], v[46:47]
	v_pk_fma_f32 v[8:9], v[8:9], v[128:129], v[44:45]
	global_store_dwordx4 v[64:65], v[8:11], off offset:576
	v_pk_fma_f32 v[30:31], v[30:31], v[142:143], v[34:35]
	v_pk_fma_f32 v[28:29], v[28:29], v[140:141], v[32:33]
	v_pk_fma_f32 v[10:11], v[22:23], v[142:143], v[50:51]
	v_pk_fma_f32 v[8:9], v[20:21], v[140:141], v[48:49]
	v_pk_fma_f32 v[26:27], v[26:27], v[138:139], v[38:39]
	v_pk_fma_f32 v[24:25], v[24:25], v[136:137], v[36:37]
	v_pk_fma_f32 v[18:19], v[18:19], v[134:135], v[42:43]
	v_pk_fma_f32 v[16:17], v[16:17], v[132:133], v[40:41]
	global_store_dwordx4 v[66:67], v[8:11], off
	v_pk_fma_f32 v[6:7], v[6:7], v[134:135], v[58:59]
	v_pk_fma_f32 v[4:5], v[4:5], v[132:133], v[56:57]
	v_pk_fma_f32 v[10:11], v[14:15], v[138:139], v[54:55]
	v_pk_fma_f32 v[8:9], v[12:13], v[136:137], v[52:53]
	v_pk_fma_f32 v[2:3], v[2:3], v[130:131], v[62:63]
	v_pk_fma_f32 v[0:1], v[0:1], v[128:129], v[60:61]
	global_store_dwordx4 v[64:65], v[28:31], off
	global_store_dwordx4 v[64:65], v[24:27], off offset:64
	global_store_dwordx4 v[64:65], v[16:19], off offset:512
	global_store_dwordx4 v[66:67], v[8:11], off offset:64
	global_store_dwordx4 v[66:67], v[4:7], off offset:512
	global_store_dwordx4 v[66:67], v[0:3], off offset:576
	s_and_b64 vcc, exec, s[42:43]
	s_mov_b32 s8, s2
	s_mov_b32 s0, s26
	s_mov_b64 s[20:21], s[38:39]
	s_mov_b64 s[44:45], s[36:37]
	s_cbranch_vccz .LBB0_332
	s_waitcnt vmcnt(0)
	s_cmpk_gt_u32 s5, 0xff
	s_cbranch_scc1 .LBB0_339
	s_barrier

; #define PG8_STAGE_A(bufoff, ptr, half, rev) do { if (REVA && (rev)) { const char* _p = (ptr) - ((half) ? hstepA : 0); PG8_STAGE(bufoff, _p, voffAr); } else { const char* _p = (ptr) + ((half) ? hstepA : 0); PG8_STAGE(bufoff, _p, voffA); } } while (0)
; #define PG8_LDA(dst, b, h) do { _Pragma("unroll") for (int m = 0; m < 4; ++m) _Pragma("unroll") for (int k = 0; k < 2; ++k) dst[m][k] = *(const LAS bf16x8*)(lds + PG8_SA(b, h) + aoff + m * 2048 + k * 1024); } while (0)
; #define PG8_LDB(dst, b, h) do { _Pragma("unroll") for (int n = 0; n < 2; ++n) _Pragma("unroll") for (int k = 0; k < 2; ++k) dst[n][k] = *(const LAS bf16x8*)(lds + PG8_SB(b, h) + boff + n * 2048 + k * 1024); } while (0)
; #define PG8_WAIT_L(n) asm volatile("s_waitcnt lgkmcnt(" #n ")" ::: "memory")
; #define PG8_BAR __builtin_amdgcn_s_barrier()
; #define PG8_SCHED __builtin_amdgcn_sched_barrier(0)
;     ...
;     for (;;) {
;         const bool has_next = next_unit(ui + 1, nM, nN, MP, nxt, rot);
;         const char* nA = has_next ? nxt.a : cA; const char* nB = has_next ? nxt.b : cB; const char* nAr = has_next ? nxt.ar : cAr; const size_t nHb = has_next ? nxt.hb : cHb;
;         for (int t = 0; t < nt; t += 2) {
;             const bool last = (t == nt - 2);
;             const char* a1 = PG8_APTR(cA, cAr, t + 1); const bool r1 = REVA && ((t + 1) & 4);
;             const char* a2 = last ? nA : PG8_APTR(cA, cAr, t + 2); const bool r2 = REVA && !last && ((t + 2) & 4);
;             const char* a3 = last ? nA + kstep : PG8_APTR(cA, cAr, t + 3); const bool r3 = REVA && !last && ((t + 3) & 4);
;             const char* b2 = last ? nB : cB + (size_t)(t + 2) * kstep; const char* b3 = b2 + kstep; const size_t hb2 = last ? nHb : cHb;
;             PG8_LDB(B0, 0, 0); PG8_SCHED; PG8_LDA(At, 0, 0); PG8_STAGE_A(PG8_SA(1, 1), a1, 1, r1);
;             PG8_WAIT_L(8); PG8_BAR; PG8_WAIT_L(0); PG8_MMA(0, 0, At, B0); PG8_BAR; PG8_SCHED;
;     ...
; #pragma unroll
;         for (int a = 0; a < 2; ++a)
; #pragma unroll
;             for (int b = 0; b < 2; ++b)
; #pragma unroll
;                 for (int m = 0; m < 4; ++m)
; #pragma unroll
;                     for (int n = 0; n < 2; ++n) acc[a][b][m][n] = (f32x4){0.f, 0.f, 0.f, 0.f};
;         cur = nxt; cA = nA; cB = nB; cAr = nAr; cHb = nHb; ++ui;
.LBB0_521:
	s_add_u32 s6, s38, 0x80
	s_addc_u32 s7, s39, 0
	s_add_u32 s8, s44, 0x80080
	s_addc_u32 s9, s45, 0
	v_lshl_add_u64 v[144:145], s[8:9], 0, v[140:141]
	v_lshl_add_u64 v[146:147], s[8:9], 0, v[142:143]
	s_add_u32 s8, s0, 0x100
	v_mov_b32_e32 v0, 0
	s_addc_u32 s9, s1, 0
	s_mov_b32 s22, -2
	s_mov_b64 s[0:1], 0
	v_mov_b32_e32 v1, v0
	v_mov_b32_e32 v2, v0
	v_mov_b32_e32 v3, v0
	v_mov_b32_e32 v4, v0
	v_mov_b32_e32 v5, v0
	v_mov_b32_e32 v6, v0
	v_mov_b32_e32 v7, v0
	v_mov_b32_e32 v16, v0
	v_mov_b32_e32 v17, v0
	v_mov_b32_e32 v18, v0
	v_mov_b32_e32 v19, v0
	v_mov_b32_e32 v20, v0
	v_mov_b32_e32 v21, v0
	v_mov_b32_e32 v22, v0
	v_mov_b32_e32 v23, v0
	v_mov_b32_e32 v32, v0
	v_mov_b32_e32 v33, v0
	v_mov_b32_e32 v34, v0
	v_mov_b32_e32 v35, v0
	v_mov_b32_e32 v36, v0
	v_mov_b32_e32 v37, v0
	v_mov_b32_e32 v38, v0
	v_mov_b32_e32 v39, v0
	v_mov_b32_e32 v48, v0
	v_mov_b32_e32 v49, v0
	v_mov_b32_e32 v50, v0
	v_mov_b32_e32 v51, v0
	v_mov_b32_e32 v52, v0
	v_mov_b32_e32 v53, v0
	v_mov_b32_e32 v54, v0
	v_mov_b32_e32 v55, v0
	v_mov_b32_e32 v8, v0
	v_mov_b32_e32 v9, v0
	v_mov_b32_e32 v10, v0
	v_mov_b32_e32 v11, v0
	v_mov_b32_e32 v12, v0
	v_mov_b32_e32 v13, v0
	v_mov_b32_e32 v14, v0
	v_mov_b32_e32 v15, v0
	v_mov_b32_e32 v24, v0
	v_mov_b32_e32 v25, v0
	v_mov_b32_e32 v26, v0
	v_mov_b32_e32 v27, v0
	v_mov_b32_e32 v28, v0
	v_mov_b32_e32 v29, v0
	v_mov_b32_e32 v30, v0
	v_mov_b32_e32 v31, v0
	v_mov_b32_e32 v40, v0
	v_mov_b32_e32 v41, v0
	v_mov_b32_e32 v42, v0
	v_mov_b32_e32 v43, v0
	v_mov_b32_e32 v44, v0
	v_mov_b32_e32 v45, v0
	v_mov_b32_e32 v46, v0
	v_mov_b32_e32 v47, v0
	v_mov_b32_e32 v56, v0
	v_mov_b32_e32 v57, v0
	v_mov_b32_e32 v58, v0
	v_mov_b32_e32 v59, v0
	v_mov_b32_e32 v60, v0
	v_mov_b32_e32 v61, v0
	v_mov_b32_e32 v62, v0
	v_mov_b32_e32 v63, v0
	v_mov_b32_e32 v64, v0
	v_mov_b32_e32 v65, v0
	v_mov_b32_e32 v66, v0
	v_mov_b32_e32 v67, v0
	v_mov_b32_e32 v68, v0
	v_mov_b32_e32 v69, v0
	v_mov_b32_e32 v70, v0
	v_mov_b32_e32 v71, v0
	v_mov_b32_e32 v80, v0
	v_mov_b32_e32 v81, v0
	v_mov_b32_e32 v82, v0
	v_mov_b32_e32 v83, v0
	v_mov_b32_e32 v84, v0
	v_mov_b32_e32 v85, v0
	v_mov_b32_e32 v86, v0
	v_mov_b32_e32 v87, v0
	v_mov_b32_e32 v96, v0
	v_mov_b32_e32 v97, v0
	v_mov_b32_e32 v98, v0
	v_mov_b32_e32 v99, v0
	v_mov_b32_e32 v100, v0
	v_mov_b32_e32 v101, v0
	v_mov_b32_e32 v102, v0
	v_mov_b32_e32 v103, v0
	v_mov_b32_e32 v112, v0
	v_mov_b32_e32 v113, v0
	v_mov_b32_e32 v114, v0
	v_mov_b32_e32 v115, v0
	v_mov_b32_e32 v116, v0
	v_mov_b32_e32 v117, v0
	v_mov_b32_e32 v118, v0
	v_mov_b32_e32 v119, v0
	v_mov_b32_e32 v72, v0
	v_mov_b32_e32 v73, v0
	v_mov_b32_e32 v74, v0
	v_mov_b32_e32 v75, v0
	v_mov_b32_e32 v76, v0
	v_mov_b32_e32 v77, v0
	v_mov_b32_e32 v78, v0
	v_mov_b32_e32 v79, v0
	v_mov_b32_e32 v88, v0
	v_mov_b32_e32 v89, v0
	v_mov_b32_e32 v90, v0
	v_mov_b32_e32 v91, v0
	v_mov_b32_e32 v92, v0
	v_mov_b32_e32 v93, v0
	v_mov_b32_e32 v94, v0
	v_mov_b32_e32 v95, v0
	v_mov_b32_e32 v104, v0
	v_mov_b32_e32 v105, v0
	v_mov_b32_e32 v106, v0
	v_mov_b32_e32 v107, v0
	v_mov_b32_e32 v108, v0
	v_mov_b32_e32 v109, v0
	v_mov_b32_e32 v110, v0
	v_mov_b32_e32 v111, v0
	v_mov_b32_e32 v120, v0
	v_mov_b32_e32 v121, v0
	v_mov_b32_e32 v122, v0
	v_mov_b32_e32 v123, v0
	v_mov_b32_e32 v124, v0
	v_mov_b32_e32 v125, v0
	v_mov_b32_e32 v126, v0
	v_mov_b32_e32 v127, v0
	v_add_u32_e32 v160, 0x10000, v139
	ds_read_b128 v[156:159], v160
	ds_read_b128 v[168:171], v160 offset:1024
	ds_read_b128 v[172:175], v160 offset:2048
	ds_read_b128 v[176:179], v160 offset:3072
.LBB0_522:
	s_add_u32 s10, s44, s0
	s_addc_u32 s11, s45, s1
	s_add_u32 s14, s10, 0x100
	s_addc_u32 s15, s11, 0
	s_add_u32 s10, s10, 0x180
	s_addc_u32 s11, s11, 0
	s_add_u32 s16, s8, s0
	s_addc_u32 s17, s9, s1
	s_add_i32 s27, 0, 0x10000
	s_cmpk_eq_i32 s0, 0xf00
	s_cselect_b32 s21, s47, s17
	s_cselect_b32 s20, s46, s16
	s_cselect_b32 s17, s39, s15
	s_cselect_b32 s16, s38, s14
	s_cselect_b32 s90, s37, s3
	s_cselect_b32 s91, s36, s2
	s_cselect_b32 s15, s7, s11
	s_cselect_b32 s14, s6, s10
	v_lshl_add_u64 v[184:185], v[144:145], 0, s[0:1]
	s_add_i32 m0, s66, 0xc000
	ds_read_b128 v[180:183], v155
	ds_read_b128 v[204:207], v155 offset:1024
	ds_read_b128 v[208:211], v155 offset:2048
	ds_read_b128 v[212:215], v155 offset:3072
	ds_read_b128 v[216:219], v155 offset:4096
	ds_read_b128 v[220:223], v155 offset:5120
	ds_read_b128 v[224:227], v155 offset:6144
	ds_read_b128 v[228:231], v155 offset:7168
	global_load_lds_dwordx4 v[184:185], off
	v_lshl_add_u64 v[184:185], v[146:147], 0, s[0:1]
	s_add_i32 m0, s66, 0xe000
	s_nop 0
	global_load_lds_dwordx4 v[184:185], off
	s_waitcnt lgkmcnt(8)
	s_barrier
	s_waitcnt lgkmcnt(0)
	s_setprio 1
	s_waitcnt lgkmcnt(0)
	v_mfma_f32_16x16x32_bf16 v[124:127], v[156:159], v[180:183], v[124:127]
	v_mfma_f32_16x16x32_bf16 v[120:123], v[172:175], v[180:183], v[120:123]
	v_mfma_f32_16x16x32_bf16 v[108:111], v[156:159], v[208:211], v[108:111]
	v_mfma_f32_16x16x32_bf16 v[104:107], v[172:175], v[208:211], v[104:107]
	v_mfma_f32_16x16x32_bf16 v[92:95], v[156:159], v[216:219], v[92:95]
	v_mfma_f32_16x16x32_bf16 v[88:91], v[172:175], v[216:219], v[88:91]
	v_mfma_f32_16x16x32_bf16 v[76:79], v[156:159], v[224:227], v[76:79]
	v_mfma_f32_16x16x32_bf16 v[72:75], v[172:175], v[224:227], v[72:75]
	v_mfma_f32_16x16x32_bf16 v[124:127], v[168:171], v[204:207], v[124:127]
	v_mfma_f32_16x16x32_bf16 v[120:123], v[176:179], v[204:207], v[120:123]
	v_mfma_f32_16x16x32_bf16 v[108:111], v[168:171], v[212:215], v[108:111]
	v_mfma_f32_16x16x32_bf16 v[104:107], v[176:179], v[212:215], v[104:107]
	v_mfma_f32_16x16x32_bf16 v[92:95], v[168:171], v[220:223], v[92:95]
	v_mfma_f32_16x16x32_bf16 v[88:91], v[176:179], v[220:223], v[88:91]
	v_mfma_f32_16x16x32_bf16 v[76:79], v[168:171], v[228:231], v[76:79]
	v_mfma_f32_16x16x32_bf16 v[72:75], v[176:179], v[228:231], v[72:75]
	s_setprio 0
	s_barrier
; #define PG8_STAGE(bufoff, gbase, voff) do { _Pragma("unroll") for (int _i = 0; _i < 2; ++_i) \
;         __builtin_amdgcn_global_load_lds((const unsigned*)((const char*)(gbase) + (voff)[_i]), (LAS unsigned*)(lds + (bufoff) + ldsw + _i * 8192), 16, 0, 0); } while (0)
; #define PG8_STAGE_A(bufoff, ptr, half, rev) do { if (REVA && (rev)) { const char* _p = (ptr) - ((half) ? hstepA : 0); PG8_STAGE(bufoff, _p, voffAr); } else { const char* _p = (ptr) + ((half) ? hstepA : 0); PG8_STAGE(bufoff, _p, voffA); } } while (0)
; #define PG8_LDA(dst, b, h) do { _Pragma("unroll") for (int m = 0; m < 4; ++m) _Pragma("unroll") for (int k = 0; k < 2; ++k) dst[m][k] = *(const LAS bf16x8*)(lds + PG8_SA(b, h) + aoff + m * 2048 + k * 1024); } while (0)
; #define PG8_LDB(dst, b, h) do { _Pragma("unroll") for (int n = 0; n < 2; ++n) _Pragma("unroll") for (int k = 0; k < 2; ++k) dst[n][k] = *(const LAS bf16x8*)(lds + PG8_SB(b, h) + boff + n * 2048 + k * 1024); } while (0)
; #define PG8_MMA(ai, bj, At, Bt) do { __builtin_amdgcn_s_setprio(1); _Pragma("unroll") for (int m = 0; m < 4; ++m) _Pragma("unroll") for (int n = 0; n < 2; ++n) _Pragma("unroll") for (int k = 0; k < 2; ++k) \
;         acc[ai][bj][m][n] = __builtin_amdgcn_mfma_f32_16x16x32_bf16(Bt[n][k], At[m][k], acc[ai][bj][m][n], 0, 0, 0); __builtin_amdgcn_s_setprio(0); } while (0)
; #define PG8_WAIT_V(n) asm volatile("s_waitcnt vmcnt(" #n ")" ::: "memory")
; #define PG8_WAIT_L(n) asm volatile("s_waitcnt lgkmcnt(" #n ")" ::: "memory")
; #define PG8_BAR __builtin_amdgcn_s_barrier()
; #define PG8_SCHED __builtin_amdgcn_sched_barrier(0)
;     ...
;             PG8_LDB(B1, 0, 1); PG8_STAGE(PG8_SB(0, 0), b2, voffB);
;             PG8_BAR; PG8_WAIT_L(0); PG8_MMA(0, 1, At, B1); PG8_BAR;
;             PG8_LDA(At, 0, 1); PG8_STAGE_A(PG8_SA(0, 0), a2, 0, r2);
;             PG8_BAR; PG8_WAIT_L(0); PG8_MMA(1, 0, At, B0); PG8_BAR; PG8_SCHED;
;             PG8_STAGE(PG8_SB(0, 1), b2 + hb2, voffB);
;             PG8_WAIT_V(6); PG8_BAR; PG8_MMA(1, 1, At, B1); PG8_BAR;
;             PG8_LDB(B0, 1, 0); PG8_SCHED; PG8_LDA(At, 1, 0); PG8_STAGE_A(PG8_SA(0, 1), a2, 1, r2);
	s_add_i32 s10, 0, 0x14000
	s_add_i32 s11, s27, s53
	v_add_u32_e32 v160, s10, v139
	v_lshl_add_u64 v[184:185], s[20:21], 0, v[130:131]
	s_mov_b32 m0, s11
	ds_read_b128 v[232:235], v160
	ds_read_b128 v[236:239], v160 offset:1024
	ds_read_b128 v[240:243], v160 offset:2048
	ds_read_b128 v[244:247], v160 offset:3072
	global_load_lds_dwordx4 v[184:185], off
	v_lshl_add_u64 v[248:249], s[20:21], 0, v[134:135]
	s_add_i32 m0, s11, 0x2000
	s_nop 0
	global_load_lds_dwordx4 v[248:249], off
	s_barrier
	s_waitcnt lgkmcnt(0)
	s_setprio 1
	s_waitcnt lgkmcnt(0)
	v_mfma_f32_16x16x32_bf16 v[116:119], v[232:235], v[180:183], v[116:119]
	v_mfma_f32_16x16x32_bf16 v[112:115], v[240:243], v[180:183], v[112:115]
	v_mfma_f32_16x16x32_bf16 v[100:103], v[232:235], v[208:211], v[100:103]
	v_mfma_f32_16x16x32_bf16 v[96:99], v[240:243], v[208:211], v[96:99]
	v_mfma_f32_16x16x32_bf16 v[84:87], v[232:235], v[216:219], v[84:87]
	v_mfma_f32_16x16x32_bf16 v[80:83], v[240:243], v[216:219], v[80:83]
	v_mfma_f32_16x16x32_bf16 v[68:71], v[232:235], v[224:227], v[68:71]
	v_mfma_f32_16x16x32_bf16 v[64:67], v[240:243], v[224:227], v[64:67]
	v_mfma_f32_16x16x32_bf16 v[116:119], v[236:239], v[204:207], v[116:119]
	v_mfma_f32_16x16x32_bf16 v[112:115], v[244:247], v[204:207], v[112:115]
	v_mfma_f32_16x16x32_bf16 v[100:103], v[236:239], v[212:215], v[100:103]
	v_mfma_f32_16x16x32_bf16 v[96:99], v[244:247], v[212:215], v[96:99]
	v_mfma_f32_16x16x32_bf16 v[84:87], v[236:239], v[220:223], v[84:87]
	v_mfma_f32_16x16x32_bf16 v[80:83], v[244:247], v[220:223], v[80:83]
	v_mfma_f32_16x16x32_bf16 v[68:71], v[236:239], v[228:231], v[68:71]
	v_mfma_f32_16x16x32_bf16 v[64:67], v[244:247], v[228:231], v[64:67]
	s_setprio 0
	s_mov_b32 m0, s66
	v_lshl_add_u64 v[250:251], s[16:17], 0, v[128:129]
	s_barrier
	ds_read_b128 v[180:183], v155 offset:16384
	ds_read_b128 v[204:207], v155 offset:17408
	ds_read_b128 v[208:211], v155 offset:18432
	ds_read_b128 v[212:215], v155 offset:19456
	ds_read_b128 v[216:219], v155 offset:20480
	ds_read_b128 v[220:223], v155 offset:21504
	ds_read_b128 v[224:227], v155 offset:22528
	ds_read_b128 v[228:231], v155 offset:23552
	global_load_lds_dwordx4 v[250:251], off
	v_lshl_add_u64 v[250:251], s[16:17], 0, v[132:133]
	s_mov_b32 m0, s67
	s_nop 0
	global_load_lds_dwordx4 v[250:251], off
	s_waitcnt vmcnt(10)
	s_barrier
	s_waitcnt lgkmcnt(0)
	s_setprio 1
	s_waitcnt lgkmcnt(0)
	v_mfma_f32_16x16x32_bf16 v[60:63], v[156:159], v[180:183], v[60:63]
	v_mfma_f32_16x16x32_bf16 v[56:59], v[172:175], v[180:183], v[56:59]
	v_mfma_f32_16x16x32_bf16 v[44:47], v[156:159], v[208:211], v[44:47]
	v_mfma_f32_16x16x32_bf16 v[40:43], v[172:175], v[208:211], v[40:43]
	v_mfma_f32_16x16x32_bf16 v[28:31], v[156:159], v[216:219], v[28:31]
	v_mfma_f32_16x16x32_bf16 v[24:27], v[172:175], v[216:219], v[24:27]
	v_mfma_f32_16x16x32_bf16 v[12:15], v[156:159], v[224:227], v[12:15]
	v_mfma_f32_16x16x32_bf16 v[8:11], v[172:175], v[224:227], v[8:11]
	v_mfma_f32_16x16x32_bf16 v[60:63], v[168:171], v[204:207], v[60:63]
	v_mfma_f32_16x16x32_bf16 v[56:59], v[176:179], v[204:207], v[56:59]
	v_mfma_f32_16x16x32_bf16 v[44:47], v[168:171], v[212:215], v[44:47]
	v_mfma_f32_16x16x32_bf16 v[40:43], v[176:179], v[212:215], v[40:43]
	v_mfma_f32_16x16x32_bf16 v[28:31], v[168:171], v[220:223], v[28:31]
	v_mfma_f32_16x16x32_bf16 v[24:27], v[176:179], v[220:223], v[24:27]
	v_mfma_f32_16x16x32_bf16 v[12:15], v[168:171], v[228:231], v[12:15]
	v_mfma_f32_16x16x32_bf16 v[8:11], v[176:179], v[228:231], v[8:11]
	s_setprio 0
	s_barrier
	s_add_u32 s20, s20, s91
	s_addc_u32 s21, s21, s90
	s_add_i32 s10, s10, s53
	v_lshl_add_u64 v[250:251], s[20:21], 0, v[130:131]
	s_mov_b32 m0, s10
	v_lshl_add_u64 v[190:191], s[20:21], 0, v[134:135]
	global_load_lds_dwordx4 v[250:251], off
	s_add_i32 m0, s10, 0x2000
	s_nop 0
	global_load_lds_dwordx4 v[190:191], off
	v_add_u32_e32 v160, 0x18000, v139
	ds_read_b128 v[156:159], v160
	ds_read_b128 v[168:171], v160 offset:1024
	ds_read_b128 v[172:175], v160 offset:2048
	ds_read_b128 v[176:179], v160 offset:3072
	s_waitcnt vmcnt(6)
	s_barrier
	s_setprio 1
	v_mfma_f32_16x16x32_bf16 v[52:55], v[232:235], v[180:183], v[52:55]
	v_mfma_f32_16x16x32_bf16 v[48:51], v[240:243], v[180:183], v[48:51]
	v_mfma_f32_16x16x32_bf16 v[36:39], v[232:235], v[208:211], v[36:39]
	v_mfma_f32_16x16x32_bf16 v[32:35], v[240:243], v[208:211], v[32:35]
	v_mfma_f32_16x16x32_bf16 v[20:23], v[232:235], v[216:219], v[20:23]
	v_mfma_f32_16x16x32_bf16 v[16:19], v[240:243], v[216:219], v[16:19]
	v_mfma_f32_16x16x32_bf16 v[4:7], v[232:235], v[224:227], v[4:7]
	v_mfma_f32_16x16x32_bf16 v[0:3], v[240:243], v[224:227], v[0:3]
	v_mfma_f32_16x16x32_bf16 v[52:55], v[236:239], v[204:207], v[52:55]
	v_mfma_f32_16x16x32_bf16 v[48:51], v[244:247], v[204:207], v[48:51]
	v_mfma_f32_16x16x32_bf16 v[36:39], v[236:239], v[212:215], v[36:39]
	v_mfma_f32_16x16x32_bf16 v[32:35], v[244:247], v[212:215], v[32:35]
	v_mfma_f32_16x16x32_bf16 v[20:23], v[236:239], v[220:223], v[20:23]
	v_mfma_f32_16x16x32_bf16 v[16:19], v[244:247], v[220:223], v[16:19]
	v_mfma_f32_16x16x32_bf16 v[4:7], v[236:239], v[228:231], v[4:7]
	v_mfma_f32_16x16x32_bf16 v[0:3], v[244:247], v[228:231], v[0:3]
	s_setprio 0
	s_add_i32 s10, 0, 0x18000
	s_barrier
	s_add_u32 s16, s16, 0x80000
	s_addc_u32 s17, s17, 0
	s_mov_b32 m0, s68
	v_lshl_add_u64 v[232:233], s[16:17], 0, v[128:129]
	ds_read_b128 v[180:183], v155 offset:32768
	ds_read_b128 v[204:207], v155 offset:33792
	ds_read_b128 v[208:211], v155 offset:34816
	ds_read_b128 v[212:215], v155 offset:35840
	ds_read_b128 v[216:219], v155 offset:36864
	ds_read_b128 v[220:223], v155 offset:37888
	ds_read_b128 v[224:227], v155 offset:38912
	ds_read_b128 v[228:231], v155 offset:39936
	global_load_lds_dwordx4 v[232:233], off
	v_lshl_add_u64 v[232:233], s[16:17], 0, v[132:133]
	s_mov_b32 m0, s69
	s_nop 0
	global_load_lds_dwordx4 v[232:233], off
	s_waitcnt lgkmcnt(8)
	s_barrier
; #define PG8_STAGE(bufoff, gbase, voff) do { _Pragma("unroll") for (int _i = 0; _i < 2; ++_i) \
;         __builtin_amdgcn_global_load_lds((const unsigned*)((const char*)(gbase) + (voff)[_i]), (LAS unsigned*)(lds + (bufoff) + ldsw + _i * 8192), 16, 0, 0); } while (0)
; #define PG8_STAGE_A(bufoff, ptr, half, rev) do { if (REVA && (rev)) { const char* _p = (ptr) - ((half) ? hstepA : 0); PG8_STAGE(bufoff, _p, voffAr); } else { const char* _p = (ptr) + ((half) ? hstepA : 0); PG8_STAGE(bufoff, _p, voffA); } } while (0)
; #define PG8_LDA(dst, b, h) do { _Pragma("unroll") for (int m = 0; m < 4; ++m) _Pragma("unroll") for (int k = 0; k < 2; ++k) dst[m][k] = *(const LAS bf16x8*)(lds + PG8_SA(b, h) + aoff + m * 2048 + k * 1024); } while (0)
; #define PG8_LDB(dst, b, h) do { _Pragma("unroll") for (int n = 0; n < 2; ++n) _Pragma("unroll") for (int k = 0; k < 2; ++k) dst[n][k] = *(const LAS bf16x8*)(lds + PG8_SB(b, h) + boff + n * 2048 + k * 1024); } while (0)
; #define PG8_MMA(ai, bj, At, Bt) do { __builtin_amdgcn_s_setprio(1); _Pragma("unroll") for (int m = 0; m < 4; ++m) _Pragma("unroll") for (int n = 0; n < 2; ++n) _Pragma("unroll") for (int k = 0; k < 2; ++k) \
;         acc[ai][bj][m][n] = __builtin_amdgcn_mfma_f32_16x16x32_bf16(Bt[n][k], At[m][k], acc[ai][bj][m][n], 0, 0, 0); __builtin_amdgcn_s_setprio(0); } while (0)
; #define PG8_WAIT_L(n) asm volatile("s_waitcnt lgkmcnt(" #n ")" ::: "memory")
; #define PG8_BAR __builtin_amdgcn_s_barrier()
; #define PG8_SCHED __builtin_amdgcn_sched_barrier(0)
;     ...
;             PG8_LDB(B0, 1, 0); PG8_SCHED; PG8_LDA(At, 1, 0); PG8_STAGE_A(PG8_SA(0, 1), a2, 1, r2);
;             PG8_WAIT_L(8); PG8_BAR; PG8_WAIT_L(0); PG8_MMA(0, 0, At, B0); PG8_BAR; PG8_SCHED;
;             PG8_LDB(B1, 1, 1); PG8_STAGE(PG8_SB(1, 0), b3, voffB);
;             PG8_BAR; PG8_WAIT_L(0); PG8_MMA(0, 1, At, B1); PG8_BAR;
;             PG8_LDA(At, 1, 1); PG8_STAGE_A(PG8_SA(1, 0), a3, 0, r3);
;             PG8_BAR; PG8_WAIT_L(0); PG8_MMA(1, 0, At, B0); PG8_BAR; PG8_SCHED;
	s_waitcnt lgkmcnt(0)
	s_setprio 1
	s_waitcnt lgkmcnt(0)
	v_mfma_f32_16x16x32_bf16 v[124:127], v[156:159], v[180:183], v[124:127]
	v_mfma_f32_16x16x32_bf16 v[120:123], v[172:175], v[180:183], v[120:123]
	v_mfma_f32_16x16x32_bf16 v[108:111], v[156:159], v[208:211], v[108:111]
	v_mfma_f32_16x16x32_bf16 v[104:107], v[172:175], v[208:211], v[104:107]
	v_mfma_f32_16x16x32_bf16 v[92:95], v[156:159], v[216:219], v[92:95]
	v_mfma_f32_16x16x32_bf16 v[88:91], v[172:175], v[216:219], v[88:91]
	v_mfma_f32_16x16x32_bf16 v[76:79], v[156:159], v[224:227], v[76:79]
	v_mfma_f32_16x16x32_bf16 v[72:75], v[172:175], v[224:227], v[72:75]
	v_mfma_f32_16x16x32_bf16 v[124:127], v[168:171], v[204:207], v[124:127]
	v_mfma_f32_16x16x32_bf16 v[120:123], v[176:179], v[204:207], v[120:123]
	v_mfma_f32_16x16x32_bf16 v[108:111], v[168:171], v[212:215], v[108:111]
	v_mfma_f32_16x16x32_bf16 v[104:107], v[176:179], v[212:215], v[104:107]
	v_mfma_f32_16x16x32_bf16 v[92:95], v[168:171], v[220:223], v[92:95]
	v_mfma_f32_16x16x32_bf16 v[88:91], v[176:179], v[220:223], v[88:91]
	v_mfma_f32_16x16x32_bf16 v[76:79], v[168:171], v[228:231], v[76:79]
	v_mfma_f32_16x16x32_bf16 v[72:75], v[176:179], v[228:231], v[72:75]
	s_setprio 0
	s_barrier
	s_add_i32 s11, 0, 0x1c000
	s_add_i32 s10, s10, s53
	v_add_u32_e32 v160, s11, v139
	v_lshl_add_u64 v[184:185], v[184:185], 0, s[28:29]
	s_mov_b32 m0, s10
	ds_read_b128 v[232:235], v160
	ds_read_b128 v[236:239], v160 offset:1024
	ds_read_b128 v[240:243], v160 offset:2048
	ds_read_b128 v[244:247], v160 offset:3072
	global_load_lds_dwordx4 v[184:185], off
	v_lshl_add_u64 v[184:185], v[248:249], 0, s[28:29]
	s_add_i32 m0, s10, 0x2000
	s_nop 0
	global_load_lds_dwordx4 v[184:185], off
	s_barrier
	s_waitcnt lgkmcnt(0)
	s_setprio 1
	s_waitcnt lgkmcnt(0)
	v_mfma_f32_16x16x32_bf16 v[116:119], v[232:235], v[180:183], v[116:119]
	v_mfma_f32_16x16x32_bf16 v[112:115], v[240:243], v[180:183], v[112:115]
	v_mfma_f32_16x16x32_bf16 v[100:103], v[232:235], v[208:211], v[100:103]
	v_mfma_f32_16x16x32_bf16 v[96:99], v[240:243], v[208:211], v[96:99]
	v_mfma_f32_16x16x32_bf16 v[84:87], v[232:235], v[216:219], v[84:87]
	v_mfma_f32_16x16x32_bf16 v[80:83], v[240:243], v[216:219], v[80:83]
	v_mfma_f32_16x16x32_bf16 v[68:71], v[232:235], v[224:227], v[68:71]
	v_mfma_f32_16x16x32_bf16 v[64:67], v[240:243], v[224:227], v[64:67]
	v_mfma_f32_16x16x32_bf16 v[116:119], v[236:239], v[204:207], v[116:119]
	v_mfma_f32_16x16x32_bf16 v[112:115], v[244:247], v[204:207], v[112:115]
	v_mfma_f32_16x16x32_bf16 v[100:103], v[236:239], v[212:215], v[100:103]
	v_mfma_f32_16x16x32_bf16 v[96:99], v[244:247], v[212:215], v[96:99]
	v_mfma_f32_16x16x32_bf16 v[84:87], v[236:239], v[220:223], v[84:87]
	v_mfma_f32_16x16x32_bf16 v[80:83], v[244:247], v[220:223], v[80:83]
	v_mfma_f32_16x16x32_bf16 v[68:71], v[236:239], v[228:231], v[68:71]
	v_mfma_f32_16x16x32_bf16 v[64:67], v[244:247], v[228:231], v[64:67]
	s_setprio 0
	s_mov_b32 m0, s70
	v_lshl_add_u64 v[184:185], s[14:15], 0, v[128:129]
	s_barrier
	ds_read_b128 v[180:183], v155 offset:49152
	ds_read_b128 v[204:207], v155 offset:50176
	ds_read_b128 v[208:211], v155 offset:51200
	ds_read_b128 v[212:215], v155 offset:52224
	ds_read_b128 v[216:219], v155 offset:53248
	ds_read_b128 v[220:223], v155 offset:54272
	ds_read_b128 v[224:227], v155 offset:55296
	ds_read_b128 v[228:231], v155 offset:56320
	global_load_lds_dwordx4 v[184:185], off
	v_lshl_add_u64 v[184:185], s[14:15], 0, v[132:133]
	s_mov_b32 m0, s71
	s_nop 0
	global_load_lds_dwordx4 v[184:185], off
	s_waitcnt vmcnt(10)
	s_barrier
; __device__ __forceinline__ unsigned cvt_pk_bf16(float lo, float hi) { unsigned r; asm volatile("v_cvt_pk_bf16_f32 %0, %1, %2" : "=v"(r) : "v"(lo), "v"(hi)); return r; }
; #define PG8_STAGE(bufoff, gbase, voff) do { _Pragma("unroll") for (int _i = 0; _i < 2; ++_i) \
;         __builtin_amdgcn_global_load_lds((const unsigned*)((const char*)(gbase) + (voff)[_i]), (LAS unsigned*)(lds + (bufoff) + ldsw + _i * 8192), 16, 0, 0); } while (0)
; #define PG8_WAIT_V(n) asm volatile("s_waitcnt vmcnt(" #n ")" ::: "memory")
; #define PG8_WAIT_L(n) asm volatile("s_waitcnt lgkmcnt(" #n ")" ::: "memory")
; #define PG8_BAR __builtin_amdgcn_s_barrier()
; #define PG8_SCHED __builtin_amdgcn_sched_barrier(0)
;     ...
;             PG8_BAR; PG8_WAIT_L(0); PG8_MMA(1, 0, At, B0); PG8_BAR; PG8_SCHED;
;             PG8_STAGE(PG8_SB(1, 1), b3 + hb2, voffB);
;             PG8_WAIT_V(6); PG8_BAR; PG8_MMA(1, 1, At, B1); PG8_BAR;
;         }
;     __device__ __forceinline__ void generic(const f32x4 (&acc)[2][2][4][2], const Unit& u, int wr, int wc, int fr, int fq) const {
;     ...
;                     if (MODE == 4) {
;                         if (u.pm < 8 && u.pn < 128) {
;                             if (bj == 0) {
;                                 const f32x4 a0 = acc[ai][0][m][0], a1 = acc[ai][0][m][1], b0 = acc[ai][1][m][0], b1 = acc[ai][1][m][1];
;                                 const f32x4 e0 = a0 + b0, e1 = a1 + b1, o0 = a0 - b0, o1 = a1 - b1;
;                                 bf16_t* p = O + (size_t)(u.pm * BM + rt) * T + (u.pn >> 4) * 4096 + (u.pn & 15) * 128 + wc * 32 + 8 * fq;
;                                 u32x4 w; w.x = cvt_pk_bf16(e0[0], e0[1]); w.y = cvt_pk_bf16(e0[2], e0[3]); w.z = cvt_pk_bf16(e1[0], e1[1]); w.w = cvt_pk_bf16(e1[2], e1[3]);
;                                 *(u32x4*)p = w;
;                                 w.x = cvt_pk_bf16(o0[0], o0[1]); w.y = cvt_pk_bf16(o0[2], o0[3]); w.z = cvt_pk_bf16(o1[0], o1[1]); w.w = cvt_pk_bf16(o1[2], o1[3]);
;                                 *(u32x4*)(p + 2048) = w;
;                             }
;                         } else {
;                             u32x4 w; w.x = cvt_pk_bf16(v0[0], v0[1]); w.y = cvt_pk_bf16(v0[2], v0[3]); w.z = cvt_pk_bf16(v1[0], v1[1]); w.w = cvt_pk_bf16(v1[2], v1[3]);
;                             *(u32x4*)(O + (size_t)(u.pm * BM + rt) * T + u.pn * BM + ct) = w;
	s_waitcnt lgkmcnt(0)
	s_setprio 1
	s_waitcnt lgkmcnt(0)
	v_mfma_f32_16x16x32_bf16 v[60:63], v[156:159], v[180:183], v[60:63]
	v_mfma_f32_16x16x32_bf16 v[56:59], v[172:175], v[180:183], v[56:59]
	v_mfma_f32_16x16x32_bf16 v[44:47], v[156:159], v[208:211], v[44:47]
	v_mfma_f32_16x16x32_bf16 v[40:43], v[172:175], v[208:211], v[40:43]
	v_mfma_f32_16x16x32_bf16 v[28:31], v[156:159], v[216:219], v[28:31]
	v_mfma_f32_16x16x32_bf16 v[24:27], v[172:175], v[216:219], v[24:27]
	v_mfma_f32_16x16x32_bf16 v[12:15], v[156:159], v[224:227], v[12:15]
	v_mfma_f32_16x16x32_bf16 v[8:11], v[172:175], v[224:227], v[8:11]
	v_mfma_f32_16x16x32_bf16 v[60:63], v[168:171], v[204:207], v[60:63]
	v_mfma_f32_16x16x32_bf16 v[56:59], v[176:179], v[204:207], v[56:59]
	v_mfma_f32_16x16x32_bf16 v[44:47], v[168:171], v[212:215], v[44:47]
	v_mfma_f32_16x16x32_bf16 v[40:43], v[176:179], v[212:215], v[40:43]
	v_mfma_f32_16x16x32_bf16 v[28:31], v[168:171], v[220:223], v[28:31]
	v_mfma_f32_16x16x32_bf16 v[24:27], v[176:179], v[220:223], v[24:27]
	v_mfma_f32_16x16x32_bf16 v[12:15], v[168:171], v[228:231], v[12:15]
	v_mfma_f32_16x16x32_bf16 v[8:11], v[176:179], v[228:231], v[8:11]
	s_setprio 0
	s_barrier
	s_add_i32 s10, s11, s53
	v_lshl_add_u64 v[156:157], v[250:251], 0, s[28:29]
	s_mov_b32 m0, s10
	s_nop 0
	global_load_lds_dwordx4 v[156:157], off
	v_lshl_add_u64 v[156:157], v[190:191], 0, s[28:29]
	s_add_i32 m0, s10, 0x2000
	s_nop 0
	global_load_lds_dwordx4 v[156:157], off
	v_add_u32_e32 v160, 0x10000, v139
	ds_read_b128 v[156:159], v160
	ds_read_b128 v[168:171], v160 offset:1024
	ds_read_b128 v[172:175], v160 offset:2048
	ds_read_b128 v[176:179], v160 offset:3072
	s_waitcnt vmcnt(6)
	s_barrier
	s_setprio 1
	v_mfma_f32_16x16x32_bf16 v[52:55], v[232:235], v[180:183], v[52:55]
	v_mfma_f32_16x16x32_bf16 v[48:51], v[240:243], v[180:183], v[48:51]
	v_mfma_f32_16x16x32_bf16 v[36:39], v[232:235], v[208:211], v[36:39]
	v_mfma_f32_16x16x32_bf16 v[32:35], v[240:243], v[208:211], v[32:35]
	v_mfma_f32_16x16x32_bf16 v[20:23], v[232:235], v[216:219], v[20:23]
	v_mfma_f32_16x16x32_bf16 v[16:19], v[240:243], v[216:219], v[16:19]
	v_mfma_f32_16x16x32_bf16 v[4:7], v[232:235], v[224:227], v[4:7]
	v_mfma_f32_16x16x32_bf16 v[0:3], v[240:243], v[224:227], v[0:3]
	v_mfma_f32_16x16x32_bf16 v[52:55], v[236:239], v[204:207], v[52:55]
	v_mfma_f32_16x16x32_bf16 v[48:51], v[244:247], v[204:207], v[48:51]
	v_mfma_f32_16x16x32_bf16 v[36:39], v[236:239], v[212:215], v[36:39]
	v_mfma_f32_16x16x32_bf16 v[32:35], v[244:247], v[212:215], v[32:35]
	v_mfma_f32_16x16x32_bf16 v[20:23], v[236:239], v[220:223], v[20:23]
	v_mfma_f32_16x16x32_bf16 v[16:19], v[244:247], v[220:223], v[16:19]
	v_mfma_f32_16x16x32_bf16 v[4:7], v[236:239], v[228:231], v[4:7]
	v_mfma_f32_16x16x32_bf16 v[0:3], v[244:247], v[228:231], v[0:3]
	s_setprio 0
	s_add_i32 s22, s22, 2
	s_add_u32 s0, s0, 0x100
	s_addc_u32 s1, s1, 0
	s_cmp_gt_u32 s22, 29
	s_barrier
	s_cbranch_scc0 .LBB0_522
	s_waitcnt lgkmcnt(0)
	s_cmp_gt_i32 s89, 7
	s_cselect_b64 s[0:1], -1, 0
	s_cmpk_gt_i32 s5, 0x7f
	s_cselect_b64 s[2:3], -1, 0
	s_or_b64 s[0:1], s[0:1], s[2:3]
	s_mov_b64 s[2:3], -1
	s_and_b64 vcc, exec, s[0:1]
	v_lshl_add_u32 v146, s89, 8, v137
	v_lshlrev_b32_e32 v144, 1, v138
	s_cbranch_vccz .LBB0_525
	v_mov_b64_e32 v[168:169], s[24:25]
	v_mad_i64_i32 v[168:169], s[2:3], v146, s80, v[168:169]
	s_lshl_b32 s2, s5, 8
	s_ashr_i32 s3, s2, 31
	v_lshl_add_u64 v[168:169], s[2:3], 1, v[168:169]
	v_mov_b32_e32 v145, v161
	v_lshl_add_u64 v[168:169], v[168:169], 0, v[144:145]
	v_cvt_pk_bf16_f32 v156, v124, v125
	v_cvt_pk_bf16_f32 v157, v126, v127
	v_cvt_pk_bf16_f32 v158, v120, v121
	v_cvt_pk_bf16_f32 v159, v122, v123
	global_store_dwordx4 v[168:169], v[156:159], off
	s_mov_b64 s[2:3], 0

; #define PG8_STAGE_A(bufoff, ptr, half, rev) do { if (REVA && (rev)) { const char* _p = (ptr) - ((half) ? hstepA : 0); PG8_STAGE(bufoff, _p, voffAr); } else { const char* _p = (ptr) + ((half) ? hstepA : 0); PG8_STAGE(bufoff, _p, voffA); } } while (0)
; #define PG8_LDA(dst, b, h) do { _Pragma("unroll") for (int m = 0; m < 4; ++m) _Pragma("unroll") for (int k = 0; k < 2; ++k) dst[m][k] = *(const LAS bf16x8*)(lds + PG8_SA(b, h) + aoff + m * 2048 + k * 1024); } while (0)
; #define PG8_LDB(dst, b, h) do { _Pragma("unroll") for (int n = 0; n < 2; ++n) _Pragma("unroll") for (int k = 0; k < 2; ++k) dst[n][k] = *(const LAS bf16x8*)(lds + PG8_SB(b, h) + boff + n * 2048 + k * 1024); } while (0)
; #define PG8_MMA(ai, bj, At, Bt) do { __builtin_amdgcn_s_setprio(1); _Pragma("unroll") for (int m = 0; m < 4; ++m) _Pragma("unroll") for (int n = 0; n < 2; ++n) _Pragma("unroll") for (int k = 0; k < 2; ++k) \
;         acc[ai][bj][m][n] = __builtin_amdgcn_mfma_f32_16x16x32_bf16(Bt[n][k], At[m][k], acc[ai][bj][m][n], 0, 0, 0); __builtin_amdgcn_s_setprio(0); } while (0)
; #define PG8_WAIT_L(n) asm volatile("s_waitcnt lgkmcnt(" #n ")" ::: "memory")
; #define PG8_BAR __builtin_amdgcn_s_barrier()
; #define PG8_SCHED __builtin_amdgcn_sched_barrier(0)
;     ...
;     for (;;) {
;         const bool has_next = next_unit(ui + 1, nM, nN, MP, nxt, rot);
;         const char* nA = has_next ? nxt.a : cA; const char* nB = has_next ? nxt.b : cB; const char* nAr = has_next ? nxt.ar : cAr; const size_t nHb = has_next ? nxt.hb : cHb;
;         for (int t = 0; t < nt; t += 2) {
;             const bool last = (t == nt - 2);
;             const char* a1 = PG8_APTR(cA, cAr, t + 1); const bool r1 = REVA && ((t + 1) & 4);
;             const char* a2 = last ? nA : PG8_APTR(cA, cAr, t + 2); const bool r2 = REVA && !last && ((t + 2) & 4);
;             const char* a3 = last ? nA + kstep : PG8_APTR(cA, cAr, t + 3); const bool r3 = REVA && !last && ((t + 3) & 4);
;             const char* b2 = last ? nB : cB + (size_t)(t + 2) * kstep; const char* b3 = b2 + kstep; const size_t hb2 = last ? nHb : cHb;
;             PG8_LDB(B0, 0, 0); PG8_SCHED; PG8_LDA(At, 0, 0); PG8_STAGE_A(PG8_SA(1, 1), a1, 1, r1);
;             PG8_WAIT_L(8); PG8_BAR; PG8_WAIT_L(0); PG8_MMA(0, 0, At, B0); PG8_BAR; PG8_SCHED;
.LBB0_566:
	s_add_u32 s25, s36, 0x80
	s_addc_u32 s27, s37, 0
	s_add_u32 s14, s38, 0x80080
	s_addc_u32 s15, s39, 0
	s_add_u32 s52, s0, 0x100
	v_mov_b32_e32 v0, 0
	v_lshl_add_u64 v[140:141], s[14:15], 0, v[136:137]
	v_lshl_add_u64 v[142:143], s[14:15], 0, v[138:139]
	s_addc_u32 s53, s1, 0
	s_mov_b32 s66, -2
	s_mov_b64 s[0:1], 0
	v_mov_b32_e32 v1, v0
	v_mov_b32_e32 v2, v0
	v_mov_b32_e32 v3, v0
	v_mov_b32_e32 v4, v0
	v_mov_b32_e32 v5, v0
	v_mov_b32_e32 v6, v0
	v_mov_b32_e32 v7, v0
	v_mov_b32_e32 v8, v0
	v_mov_b32_e32 v9, v0
	v_mov_b32_e32 v10, v0
	v_mov_b32_e32 v11, v0
	v_mov_b32_e32 v16, v0
	v_mov_b32_e32 v17, v0
	v_mov_b32_e32 v18, v0
	v_mov_b32_e32 v19, v0
	v_mov_b32_e32 v24, v0
	v_mov_b32_e32 v25, v0
	v_mov_b32_e32 v26, v0
	v_mov_b32_e32 v27, v0
	v_mov_b32_e32 v32, v0
	v_mov_b32_e32 v33, v0
	v_mov_b32_e32 v34, v0
	v_mov_b32_e32 v35, v0
	v_mov_b32_e32 v40, v0
	v_mov_b32_e32 v41, v0
	v_mov_b32_e32 v42, v0
	v_mov_b32_e32 v43, v0
	v_mov_b32_e32 v48, v0
	v_mov_b32_e32 v49, v0
	v_mov_b32_e32 v50, v0
	v_mov_b32_e32 v51, v0
	v_mov_b32_e32 v12, v0
	v_mov_b32_e32 v13, v0
	v_mov_b32_e32 v14, v0
	v_mov_b32_e32 v15, v0
	v_mov_b32_e32 v20, v0
	v_mov_b32_e32 v21, v0
	v_mov_b32_e32 v22, v0
	v_mov_b32_e32 v23, v0
	v_mov_b32_e32 v28, v0
	v_mov_b32_e32 v29, v0
	v_mov_b32_e32 v30, v0
	v_mov_b32_e32 v31, v0
	v_mov_b32_e32 v36, v0
	v_mov_b32_e32 v37, v0
	v_mov_b32_e32 v38, v0
	v_mov_b32_e32 v39, v0
	v_mov_b32_e32 v44, v0
	v_mov_b32_e32 v45, v0
	v_mov_b32_e32 v46, v0
	v_mov_b32_e32 v47, v0
	v_mov_b32_e32 v52, v0
	v_mov_b32_e32 v53, v0
	v_mov_b32_e32 v54, v0
	v_mov_b32_e32 v55, v0
	v_mov_b32_e32 v56, v0
	v_mov_b32_e32 v57, v0
	v_mov_b32_e32 v58, v0
	v_mov_b32_e32 v59, v0
	v_mov_b32_e32 v60, v0
	v_mov_b32_e32 v61, v0
	v_mov_b32_e32 v62, v0
	v_mov_b32_e32 v63, v0
	v_mov_b32_e32 v64, v0
	v_mov_b32_e32 v65, v0
	v_mov_b32_e32 v66, v0
	v_mov_b32_e32 v67, v0
	v_mov_b32_e32 v68, v0
	v_mov_b32_e32 v69, v0
	v_mov_b32_e32 v70, v0
	v_mov_b32_e32 v71, v0
	v_mov_b32_e32 v72, v0
	v_mov_b32_e32 v73, v0
	v_mov_b32_e32 v74, v0
	v_mov_b32_e32 v75, v0
	v_mov_b32_e32 v80, v0
	v_mov_b32_e32 v81, v0
	v_mov_b32_e32 v82, v0
	v_mov_b32_e32 v83, v0
	v_mov_b32_e32 v88, v0
	v_mov_b32_e32 v89, v0
	v_mov_b32_e32 v90, v0
	v_mov_b32_e32 v91, v0
	v_mov_b32_e32 v96, v0
	v_mov_b32_e32 v97, v0
	v_mov_b32_e32 v98, v0
	v_mov_b32_e32 v99, v0
	v_mov_b32_e32 v104, v0
	v_mov_b32_e32 v105, v0
	v_mov_b32_e32 v106, v0
	v_mov_b32_e32 v107, v0
	v_mov_b32_e32 v112, v0
	v_mov_b32_e32 v113, v0
	v_mov_b32_e32 v114, v0
	v_mov_b32_e32 v115, v0
	v_mov_b32_e32 v76, v0
	v_mov_b32_e32 v77, v0
	v_mov_b32_e32 v78, v0
	v_mov_b32_e32 v79, v0
	v_mov_b32_e32 v84, v0
	v_mov_b32_e32 v85, v0
	v_mov_b32_e32 v86, v0
	v_mov_b32_e32 v87, v0
	v_mov_b32_e32 v92, v0
	v_mov_b32_e32 v93, v0
	v_mov_b32_e32 v94, v0
	v_mov_b32_e32 v95, v0
	v_mov_b32_e32 v100, v0
	v_mov_b32_e32 v101, v0
	v_mov_b32_e32 v102, v0
	v_mov_b32_e32 v103, v0
	v_mov_b32_e32 v108, v0
	v_mov_b32_e32 v109, v0
	v_mov_b32_e32 v110, v0
	v_mov_b32_e32 v111, v0
	v_mov_b32_e32 v116, v0
	v_mov_b32_e32 v117, v0
	v_mov_b32_e32 v118, v0
	v_mov_b32_e32 v119, v0
	v_mov_b32_e32 v120, v0
	v_mov_b32_e32 v121, v0
	v_mov_b32_e32 v122, v0
	v_mov_b32_e32 v123, v0
	v_mov_b32_e32 v124, v0
	v_mov_b32_e32 v125, v0
	v_mov_b32_e32 v126, v0
	v_mov_b32_e32 v127, v0
	v_add_u32_e32 v158, 0x10000, v145
	ds_read_b128 v[150:153], v158
	ds_read_b128 v[154:157], v158 offset:1024
	ds_read_b128 v[168:171], v158 offset:2048
	ds_read_b128 v[172:175], v158 offset:3072
.LBB0_567:
	s_add_u32 s10, s38, s0
	s_addc_u32 s11, s39, s1
	s_add_u32 s16, s10, 0x100
	s_addc_u32 s17, s11, 0
	s_add_u32 s10, s10, 0x180
	s_addc_u32 s11, s11, 0
	s_add_u32 s14, s52, s0
	s_addc_u32 s15, s53, s1
	s_add_i32 s67, 0, 0x10000
	s_cmpk_eq_i32 s0, 0xf00
	s_cselect_b32 s15, s45, s15
	s_cselect_b32 s14, s44, s14
	s_cselect_b32 s21, s37, s17
	s_cselect_b32 s20, s36, s16
	s_cselect_b32 s17, s27, s11
	s_cselect_b32 s16, s25, s10
	v_lshl_add_u64 v[158:159], v[140:141], 0, s[0:1]
	s_add_i32 m0, s22, 0xc000
	ds_read_b128 v[176:179], v149
	ds_read_b128 v[180:183], v149 offset:1024
	ds_read_b128 v[204:207], v149 offset:2048
	ds_read_b128 v[208:211], v149 offset:3072
	ds_read_b128 v[212:215], v149 offset:4096
	ds_read_b128 v[216:219], v149 offset:5120
	ds_read_b128 v[220:223], v149 offset:6144
	ds_read_b128 v[224:227], v149 offset:7168
	global_load_lds_dwordx4 v[158:159], off
	v_lshl_add_u64 v[158:159], v[142:143], 0, s[0:1]
	s_add_i32 m0, s22, 0xe000
	s_nop 0
	global_load_lds_dwordx4 v[158:159], off
	s_waitcnt lgkmcnt(8)
	s_barrier
	s_waitcnt lgkmcnt(0)
	s_setprio 1
	s_waitcnt lgkmcnt(0)
	v_mfma_f32_16x16x32_bf16 v[124:127], v[150:153], v[176:179], v[124:127]
	v_mfma_f32_16x16x32_bf16 v[120:123], v[168:171], v[176:179], v[120:123]
	v_mfma_f32_16x16x32_bf16 v[116:119], v[150:153], v[204:207], v[116:119]
	v_mfma_f32_16x16x32_bf16 v[108:111], v[168:171], v[204:207], v[108:111]
	v_mfma_f32_16x16x32_bf16 v[100:103], v[150:153], v[212:215], v[100:103]
	v_mfma_f32_16x16x32_bf16 v[92:95], v[168:171], v[212:215], v[92:95]
	v_mfma_f32_16x16x32_bf16 v[84:87], v[150:153], v[220:223], v[84:87]
	v_mfma_f32_16x16x32_bf16 v[76:79], v[168:171], v[220:223], v[76:79]
	v_mfma_f32_16x16x32_bf16 v[124:127], v[154:157], v[180:183], v[124:127]
	v_mfma_f32_16x16x32_bf16 v[120:123], v[172:175], v[180:183], v[120:123]
	v_mfma_f32_16x16x32_bf16 v[116:119], v[154:157], v[208:211], v[116:119]
	v_mfma_f32_16x16x32_bf16 v[108:111], v[172:175], v[208:211], v[108:111]
	v_mfma_f32_16x16x32_bf16 v[100:103], v[154:157], v[216:219], v[100:103]
	v_mfma_f32_16x16x32_bf16 v[92:95], v[172:175], v[216:219], v[92:95]
	v_mfma_f32_16x16x32_bf16 v[84:87], v[154:157], v[224:227], v[84:87]
	v_mfma_f32_16x16x32_bf16 v[76:79], v[172:175], v[224:227], v[76:79]
	s_setprio 0
	s_barrier
; #define PG8_STAGE(bufoff, gbase, voff) do { _Pragma("unroll") for (int _i = 0; _i < 2; ++_i) \
;         __builtin_amdgcn_global_load_lds((const unsigned*)((const char*)(gbase) + (voff)[_i]), (LAS unsigned*)(lds + (bufoff) + ldsw + _i * 8192), 16, 0, 0); } while (0)
; #define PG8_STAGE_A(bufoff, ptr, half, rev) do { if (REVA && (rev)) { const char* _p = (ptr) - ((half) ? hstepA : 0); PG8_STAGE(bufoff, _p, voffAr); } else { const char* _p = (ptr) + ((half) ? hstepA : 0); PG8_STAGE(bufoff, _p, voffA); } } while (0)
; #define PG8_LDA(dst, b, h) do { _Pragma("unroll") for (int m = 0; m < 4; ++m) _Pragma("unroll") for (int k = 0; k < 2; ++k) dst[m][k] = *(const LAS bf16x8*)(lds + PG8_SA(b, h) + aoff + m * 2048 + k * 1024); } while (0)
; #define PG8_LDB(dst, b, h) do { _Pragma("unroll") for (int n = 0; n < 2; ++n) _Pragma("unroll") for (int k = 0; k < 2; ++k) dst[n][k] = *(const LAS bf16x8*)(lds + PG8_SB(b, h) + boff + n * 2048 + k * 1024); } while (0)
; #define PG8_MMA(ai, bj, At, Bt) do { __builtin_amdgcn_s_setprio(1); _Pragma("unroll") for (int m = 0; m < 4; ++m) _Pragma("unroll") for (int n = 0; n < 2; ++n) _Pragma("unroll") for (int k = 0; k < 2; ++k) \
;         acc[ai][bj][m][n] = __builtin_amdgcn_mfma_f32_16x16x32_bf16(Bt[n][k], At[m][k], acc[ai][bj][m][n], 0, 0, 0); __builtin_amdgcn_s_setprio(0); } while (0)
; #define PG8_WAIT_V(n) asm volatile("s_waitcnt vmcnt(" #n ")" ::: "memory")
; #define PG8_WAIT_L(n) asm volatile("s_waitcnt lgkmcnt(" #n ")" ::: "memory")
; #define PG8_BAR __builtin_amdgcn_s_barrier()
; #define PG8_SCHED __builtin_amdgcn_sched_barrier(0)
;     ...
;             PG8_LDB(B1, 0, 1); PG8_STAGE(PG8_SB(0, 0), b2, voffB);
;             PG8_BAR; PG8_WAIT_L(0); PG8_MMA(0, 1, At, B1); PG8_BAR;
;             PG8_LDA(At, 0, 1); PG8_STAGE_A(PG8_SA(0, 0), a2, 0, r2);
;             PG8_BAR; PG8_WAIT_L(0); PG8_MMA(1, 0, At, B0); PG8_BAR; PG8_SCHED;
;             PG8_STAGE(PG8_SB(0, 1), b2 + hb2, voffB);
;             PG8_WAIT_V(6); PG8_BAR; PG8_MMA(1, 1, At, B1); PG8_BAR;
;             PG8_LDB(B0, 1, 0); PG8_SCHED; PG8_LDA(At, 1, 0); PG8_STAGE_A(PG8_SA(0, 1), a2, 1, r2);
	s_add_i32 s10, 0, 0x14000
	v_add_u32_e32 v158, s10, v145
	s_add_i32 s11, s67, s5
	ds_read_b128 v[228:231], v158
	ds_read_b128 v[232:235], v158 offset:1024
	ds_read_b128 v[236:239], v158 offset:2048
	ds_read_b128 v[240:243], v158 offset:3072
	v_lshl_add_u64 v[158:159], s[14:15], 0, v[132:133]
	s_mov_b32 m0, s11
	v_lshl_add_u64 v[184:185], s[14:15], 0, v[128:129]
	global_load_lds_dwordx4 v[158:159], off
	s_add_i32 m0, s11, 0x2000
	s_nop 0
	global_load_lds_dwordx4 v[184:185], off
	s_barrier
	s_waitcnt lgkmcnt(0)
	s_setprio 1
	s_waitcnt lgkmcnt(0)
	v_mfma_f32_16x16x32_bf16 v[112:115], v[228:231], v[176:179], v[112:115]
	v_mfma_f32_16x16x32_bf16 v[104:107], v[236:239], v[176:179], v[104:107]
	v_mfma_f32_16x16x32_bf16 v[96:99], v[228:231], v[204:207], v[96:99]
	v_mfma_f32_16x16x32_bf16 v[88:91], v[236:239], v[204:207], v[88:91]
	v_mfma_f32_16x16x32_bf16 v[80:83], v[228:231], v[212:215], v[80:83]
	v_mfma_f32_16x16x32_bf16 v[72:75], v[236:239], v[212:215], v[72:75]
	v_mfma_f32_16x16x32_bf16 v[68:71], v[228:231], v[220:223], v[68:71]
	v_mfma_f32_16x16x32_bf16 v[64:67], v[236:239], v[220:223], v[64:67]
	v_mfma_f32_16x16x32_bf16 v[112:115], v[232:235], v[180:183], v[112:115]
	v_mfma_f32_16x16x32_bf16 v[104:107], v[240:243], v[180:183], v[104:107]
	v_mfma_f32_16x16x32_bf16 v[96:99], v[232:235], v[208:211], v[96:99]
	v_mfma_f32_16x16x32_bf16 v[88:91], v[240:243], v[208:211], v[88:91]
	v_mfma_f32_16x16x32_bf16 v[80:83], v[232:235], v[216:219], v[80:83]
	v_mfma_f32_16x16x32_bf16 v[72:75], v[240:243], v[216:219], v[72:75]
	v_mfma_f32_16x16x32_bf16 v[68:71], v[232:235], v[224:227], v[68:71]
	v_mfma_f32_16x16x32_bf16 v[64:67], v[240:243], v[224:227], v[64:67]
	s_setprio 0
	s_mov_b32 m0, s22
	v_lshl_add_u64 v[190:191], s[20:21], 0, v[134:135]
	s_barrier
	ds_read_b128 v[176:179], v149 offset:16384
	ds_read_b128 v[180:183], v149 offset:17408
	ds_read_b128 v[204:207], v149 offset:18432
	ds_read_b128 v[208:211], v149 offset:19456
	ds_read_b128 v[212:215], v149 offset:20480
	ds_read_b128 v[216:219], v149 offset:21504
	ds_read_b128 v[220:223], v149 offset:22528
	ds_read_b128 v[224:227], v149 offset:23552
	global_load_lds_dwordx4 v[190:191], off
	v_lshl_add_u64 v[190:191], s[20:21], 0, v[130:131]
	s_mov_b32 m0, s46
	s_nop 0
	global_load_lds_dwordx4 v[190:191], off
	s_waitcnt vmcnt(10)
	s_barrier
	s_waitcnt lgkmcnt(0)
	s_setprio 1
	s_waitcnt lgkmcnt(0)
	v_mfma_f32_16x16x32_bf16 v[60:63], v[150:153], v[176:179], v[60:63]
	v_mfma_f32_16x16x32_bf16 v[56:59], v[168:171], v[176:179], v[56:59]
	v_mfma_f32_16x16x32_bf16 v[52:55], v[150:153], v[204:207], v[52:55]
	v_mfma_f32_16x16x32_bf16 v[44:47], v[168:171], v[204:207], v[44:47]
	v_mfma_f32_16x16x32_bf16 v[36:39], v[150:153], v[212:215], v[36:39]
	v_mfma_f32_16x16x32_bf16 v[28:31], v[168:171], v[212:215], v[28:31]
	v_mfma_f32_16x16x32_bf16 v[20:23], v[150:153], v[220:223], v[20:23]
	v_mfma_f32_16x16x32_bf16 v[12:15], v[168:171], v[220:223], v[12:15]
	v_mfma_f32_16x16x32_bf16 v[60:63], v[154:157], v[180:183], v[60:63]
	v_mfma_f32_16x16x32_bf16 v[56:59], v[172:175], v[180:183], v[56:59]
	v_mfma_f32_16x16x32_bf16 v[52:55], v[154:157], v[208:211], v[52:55]
	v_mfma_f32_16x16x32_bf16 v[44:47], v[172:175], v[208:211], v[44:47]
	v_mfma_f32_16x16x32_bf16 v[36:39], v[154:157], v[216:219], v[36:39]
	v_mfma_f32_16x16x32_bf16 v[28:31], v[172:175], v[216:219], v[28:31]
	v_mfma_f32_16x16x32_bf16 v[20:23], v[154:157], v[224:227], v[20:23]
	v_mfma_f32_16x16x32_bf16 v[12:15], v[172:175], v[224:227], v[12:15]
	s_setprio 0
	s_barrier
	s_add_u32 s68, s14, 0x80000
	s_addc_u32 s69, s15, 0
	s_add_i32 s10, s10, s5
	v_lshl_add_u64 v[150:151], s[68:69], 0, v[132:133]
	s_mov_b32 m0, s10
	s_nop 0
	global_load_lds_dwordx4 v[150:151], off
	v_lshl_add_u64 v[150:151], s[68:69], 0, v[128:129]
	s_add_i32 m0, s10, 0x2000
	s_nop 0
	global_load_lds_dwordx4 v[150:151], off
	v_add_u32_e32 v172, 0x18000, v145
	ds_read_b128 v[150:153], v172
	ds_read_b128 v[154:157], v172 offset:1024
	ds_read_b128 v[168:171], v172 offset:2048
	ds_read_b128 v[172:175], v172 offset:3072
	s_waitcnt vmcnt(6)
	s_barrier
	s_setprio 1
	v_mfma_f32_16x16x32_bf16 v[48:51], v[228:231], v[176:179], v[48:51]
	v_mfma_f32_16x16x32_bf16 v[40:43], v[236:239], v[176:179], v[40:43]
	v_mfma_f32_16x16x32_bf16 v[32:35], v[228:231], v[204:207], v[32:35]
	v_mfma_f32_16x16x32_bf16 v[24:27], v[236:239], v[204:207], v[24:27]
	v_mfma_f32_16x16x32_bf16 v[16:19], v[228:231], v[212:215], v[16:19]
	v_mfma_f32_16x16x32_bf16 v[8:11], v[236:239], v[212:215], v[8:11]
	v_mfma_f32_16x16x32_bf16 v[4:7], v[228:231], v[220:223], v[4:7]
	v_mfma_f32_16x16x32_bf16 v[0:3], v[236:239], v[220:223], v[0:3]
	v_mfma_f32_16x16x32_bf16 v[48:51], v[232:235], v[180:183], v[48:51]
	v_mfma_f32_16x16x32_bf16 v[40:43], v[240:243], v[180:183], v[40:43]
	v_mfma_f32_16x16x32_bf16 v[32:35], v[232:235], v[208:211], v[32:35]
	v_mfma_f32_16x16x32_bf16 v[24:27], v[240:243], v[208:211], v[24:27]
	v_mfma_f32_16x16x32_bf16 v[16:19], v[232:235], v[216:219], v[16:19]
	v_mfma_f32_16x16x32_bf16 v[8:11], v[240:243], v[216:219], v[8:11]
	v_mfma_f32_16x16x32_bf16 v[4:7], v[232:235], v[224:227], v[4:7]
	v_mfma_f32_16x16x32_bf16 v[0:3], v[240:243], v[224:227], v[0:3]
	s_setprio 0
	s_add_i32 s10, 0, 0x18000
	s_barrier
	s_add_u32 s20, s20, 0x80000
	s_addc_u32 s21, s21, 0
	s_mov_b32 m0, s47
	v_lshl_add_u64 v[190:191], s[20:21], 0, v[134:135]
	ds_read_b128 v[176:179], v149 offset:32768
	ds_read_b128 v[180:183], v149 offset:33792
	ds_read_b128 v[204:207], v149 offset:34816
	ds_read_b128 v[208:211], v149 offset:35840
	ds_read_b128 v[212:215], v149 offset:36864
	ds_read_b128 v[216:219], v149 offset:37888
	ds_read_b128 v[220:223], v149 offset:38912
	ds_read_b128 v[224:227], v149 offset:39936
	global_load_lds_dwordx4 v[190:191], off
	v_lshl_add_u64 v[190:191], s[20:21], 0, v[130:131]
	s_mov_b32 m0, s50
	s_nop 0
	global_load_lds_dwordx4 v[190:191], off
	s_waitcnt lgkmcnt(8)
	s_barrier
; #define PG8_STAGE(bufoff, gbase, voff) do { _Pragma("unroll") for (int _i = 0; _i < 2; ++_i) \
;         __builtin_amdgcn_global_load_lds((const unsigned*)((const char*)(gbase) + (voff)[_i]), (LAS unsigned*)(lds + (bufoff) + ldsw + _i * 8192), 16, 0, 0); } while (0)
; #define PG8_STAGE_A(bufoff, ptr, half, rev) do { if (REVA && (rev)) { const char* _p = (ptr) - ((half) ? hstepA : 0); PG8_STAGE(bufoff, _p, voffAr); } else { const char* _p = (ptr) + ((half) ? hstepA : 0); PG8_STAGE(bufoff, _p, voffA); } } while (0)
; #define PG8_LDA(dst, b, h) do { _Pragma("unroll") for (int m = 0; m < 4; ++m) _Pragma("unroll") for (int k = 0; k < 2; ++k) dst[m][k] = *(const LAS bf16x8*)(lds + PG8_SA(b, h) + aoff + m * 2048 + k * 1024); } while (0)
; #define PG8_LDB(dst, b, h) do { _Pragma("unroll") for (int n = 0; n < 2; ++n) _Pragma("unroll") for (int k = 0; k < 2; ++k) dst[n][k] = *(const LAS bf16x8*)(lds + PG8_SB(b, h) + boff + n * 2048 + k * 1024); } while (0)
; #define PG8_MMA(ai, bj, At, Bt) do { __builtin_amdgcn_s_setprio(1); _Pragma("unroll") for (int m = 0; m < 4; ++m) _Pragma("unroll") for (int n = 0; n < 2; ++n) _Pragma("unroll") for (int k = 0; k < 2; ++k) \
;         acc[ai][bj][m][n] = __builtin_amdgcn_mfma_f32_16x16x32_bf16(Bt[n][k], At[m][k], acc[ai][bj][m][n], 0, 0, 0); __builtin_amdgcn_s_setprio(0); } while (0)
; #define PG8_WAIT_V(n) asm volatile("s_waitcnt vmcnt(" #n ")" ::: "memory")
; #define PG8_WAIT_L(n) asm volatile("s_waitcnt lgkmcnt(" #n ")" ::: "memory")
; #define PG8_BAR __builtin_amdgcn_s_barrier()
; #define PG8_SCHED __builtin_amdgcn_sched_barrier(0)
;     ...
;             PG8_LDB(B0, 1, 0); PG8_SCHED; PG8_LDA(At, 1, 0); PG8_STAGE_A(PG8_SA(0, 1), a2, 1, r2);
;             PG8_WAIT_L(8); PG8_BAR; PG8_WAIT_L(0); PG8_MMA(0, 0, At, B0); PG8_BAR; PG8_SCHED;
;             PG8_LDB(B1, 1, 1); PG8_STAGE(PG8_SB(1, 0), b3, voffB);
;             PG8_BAR; PG8_WAIT_L(0); PG8_MMA(0, 1, At, B1); PG8_BAR;
;             PG8_LDA(At, 1, 1); PG8_STAGE_A(PG8_SA(1, 0), a3, 0, r3);
;             PG8_BAR; PG8_WAIT_L(0); PG8_MMA(1, 0, At, B0); PG8_BAR; PG8_SCHED;
;             PG8_STAGE(PG8_SB(1, 1), b3 + hb2, voffB);
;             PG8_WAIT_V(6); PG8_BAR; PG8_MMA(1, 1, At, B1); PG8_BAR;
	s_waitcnt lgkmcnt(0)
	s_setprio 1
	s_waitcnt lgkmcnt(0)
	v_mfma_f32_16x16x32_bf16 v[124:127], v[150:153], v[176:179], v[124:127]
	v_mfma_f32_16x16x32_bf16 v[120:123], v[168:171], v[176:179], v[120:123]
	v_mfma_f32_16x16x32_bf16 v[116:119], v[150:153], v[204:207], v[116:119]
	v_mfma_f32_16x16x32_bf16 v[108:111], v[168:171], v[204:207], v[108:111]
	v_mfma_f32_16x16x32_bf16 v[100:103], v[150:153], v[212:215], v[100:103]
	v_mfma_f32_16x16x32_bf16 v[92:95], v[168:171], v[212:215], v[92:95]
	v_mfma_f32_16x16x32_bf16 v[84:87], v[150:153], v[220:223], v[84:87]
	v_mfma_f32_16x16x32_bf16 v[76:79], v[168:171], v[220:223], v[76:79]
	v_mfma_f32_16x16x32_bf16 v[124:127], v[154:157], v[180:183], v[124:127]
	v_mfma_f32_16x16x32_bf16 v[120:123], v[172:175], v[180:183], v[120:123]
	v_mfma_f32_16x16x32_bf16 v[116:119], v[154:157], v[208:211], v[116:119]
	v_mfma_f32_16x16x32_bf16 v[108:111], v[172:175], v[208:211], v[108:111]
	v_mfma_f32_16x16x32_bf16 v[100:103], v[154:157], v[216:219], v[100:103]
	v_mfma_f32_16x16x32_bf16 v[92:95], v[172:175], v[216:219], v[92:95]
	v_mfma_f32_16x16x32_bf16 v[84:87], v[154:157], v[224:227], v[84:87]
	v_mfma_f32_16x16x32_bf16 v[76:79], v[172:175], v[224:227], v[76:79]
	s_setprio 0
	s_barrier
	s_add_i32 s11, 0, 0x1c000
	s_add_i32 s10, s10, s5
	v_add_u32_e32 v190, s11, v145
	v_lshl_add_u64 v[158:159], v[158:159], 0, s[28:29]
	s_mov_b32 m0, s10
	ds_read_b128 v[228:231], v190
	ds_read_b128 v[232:235], v190 offset:1024
	ds_read_b128 v[236:239], v190 offset:2048
	ds_read_b128 v[240:243], v190 offset:3072
	global_load_lds_dwordx4 v[158:159], off
	v_lshl_add_u64 v[158:159], v[184:185], 0, s[28:29]
	s_add_i32 m0, s10, 0x2000
	s_nop 0
	global_load_lds_dwordx4 v[158:159], off
	s_barrier
	s_waitcnt lgkmcnt(0)
	s_setprio 1
	s_waitcnt lgkmcnt(0)
	v_mfma_f32_16x16x32_bf16 v[112:115], v[228:231], v[176:179], v[112:115]
	v_mfma_f32_16x16x32_bf16 v[104:107], v[236:239], v[176:179], v[104:107]
	v_mfma_f32_16x16x32_bf16 v[96:99], v[228:231], v[204:207], v[96:99]
	v_mfma_f32_16x16x32_bf16 v[88:91], v[236:239], v[204:207], v[88:91]
	v_mfma_f32_16x16x32_bf16 v[80:83], v[228:231], v[212:215], v[80:83]
	v_mfma_f32_16x16x32_bf16 v[72:75], v[236:239], v[212:215], v[72:75]
	v_mfma_f32_16x16x32_bf16 v[68:71], v[228:231], v[220:223], v[68:71]
	v_mfma_f32_16x16x32_bf16 v[64:67], v[236:239], v[220:223], v[64:67]
	v_mfma_f32_16x16x32_bf16 v[112:115], v[232:235], v[180:183], v[112:115]
	v_mfma_f32_16x16x32_bf16 v[104:107], v[240:243], v[180:183], v[104:107]
	v_mfma_f32_16x16x32_bf16 v[96:99], v[232:235], v[208:211], v[96:99]
	v_mfma_f32_16x16x32_bf16 v[88:91], v[240:243], v[208:211], v[88:91]
	v_mfma_f32_16x16x32_bf16 v[80:83], v[232:235], v[216:219], v[80:83]
	v_mfma_f32_16x16x32_bf16 v[72:75], v[240:243], v[216:219], v[72:75]
	v_mfma_f32_16x16x32_bf16 v[68:71], v[232:235], v[224:227], v[68:71]
	v_mfma_f32_16x16x32_bf16 v[64:67], v[240:243], v[224:227], v[64:67]
	s_setprio 0
	s_mov_b32 m0, s48
	v_lshl_add_u64 v[158:159], s[16:17], 0, v[134:135]
	s_barrier
	ds_read_b128 v[176:179], v149 offset:49152
	ds_read_b128 v[180:183], v149 offset:50176
	ds_read_b128 v[204:207], v149 offset:51200
	ds_read_b128 v[208:211], v149 offset:52224
	ds_read_b128 v[212:215], v149 offset:53248
	ds_read_b128 v[216:219], v149 offset:54272
	ds_read_b128 v[220:223], v149 offset:55296
	ds_read_b128 v[224:227], v149 offset:56320
	global_load_lds_dwordx4 v[158:159], off
	v_lshl_add_u64 v[158:159], s[16:17], 0, v[130:131]
	s_mov_b32 m0, s49
	s_nop 0
	global_load_lds_dwordx4 v[158:159], off
	s_waitcnt vmcnt(10)
	s_barrier
	s_waitcnt lgkmcnt(0)
	s_setprio 1
	s_waitcnt lgkmcnt(0)
	v_mfma_f32_16x16x32_bf16 v[60:63], v[150:153], v[176:179], v[60:63]
	v_mfma_f32_16x16x32_bf16 v[56:59], v[168:171], v[176:179], v[56:59]
	v_mfma_f32_16x16x32_bf16 v[52:55], v[150:153], v[204:207], v[52:55]
	v_mfma_f32_16x16x32_bf16 v[44:47], v[168:171], v[204:207], v[44:47]
	v_mfma_f32_16x16x32_bf16 v[36:39], v[150:153], v[212:215], v[36:39]
	v_mfma_f32_16x16x32_bf16 v[28:31], v[168:171], v[212:215], v[28:31]
	v_mfma_f32_16x16x32_bf16 v[20:23], v[150:153], v[220:223], v[20:23]
	v_mfma_f32_16x16x32_bf16 v[12:15], v[168:171], v[220:223], v[12:15]
	v_mfma_f32_16x16x32_bf16 v[60:63], v[154:157], v[180:183], v[60:63]
	v_mfma_f32_16x16x32_bf16 v[56:59], v[172:175], v[180:183], v[56:59]
	v_mfma_f32_16x16x32_bf16 v[52:55], v[154:157], v[208:211], v[52:55]
	v_mfma_f32_16x16x32_bf16 v[44:47], v[172:175], v[208:211], v[44:47]
	v_mfma_f32_16x16x32_bf16 v[36:39], v[154:157], v[216:219], v[36:39]
	v_mfma_f32_16x16x32_bf16 v[28:31], v[172:175], v[216:219], v[28:31]
	v_mfma_f32_16x16x32_bf16 v[20:23], v[154:157], v[224:227], v[20:23]
	v_mfma_f32_16x16x32_bf16 v[12:15], v[172:175], v[224:227], v[12:15]
	s_setprio 0
	s_barrier
	s_add_u32 s14, s14, 0x80080
	s_addc_u32 s15, s15, 0
	s_add_i32 s10, s11, s5
	v_lshl_add_u64 v[150:151], s[14:15], 0, v[132:133]
	s_mov_b32 m0, s10
	s_nop 0
	global_load_lds_dwordx4 v[150:151], off
	v_lshl_add_u64 v[150:151], s[14:15], 0, v[128:129]
	s_add_i32 m0, s10, 0x2000
	s_nop 0
	global_load_lds_dwordx4 v[150:151], off
	v_add_u32_e32 v158, 0x10000, v145
	ds_read_b128 v[150:153], v158
	ds_read_b128 v[154:157], v158 offset:1024
	ds_read_b128 v[168:171], v158 offset:2048
	ds_read_b128 v[172:175], v158 offset:3072
	s_waitcnt vmcnt(6)
	s_barrier
; __device__ __forceinline__ unsigned cvt_pk_bf16(float lo, float hi) { unsigned r; asm volatile("v_cvt_pk_bf16_f32 %0, %1, %2" : "=v"(r) : "v"(lo), "v"(hi)); return r; }
; #define PG8_WAIT_V(n) asm volatile("s_waitcnt vmcnt(" #n ")" ::: "memory")
; #define PG8_BAR __builtin_amdgcn_s_barrier()
;     ...
;     PG8_WAIT_V(0);
;     if (wr == 0) PG8_BAR;
;     PG8_BAR;
;     __device__ __forceinline__ void generic(const f32x4 (&acc)[2][2][4][2], const Unit& u, int wr, int wc, int fr, int fq) const {
;     ...
;                     } else if (MODE == 0) {
;                         u32x4 w; w.x = cvt_pk_bf16(v0[0], v0[1]); w.y = cvt_pk_bf16(v0[2], v0[3]); w.z = cvt_pk_bf16(v1[0], v1[1]); w.w = cvt_pk_bf16(v1[2], v1[3]);
;                         *(u32x4*)(O + (size_t)(u.pm * BM + rt) * ldc + u.pn * BM + ct) = w;
	s_setprio 1
	v_mfma_f32_16x16x32_bf16 v[48:51], v[228:231], v[176:179], v[48:51]
	v_mfma_f32_16x16x32_bf16 v[40:43], v[236:239], v[176:179], v[40:43]
	v_mfma_f32_16x16x32_bf16 v[32:35], v[228:231], v[204:207], v[32:35]
	v_mfma_f32_16x16x32_bf16 v[24:27], v[236:239], v[204:207], v[24:27]
	v_mfma_f32_16x16x32_bf16 v[16:19], v[228:231], v[212:215], v[16:19]
	v_mfma_f32_16x16x32_bf16 v[8:11], v[236:239], v[212:215], v[8:11]
	v_mfma_f32_16x16x32_bf16 v[4:7], v[228:231], v[220:223], v[4:7]
	v_mfma_f32_16x16x32_bf16 v[0:3], v[236:239], v[220:223], v[0:3]
	v_mfma_f32_16x16x32_bf16 v[48:51], v[232:235], v[180:183], v[48:51]
	v_mfma_f32_16x16x32_bf16 v[40:43], v[240:243], v[180:183], v[40:43]
	v_mfma_f32_16x16x32_bf16 v[32:35], v[232:235], v[208:211], v[32:35]
	v_mfma_f32_16x16x32_bf16 v[24:27], v[240:243], v[208:211], v[24:27]
	v_mfma_f32_16x16x32_bf16 v[16:19], v[232:235], v[216:219], v[16:19]
	v_mfma_f32_16x16x32_bf16 v[8:11], v[240:243], v[216:219], v[8:11]
	v_mfma_f32_16x16x32_bf16 v[4:7], v[232:235], v[224:227], v[4:7]
	v_mfma_f32_16x16x32_bf16 v[0:3], v[240:243], v[224:227], v[0:3]
	s_setprio 0
	s_add_i32 s66, s66, 2
	s_add_u32 s0, s0, 0x100
	s_addc_u32 s1, s1, 0
	s_cmp_gt_u32 s66, 29
	s_barrier
	s_cbranch_scc0 .LBB0_567
	s_waitcnt lgkmcnt(0)
	s_lshl_b32 s9, s9, 8
	v_cvt_pk_bf16_f32 v124, v124, v125
	v_cvt_pk_bf16_f32 v125, v126, v127
	v_cvt_pk_bf16_f32 v126, v120, v121
	v_add_u32_e32 v120, s9, v144
	v_ashrrev_i32_e32 v121, 31, v120
	s_lshl_b32 s0, s8, 8
	v_cvt_pk_bf16_f32 v127, v122, v123
	v_lshlrev_b64 v[122:123], 12, v[120:121]
	s_ashr_i32 s1, s0, 31
	v_lshl_add_u64 v[122:123], s[2:3], 0, v[122:123]
	s_lshl_b64 s[0:1], s[0:1], 1
	v_lshl_add_u64 v[122:123], v[122:123], 0, s[0:1]
	v_lshl_add_u64 v[122:123], v[122:123], 0, v[160:161]
	global_store_dwordx4 v[122:123], v[124:127], off
	v_cvt_pk_bf16_f32 v112, v112, v113
	v_cvt_pk_bf16_f32 v113, v114, v115
	v_cvt_pk_bf16_f32 v114, v104, v105
	v_cvt_pk_bf16_f32 v115, v106, v107
	global_store_dwordx4 v[122:123], v[112:115], off offset:256
	v_cvt_pk_bf16_f32 v104, v116, v117
	v_cvt_pk_bf16_f32 v105, v118, v119
	v_cvt_pk_bf16_f32 v106, v108, v109
	v_add_u32_e32 v108, s9, v146
	v_ashrrev_i32_e32 v109, 31, v108
	v_lshlrev_b64 v[108:109], 12, v[108:109]
	v_lshl_add_u64 v[108:109], s[2:3], 0, v[108:109]
	v_lshl_add_u64 v[108:109], v[108:109], 0, s[0:1]
	v_lshl_add_u64 v[108:109], v[108:109], 0, v[160:161]
	v_cvt_pk_bf16_f32 v107, v110, v111
	global_store_dwordx4 v[108:109], v[104:107], off
	v_cvt_pk_bf16_f32 v96, v96, v97
	v_cvt_pk_bf16_f32 v97, v98, v99
	v_cvt_pk_bf16_f32 v98, v88, v89
	v_cvt_pk_bf16_f32 v99, v90, v91
	global_store_dwordx4 v[108:109], v[96:99], off offset:256
	v_cvt_pk_bf16_f32 v88, v100, v101
	v_cvt_pk_bf16_f32 v89, v102, v103
	v_cvt_pk_bf16_f32 v90, v92, v93
	v_add_u32_e32 v92, s9, v147
	v_ashrrev_i32_e32 v93, 31, v92
	v_lshlrev_b64 v[92:93], 12, v[92:93]
	v_lshl_add_u64 v[92:93], s[2:3], 0, v[92:93]
	v_lshl_add_u64 v[92:93], v[92:93], 0, s[0:1]
	v_lshl_add_u64 v[92:93], v[92:93], 0, v[160:161]
	v_cvt_pk_bf16_f32 v91, v94, v95
	global_store_dwordx4 v[92:93], v[88:91], off
	v_cvt_pk_bf16_f32 v80, v80, v81
	v_cvt_pk_bf16_f32 v81, v82, v83
	v_cvt_pk_bf16_f32 v82, v72, v73
	v_cvt_pk_bf16_f32 v83, v74, v75
	global_store_dwordx4 v[92:93], v[80:83], off offset:256
	v_cvt_pk_bf16_f32 v72, v84, v85
	v_cvt_pk_bf16_f32 v73, v86, v87
	v_cvt_pk_bf16_f32 v74, v76, v77
	v_add_u32_e32 v76, s9, v148
	v_ashrrev_i32_e32 v77, 31, v76
	v_lshlrev_b64 v[76:77], 12, v[76:77]
	v_lshl_add_u64 v[76:77], s[2:3], 0, v[76:77]
	v_lshl_add_u64 v[76:77], v[76:77], 0, s[0:1]
	v_lshl_add_u64 v[76:77], v[76:77], 0, v[160:161]
	v_cvt_pk_bf16_f32 v75, v78, v79
	global_store_dwordx4 v[76:77], v[72:75], off
	v_cvt_pk_bf16_f32 v68, v68, v69
	v_cvt_pk_bf16_f32 v69, v70, v71
	v_cvt_pk_bf16_f32 v70, v64, v65
	v_cvt_pk_bf16_f32 v71, v66, v67
	global_store_dwordx4 v[76:77], v[68:71], off offset:256
	v_cvt_pk_bf16_f32 v60, v60, v61
	v_cvt_pk_bf16_f32 v61, v62, v63
	v_cvt_pk_bf16_f32 v62, v56, v57
	v_add_u32_e32 v56, 0x80, v120
	v_ashrrev_i32_e32 v57, 31, v56
	v_lshlrev_b64 v[56:57], 12, v[56:57]
	v_lshl_add_u64 v[56:57], s[2:3], 0, v[56:57]
	v_lshl_add_u64 v[56:57], v[56:57], 0, s[0:1]
	v_lshl_add_u64 v[56:57], v[56:57], 0, v[160:161]
	v_cvt_pk_bf16_f32 v63, v58, v59
	global_store_dwordx4 v[56:57], v[60:63], off
	v_cvt_pk_bf16_f32 v48, v48, v49
	v_cvt_pk_bf16_f32 v49, v50, v51
	v_cvt_pk_bf16_f32 v50, v40, v41
	v_cvt_pk_bf16_f32 v51, v42, v43
	global_store_dwordx4 v[56:57], v[48:51], off offset:256
	v_cvt_pk_bf16_f32 v40, v52, v53
	v_cvt_pk_bf16_f32 v41, v54, v55
	v_cvt_pk_bf16_f32 v42, v44, v45
	v_add_u32_e32 v44, 0x90, v120
	v_ashrrev_i32_e32 v45, 31, v44
	v_lshlrev_b64 v[44:45], 12, v[44:45]
	v_lshl_add_u64 v[44:45], s[2:3], 0, v[44:45]
	v_lshl_add_u64 v[44:45], v[44:45], 0, s[0:1]
	v_lshl_add_u64 v[44:45], v[44:45], 0, v[160:161]
	v_cvt_pk_bf16_f32 v43, v46, v47
	global_store_dwordx4 v[44:45], v[40:43], off
	v_cvt_pk_bf16_f32 v32, v32, v33
	v_cvt_pk_bf16_f32 v33, v34, v35
	v_cvt_pk_bf16_f32 v34, v24, v25
	v_cvt_pk_bf16_f32 v35, v26, v27
	global_store_dwordx4 v[44:45], v[32:35], off offset:256
	v_cvt_pk_bf16_f32 v24, v36, v37
	v_cvt_pk_bf16_f32 v25, v38, v39
	v_cvt_pk_bf16_f32 v26, v28, v29
	v_add_u32_e32 v28, 0xa0, v120
	v_ashrrev_i32_e32 v29, 31, v28
	v_lshlrev_b64 v[28:29], 12, v[28:29]
	v_lshl_add_u64 v[28:29], s[2:3], 0, v[28:29]
	v_lshl_add_u64 v[28:29], v[28:29], 0, s[0:1]
	v_lshl_add_u64 v[28:29], v[28:29], 0, v[160:161]
	v_cvt_pk_bf16_f32 v27, v30, v31
	global_store_dwordx4 v[28:29], v[24:27], off
	v_cvt_pk_bf16_f32 v16, v16, v17
	v_cvt_pk_bf16_f32 v17, v18, v19
	v_cvt_pk_bf16_f32 v18, v8, v9
	v_cvt_pk_bf16_f32 v19, v10, v11
	global_store_dwordx4 v[28:29], v[16:19], off offset:256
	v_cvt_pk_bf16_f32 v8, v20, v21
	v_cvt_pk_bf16_f32 v9, v22, v23
	v_cvt_pk_bf16_f32 v10, v12, v13
	v_add_u32_e32 v12, 0xb0, v120
	v_ashrrev_i32_e32 v13, 31, v12
	v_lshlrev_b64 v[12:13], 12, v[12:13]
	v_lshl_add_u64 v[12:13], s[2:3], 0, v[12:13]
	v_lshl_add_u64 v[12:13], v[12:13], 0, s[0:1]
	v_lshl_add_u64 v[12:13], v[12:13], 0, v[160:161]
	s_and_b64 vcc, exec, s[42:43]
	s_mov_b32 s8, s24
	s_mov_b32 s9, s26
	s_mov_b64 s[0:1], s[44:45]
	s_mov_b64 s[38:39], s[36:37]
	v_cvt_pk_bf16_f32 v11, v14, v15
	global_store_dwordx4 v[12:13], v[8:11], off
	v_cvt_pk_bf16_f32 v4, v4, v5
	v_cvt_pk_bf16_f32 v5, v6, v7
	v_cvt_pk_bf16_f32 v6, v0, v1
	v_cvt_pk_bf16_f32 v7, v2, v3
	global_store_dwordx4 v[12:13], v[4:7], off offset:256
	s_cbranch_vccz .LBB0_564
	s_waitcnt vmcnt(0)
	s_cmpk_gt_u32 s4, 0xff
	s_cbranch_scc1 .LBB0_571
	s_barrier

; #define PG8_STAGE_A(bufoff, ptr, half, rev) do { if (REVA && (rev)) { const char* _p = (ptr) - ((half) ? hstepA : 0); PG8_STAGE(bufoff, _p, voffAr); } else { const char* _p = (ptr) + ((half) ? hstepA : 0); PG8_STAGE(bufoff, _p, voffA); } } while (0)
; #define PG8_LDA(dst, b, h) do { _Pragma("unroll") for (int m = 0; m < 4; ++m) _Pragma("unroll") for (int k = 0; k < 2; ++k) dst[m][k] = *(const LAS bf16x8*)(lds + PG8_SA(b, h) + aoff + m * 2048 + k * 1024); } while (0)
; #define PG8_LDB(dst, b, h) do { _Pragma("unroll") for (int n = 0; n < 2; ++n) _Pragma("unroll") for (int k = 0; k < 2; ++k) dst[n][k] = *(const LAS bf16x8*)(lds + PG8_SB(b, h) + boff + n * 2048 + k * 1024); } while (0)
; #define PG8_MMA(ai, bj, At, Bt) do { __builtin_amdgcn_s_setprio(1); _Pragma("unroll") for (int m = 0; m < 4; ++m) _Pragma("unroll") for (int n = 0; n < 2; ++n) _Pragma("unroll") for (int k = 0; k < 2; ++k) \
;         acc[ai][bj][m][n] = __builtin_amdgcn_mfma_f32_16x16x32_bf16(Bt[n][k], At[m][k], acc[ai][bj][m][n], 0, 0, 0); __builtin_amdgcn_s_setprio(0); } while (0)
; #define PG8_WAIT_L(n) asm volatile("s_waitcnt lgkmcnt(" #n ")" ::: "memory")
; #define PG8_BAR __builtin_amdgcn_s_barrier()
; #define PG8_SCHED __builtin_amdgcn_sched_barrier(0)
;     ...
;     for (;;) {
;         const bool has_next = next_unit(ui + 1, nM, nN, MP, nxt, rot);
;         const char* nA = has_next ? nxt.a : cA; const char* nB = has_next ? nxt.b : cB; const char* nAr = has_next ? nxt.ar : cAr; const size_t nHb = has_next ? nxt.hb : cHb;
;         for (int t = 0; t < nt; t += 2) {
;             const bool last = (t == nt - 2);
;             const char* a1 = PG8_APTR(cA, cAr, t + 1); const bool r1 = REVA && ((t + 1) & 4);
;             const char* a2 = last ? nA : PG8_APTR(cA, cAr, t + 2); const bool r2 = REVA && !last && ((t + 2) & 4);
;             const char* a3 = last ? nA + kstep : PG8_APTR(cA, cAr, t + 3); const bool r3 = REVA && !last && ((t + 3) & 4);
;             const char* b2 = last ? nB : cB + (size_t)(t + 2) * kstep; const char* b3 = b2 + kstep; const size_t hb2 = last ? nHb : cHb;
;             PG8_LDB(B0, 0, 0); PG8_SCHED; PG8_LDA(At, 0, 0); PG8_STAGE_A(PG8_SA(1, 1), a1, 1, r1);
;             PG8_WAIT_L(8); PG8_BAR; PG8_WAIT_L(0); PG8_MMA(0, 0, At, B0); PG8_BAR; PG8_SCHED;
.LBB0_902:
	s_add_u32 s8, s2, 0x80
	s_addc_u32 s9, s3, 0
	s_add_u32 s22, s0, 0x100
	s_addc_u32 s27, s1, 0
	s_add_u32 s0, s38, 0x80080
	s_addc_u32 s1, s39, 0
	v_mov_b32_e32 v0, 0
	v_lshl_add_u64 v[140:141], s[0:1], 0, v[136:137]
	v_lshl_add_u64 v[142:143], s[0:1], 0, v[138:139]
	s_mov_b32 s44, -2
	s_mov_b64 s[0:1], 0
	v_mov_b32_e32 v1, v0
	v_mov_b32_e32 v2, v0
	v_mov_b32_e32 v3, v0
	v_mov_b32_e32 v4, v0
	v_mov_b32_e32 v5, v0
	v_mov_b32_e32 v6, v0
	v_mov_b32_e32 v7, v0
	v_mov_b32_e32 v16, v0
	v_mov_b32_e32 v17, v0
	v_mov_b32_e32 v18, v0
	v_mov_b32_e32 v19, v0
	v_mov_b32_e32 v20, v0
	v_mov_b32_e32 v21, v0
	v_mov_b32_e32 v22, v0
	v_mov_b32_e32 v23, v0
	v_mov_b32_e32 v32, v0
	v_mov_b32_e32 v33, v0
	v_mov_b32_e32 v34, v0
	v_mov_b32_e32 v35, v0
	v_mov_b32_e32 v36, v0
	v_mov_b32_e32 v37, v0
	v_mov_b32_e32 v38, v0
	v_mov_b32_e32 v39, v0
	v_mov_b32_e32 v48, v0
	v_mov_b32_e32 v49, v0
	v_mov_b32_e32 v50, v0
	v_mov_b32_e32 v51, v0
	v_mov_b32_e32 v52, v0
	v_mov_b32_e32 v53, v0
	v_mov_b32_e32 v54, v0
	v_mov_b32_e32 v55, v0
	v_mov_b32_e32 v8, v0
	v_mov_b32_e32 v9, v0
	v_mov_b32_e32 v10, v0
	v_mov_b32_e32 v11, v0
	v_mov_b32_e32 v12, v0
	v_mov_b32_e32 v13, v0
	v_mov_b32_e32 v14, v0
	v_mov_b32_e32 v15, v0
	v_mov_b32_e32 v24, v0
	v_mov_b32_e32 v25, v0
	v_mov_b32_e32 v26, v0
	v_mov_b32_e32 v27, v0
	v_mov_b32_e32 v28, v0
	v_mov_b32_e32 v29, v0
	v_mov_b32_e32 v30, v0
	v_mov_b32_e32 v31, v0
	v_mov_b32_e32 v40, v0
	v_mov_b32_e32 v41, v0
	v_mov_b32_e32 v42, v0
	v_mov_b32_e32 v43, v0
	v_mov_b32_e32 v44, v0
	v_mov_b32_e32 v45, v0
	v_mov_b32_e32 v46, v0
	v_mov_b32_e32 v47, v0
	v_mov_b32_e32 v56, v0
	v_mov_b32_e32 v57, v0
	v_mov_b32_e32 v58, v0
	v_mov_b32_e32 v59, v0
	v_mov_b32_e32 v60, v0
	v_mov_b32_e32 v61, v0
	v_mov_b32_e32 v62, v0
	v_mov_b32_e32 v63, v0
	v_mov_b32_e32 v64, v0
	v_mov_b32_e32 v65, v0
	v_mov_b32_e32 v66, v0
	v_mov_b32_e32 v67, v0
	v_mov_b32_e32 v68, v0
	v_mov_b32_e32 v69, v0
	v_mov_b32_e32 v70, v0
	v_mov_b32_e32 v71, v0
	v_mov_b32_e32 v80, v0
	v_mov_b32_e32 v81, v0
	v_mov_b32_e32 v82, v0
	v_mov_b32_e32 v83, v0
	v_mov_b32_e32 v84, v0
	v_mov_b32_e32 v85, v0
	v_mov_b32_e32 v86, v0
	v_mov_b32_e32 v87, v0
	v_mov_b32_e32 v96, v0
	v_mov_b32_e32 v97, v0
	v_mov_b32_e32 v98, v0
	v_mov_b32_e32 v99, v0
	v_mov_b32_e32 v100, v0
	v_mov_b32_e32 v101, v0
	v_mov_b32_e32 v102, v0
	v_mov_b32_e32 v103, v0
	v_mov_b32_e32 v112, v0
	v_mov_b32_e32 v113, v0
	v_mov_b32_e32 v114, v0
	v_mov_b32_e32 v115, v0
	v_mov_b32_e32 v116, v0
	v_mov_b32_e32 v117, v0
	v_mov_b32_e32 v118, v0
	v_mov_b32_e32 v119, v0
	v_mov_b32_e32 v72, v0
	v_mov_b32_e32 v73, v0
	v_mov_b32_e32 v74, v0
	v_mov_b32_e32 v75, v0
	v_mov_b32_e32 v76, v0
	v_mov_b32_e32 v77, v0
	v_mov_b32_e32 v78, v0
	v_mov_b32_e32 v79, v0
	v_mov_b32_e32 v88, v0
	v_mov_b32_e32 v89, v0
	v_mov_b32_e32 v90, v0
	v_mov_b32_e32 v91, v0
	v_mov_b32_e32 v92, v0
	v_mov_b32_e32 v93, v0
	v_mov_b32_e32 v94, v0
	v_mov_b32_e32 v95, v0
	v_mov_b32_e32 v104, v0
	v_mov_b32_e32 v105, v0
	v_mov_b32_e32 v106, v0
	v_mov_b32_e32 v107, v0
	v_mov_b32_e32 v108, v0
	v_mov_b32_e32 v109, v0
	v_mov_b32_e32 v110, v0
	v_mov_b32_e32 v111, v0
	v_mov_b32_e32 v120, v0
	v_mov_b32_e32 v121, v0
	v_mov_b32_e32 v122, v0
	v_mov_b32_e32 v123, v0
	v_mov_b32_e32 v124, v0
	v_mov_b32_e32 v125, v0
	v_mov_b32_e32 v126, v0
	v_mov_b32_e32 v127, v0
	v_add_u32_e32 v158, 0x10000, v145
	ds_read_b128 v[154:157], v158
	ds_read_b128 v[168:171], v158 offset:1024
	ds_read_b128 v[172:175], v158 offset:2048
	ds_read_b128 v[176:179], v158 offset:3072
.LBB0_903:
	s_add_u32 s10, s38, s0
	s_addc_u32 s11, s39, s1
	s_add_u32 s20, s10, 0x100
	s_addc_u32 s21, s11, 0
	s_add_u32 s10, s10, 0x180
	s_addc_u32 s11, s11, 0
	s_add_u32 s14, s22, s0
	s_addc_u32 s15, s27, s1
	s_add_i32 s45, 0, 0x10000
	s_cmpk_eq_i32 s0, 0xf00
	s_cselect_b32 s15, s37, s15
	s_cselect_b32 s14, s36, s14
	s_cselect_b32 s17, s9, s11
	s_cselect_b32 s16, s8, s10
	s_cselect_b32 s21, s3, s21
	s_cselect_b32 s20, s2, s20
	v_lshl_add_u64 v[158:159], v[140:141], 0, s[0:1]
	s_add_i32 m0, s48, 0xc000
	ds_read_b128 v[180:183], v153
	ds_read_b128 v[204:207], v153 offset:1024
	ds_read_b128 v[208:211], v153 offset:2048
	ds_read_b128 v[212:215], v153 offset:3072
	ds_read_b128 v[216:219], v153 offset:4096
	ds_read_b128 v[220:223], v153 offset:5120
	ds_read_b128 v[224:227], v153 offset:6144
	ds_read_b128 v[228:231], v153 offset:7168
	global_load_lds_dwordx4 v[158:159], off
	v_lshl_add_u64 v[158:159], v[142:143], 0, s[0:1]
	s_add_i32 m0, s48, 0xe000
	s_nop 0
	global_load_lds_dwordx4 v[158:159], off
	s_waitcnt lgkmcnt(8)
	s_barrier
	s_waitcnt lgkmcnt(0)
	s_setprio 1
	s_waitcnt lgkmcnt(0)
	v_mfma_f32_16x16x32_bf16 v[124:127], v[154:157], v[180:183], v[124:127]
	v_mfma_f32_16x16x32_bf16 v[120:123], v[172:175], v[180:183], v[120:123]
	v_mfma_f32_16x16x32_bf16 v[108:111], v[154:157], v[208:211], v[108:111]
	v_mfma_f32_16x16x32_bf16 v[104:107], v[172:175], v[208:211], v[104:107]
	v_mfma_f32_16x16x32_bf16 v[92:95], v[154:157], v[216:219], v[92:95]
	v_mfma_f32_16x16x32_bf16 v[88:91], v[172:175], v[216:219], v[88:91]
	v_mfma_f32_16x16x32_bf16 v[76:79], v[154:157], v[224:227], v[76:79]
	v_mfma_f32_16x16x32_bf16 v[72:75], v[172:175], v[224:227], v[72:75]
	v_mfma_f32_16x16x32_bf16 v[124:127], v[168:171], v[204:207], v[124:127]
	v_mfma_f32_16x16x32_bf16 v[120:123], v[176:179], v[204:207], v[120:123]
	v_mfma_f32_16x16x32_bf16 v[108:111], v[168:171], v[212:215], v[108:111]
	v_mfma_f32_16x16x32_bf16 v[104:107], v[176:179], v[212:215], v[104:107]
	v_mfma_f32_16x16x32_bf16 v[92:95], v[168:171], v[220:223], v[92:95]
	v_mfma_f32_16x16x32_bf16 v[88:91], v[176:179], v[220:223], v[88:91]
	v_mfma_f32_16x16x32_bf16 v[76:79], v[168:171], v[228:231], v[76:79]
	v_mfma_f32_16x16x32_bf16 v[72:75], v[176:179], v[228:231], v[72:75]
	s_setprio 0
	s_barrier
; #define PG8_STAGE(bufoff, gbase, voff) do { _Pragma("unroll") for (int _i = 0; _i < 2; ++_i) \
;         __builtin_amdgcn_global_load_lds((const unsigned*)((const char*)(gbase) + (voff)[_i]), (LAS unsigned*)(lds + (bufoff) + ldsw + _i * 8192), 16, 0, 0); } while (0)
; #define PG8_STAGE_A(bufoff, ptr, half, rev) do { if (REVA && (rev)) { const char* _p = (ptr) - ((half) ? hstepA : 0); PG8_STAGE(bufoff, _p, voffAr); } else { const char* _p = (ptr) + ((half) ? hstepA : 0); PG8_STAGE(bufoff, _p, voffA); } } while (0)
; #define PG8_LDA(dst, b, h) do { _Pragma("unroll") for (int m = 0; m < 4; ++m) _Pragma("unroll") for (int k = 0; k < 2; ++k) dst[m][k] = *(const LAS bf16x8*)(lds + PG8_SA(b, h) + aoff + m * 2048 + k * 1024); } while (0)
; #define PG8_LDB(dst, b, h) do { _Pragma("unroll") for (int n = 0; n < 2; ++n) _Pragma("unroll") for (int k = 0; k < 2; ++k) dst[n][k] = *(const LAS bf16x8*)(lds + PG8_SB(b, h) + boff + n * 2048 + k * 1024); } while (0)
; #define PG8_MMA(ai, bj, At, Bt) do { __builtin_amdgcn_s_setprio(1); _Pragma("unroll") for (int m = 0; m < 4; ++m) _Pragma("unroll") for (int n = 0; n < 2; ++n) _Pragma("unroll") for (int k = 0; k < 2; ++k) \
;         acc[ai][bj][m][n] = __builtin_amdgcn_mfma_f32_16x16x32_bf16(Bt[n][k], At[m][k], acc[ai][bj][m][n], 0, 0, 0); __builtin_amdgcn_s_setprio(0); } while (0)
; #define PG8_WAIT_V(n) asm volatile("s_waitcnt vmcnt(" #n ")" ::: "memory")
; #define PG8_WAIT_L(n) asm volatile("s_waitcnt lgkmcnt(" #n ")" ::: "memory")
; #define PG8_BAR __builtin_amdgcn_s_barrier()
; #define PG8_SCHED __builtin_amdgcn_sched_barrier(0)
;     ...
;             PG8_LDB(B1, 0, 1); PG8_STAGE(PG8_SB(0, 0), b2, voffB);
;             PG8_BAR; PG8_WAIT_L(0); PG8_MMA(0, 1, At, B1); PG8_BAR;
;             PG8_LDA(At, 0, 1); PG8_STAGE_A(PG8_SA(0, 0), a2, 0, r2);
;             PG8_BAR; PG8_WAIT_L(0); PG8_MMA(1, 0, At, B0); PG8_BAR; PG8_SCHED;
;             PG8_STAGE(PG8_SB(0, 1), b2 + hb2, voffB);
;             PG8_WAIT_V(6); PG8_BAR; PG8_MMA(1, 1, At, B1); PG8_BAR;
;             PG8_LDB(B0, 1, 0); PG8_SCHED; PG8_LDA(At, 1, 0); PG8_STAGE_A(PG8_SA(0, 1), a2, 1, r2);
	s_add_i32 s10, 0, 0x14000
	v_add_u32_e32 v158, s10, v145
	s_add_i32 s11, s45, s47
	ds_read_b128 v[232:235], v158
	ds_read_b128 v[236:239], v158 offset:1024
	ds_read_b128 v[240:243], v158 offset:2048
	ds_read_b128 v[244:247], v158 offset:3072
	v_lshl_add_u64 v[158:159], s[14:15], 0, v[130:131]
	s_mov_b32 m0, s11
	v_lshl_add_u64 v[184:185], s[14:15], 0, v[134:135]
	global_load_lds_dwordx4 v[158:159], off
	s_add_i32 m0, s11, 0x2000
	s_nop 0
	global_load_lds_dwordx4 v[184:185], off
	s_barrier
	s_waitcnt lgkmcnt(0)
	s_setprio 1
	s_waitcnt lgkmcnt(0)
	v_mfma_f32_16x16x32_bf16 v[116:119], v[232:235], v[180:183], v[116:119]
	v_mfma_f32_16x16x32_bf16 v[112:115], v[240:243], v[180:183], v[112:115]
	v_mfma_f32_16x16x32_bf16 v[100:103], v[232:235], v[208:211], v[100:103]
	v_mfma_f32_16x16x32_bf16 v[96:99], v[240:243], v[208:211], v[96:99]
	v_mfma_f32_16x16x32_bf16 v[84:87], v[232:235], v[216:219], v[84:87]
	v_mfma_f32_16x16x32_bf16 v[80:83], v[240:243], v[216:219], v[80:83]
	v_mfma_f32_16x16x32_bf16 v[68:71], v[232:235], v[224:227], v[68:71]
	v_mfma_f32_16x16x32_bf16 v[64:67], v[240:243], v[224:227], v[64:67]
	v_mfma_f32_16x16x32_bf16 v[116:119], v[236:239], v[204:207], v[116:119]
	v_mfma_f32_16x16x32_bf16 v[112:115], v[244:247], v[204:207], v[112:115]
	v_mfma_f32_16x16x32_bf16 v[100:103], v[236:239], v[212:215], v[100:103]
	v_mfma_f32_16x16x32_bf16 v[96:99], v[244:247], v[212:215], v[96:99]
	v_mfma_f32_16x16x32_bf16 v[84:87], v[236:239], v[220:223], v[84:87]
	v_mfma_f32_16x16x32_bf16 v[80:83], v[244:247], v[220:223], v[80:83]
	v_mfma_f32_16x16x32_bf16 v[68:71], v[236:239], v[228:231], v[68:71]
	v_mfma_f32_16x16x32_bf16 v[64:67], v[244:247], v[228:231], v[64:67]
	s_setprio 0
	s_mov_b32 m0, s48
	v_lshl_add_u64 v[190:191], s[20:21], 0, v[128:129]
	s_barrier
	ds_read_b128 v[180:183], v153 offset:16384
	ds_read_b128 v[204:207], v153 offset:17408
	ds_read_b128 v[208:211], v153 offset:18432
	ds_read_b128 v[212:215], v153 offset:19456
	ds_read_b128 v[216:219], v153 offset:20480
	ds_read_b128 v[220:223], v153 offset:21504
	ds_read_b128 v[224:227], v153 offset:22528
	ds_read_b128 v[228:231], v153 offset:23552
	global_load_lds_dwordx4 v[190:191], off
	v_lshl_add_u64 v[190:191], s[20:21], 0, v[132:133]
	s_mov_b32 m0, s49
	s_nop 0
	global_load_lds_dwordx4 v[190:191], off
	s_waitcnt vmcnt(10)
	s_barrier
	s_waitcnt lgkmcnt(0)
	s_setprio 1
	s_waitcnt lgkmcnt(0)
	v_mfma_f32_16x16x32_bf16 v[60:63], v[154:157], v[180:183], v[60:63]
	v_mfma_f32_16x16x32_bf16 v[56:59], v[172:175], v[180:183], v[56:59]
	v_mfma_f32_16x16x32_bf16 v[44:47], v[154:157], v[208:211], v[44:47]
	v_mfma_f32_16x16x32_bf16 v[40:43], v[172:175], v[208:211], v[40:43]
	v_mfma_f32_16x16x32_bf16 v[28:31], v[154:157], v[216:219], v[28:31]
	v_mfma_f32_16x16x32_bf16 v[24:27], v[172:175], v[216:219], v[24:27]
	v_mfma_f32_16x16x32_bf16 v[12:15], v[154:157], v[224:227], v[12:15]
	v_mfma_f32_16x16x32_bf16 v[8:11], v[172:175], v[224:227], v[8:11]
	v_mfma_f32_16x16x32_bf16 v[60:63], v[168:171], v[204:207], v[60:63]
	v_mfma_f32_16x16x32_bf16 v[56:59], v[176:179], v[204:207], v[56:59]
	v_mfma_f32_16x16x32_bf16 v[44:47], v[168:171], v[212:215], v[44:47]
	v_mfma_f32_16x16x32_bf16 v[40:43], v[176:179], v[212:215], v[40:43]
	v_mfma_f32_16x16x32_bf16 v[28:31], v[168:171], v[220:223], v[28:31]
	v_mfma_f32_16x16x32_bf16 v[24:27], v[176:179], v[220:223], v[24:27]
	v_mfma_f32_16x16x32_bf16 v[12:15], v[168:171], v[228:231], v[12:15]
	v_mfma_f32_16x16x32_bf16 v[8:11], v[176:179], v[228:231], v[8:11]
	s_setprio 0
	s_barrier
	s_add_u32 s70, s14, 0x880000
	s_addc_u32 s71, s15, 0
	s_add_i32 s10, s10, s47
	v_lshl_add_u64 v[154:155], s[70:71], 0, v[130:131]
	s_mov_b32 m0, s10
	s_nop 0
	global_load_lds_dwordx4 v[154:155], off
	v_lshl_add_u64 v[154:155], s[70:71], 0, v[134:135]
	s_add_i32 m0, s10, 0x2000
	s_nop 0
	global_load_lds_dwordx4 v[154:155], off
	v_add_u32_e32 v176, 0x18000, v145
	ds_read_b128 v[154:157], v176
	ds_read_b128 v[168:171], v176 offset:1024
	ds_read_b128 v[172:175], v176 offset:2048
	ds_read_b128 v[176:179], v176 offset:3072
	s_waitcnt vmcnt(6)
	s_barrier
	s_setprio 1
	v_mfma_f32_16x16x32_bf16 v[52:55], v[232:235], v[180:183], v[52:55]
	v_mfma_f32_16x16x32_bf16 v[48:51], v[240:243], v[180:183], v[48:51]
	v_mfma_f32_16x16x32_bf16 v[36:39], v[232:235], v[208:211], v[36:39]
	v_mfma_f32_16x16x32_bf16 v[32:35], v[240:243], v[208:211], v[32:35]
	v_mfma_f32_16x16x32_bf16 v[20:23], v[232:235], v[216:219], v[20:23]
	v_mfma_f32_16x16x32_bf16 v[16:19], v[240:243], v[216:219], v[16:19]
	v_mfma_f32_16x16x32_bf16 v[4:7], v[232:235], v[224:227], v[4:7]
	v_mfma_f32_16x16x32_bf16 v[0:3], v[240:243], v[224:227], v[0:3]
	v_mfma_f32_16x16x32_bf16 v[52:55], v[236:239], v[204:207], v[52:55]
	v_mfma_f32_16x16x32_bf16 v[48:51], v[244:247], v[204:207], v[48:51]
	v_mfma_f32_16x16x32_bf16 v[36:39], v[236:239], v[212:215], v[36:39]
	v_mfma_f32_16x16x32_bf16 v[32:35], v[244:247], v[212:215], v[32:35]
	v_mfma_f32_16x16x32_bf16 v[20:23], v[236:239], v[220:223], v[20:23]
	v_mfma_f32_16x16x32_bf16 v[16:19], v[244:247], v[220:223], v[16:19]
	v_mfma_f32_16x16x32_bf16 v[4:7], v[236:239], v[228:231], v[4:7]
	v_mfma_f32_16x16x32_bf16 v[0:3], v[244:247], v[228:231], v[0:3]
	s_setprio 0
	s_add_i32 s10, 0, 0x18000
	s_barrier
	s_add_u32 s20, s20, 0x80000
	s_addc_u32 s21, s21, 0
	s_mov_b32 m0, s50
	v_lshl_add_u64 v[190:191], s[20:21], 0, v[128:129]
	ds_read_b128 v[180:183], v153 offset:32768
	ds_read_b128 v[204:207], v153 offset:33792
	ds_read_b128 v[208:211], v153 offset:34816
	ds_read_b128 v[212:215], v153 offset:35840
	ds_read_b128 v[216:219], v153 offset:36864
	ds_read_b128 v[220:223], v153 offset:37888
	ds_read_b128 v[224:227], v153 offset:38912
	ds_read_b128 v[228:231], v153 offset:39936
	global_load_lds_dwordx4 v[190:191], off
	v_lshl_add_u64 v[190:191], s[20:21], 0, v[132:133]
	s_mov_b32 m0, s51
	s_nop 0
	global_load_lds_dwordx4 v[190:191], off
	s_waitcnt lgkmcnt(8)
	s_barrier
; #define PG8_STAGE(bufoff, gbase, voff) do { _Pragma("unroll") for (int _i = 0; _i < 2; ++_i) \
;         __builtin_amdgcn_global_load_lds((const unsigned*)((const char*)(gbase) + (voff)[_i]), (LAS unsigned*)(lds + (bufoff) + ldsw + _i * 8192), 16, 0, 0); } while (0)
; #define PG8_STAGE_A(bufoff, ptr, half, rev) do { if (REVA && (rev)) { const char* _p = (ptr) - ((half) ? hstepA : 0); PG8_STAGE(bufoff, _p, voffAr); } else { const char* _p = (ptr) + ((half) ? hstepA : 0); PG8_STAGE(bufoff, _p, voffA); } } while (0)
; #define PG8_LDA(dst, b, h) do { _Pragma("unroll") for (int m = 0; m < 4; ++m) _Pragma("unroll") for (int k = 0; k < 2; ++k) dst[m][k] = *(const LAS bf16x8*)(lds + PG8_SA(b, h) + aoff + m * 2048 + k * 1024); } while (0)
; #define PG8_LDB(dst, b, h) do { _Pragma("unroll") for (int n = 0; n < 2; ++n) _Pragma("unroll") for (int k = 0; k < 2; ++k) dst[n][k] = *(const LAS bf16x8*)(lds + PG8_SB(b, h) + boff + n * 2048 + k * 1024); } while (0)
; #define PG8_MMA(ai, bj, At, Bt) do { __builtin_amdgcn_s_setprio(1); _Pragma("unroll") for (int m = 0; m < 4; ++m) _Pragma("unroll") for (int n = 0; n < 2; ++n) _Pragma("unroll") for (int k = 0; k < 2; ++k) \
;         acc[ai][bj][m][n] = __builtin_amdgcn_mfma_f32_16x16x32_bf16(Bt[n][k], At[m][k], acc[ai][bj][m][n], 0, 0, 0); __builtin_amdgcn_s_setprio(0); } while (0)
; #define PG8_WAIT_L(n) asm volatile("s_waitcnt lgkmcnt(" #n ")" ::: "memory")
; #define PG8_BAR __builtin_amdgcn_s_barrier()
; #define PG8_SCHED __builtin_amdgcn_sched_barrier(0)
;     ...
;             PG8_LDB(B0, 1, 0); PG8_SCHED; PG8_LDA(At, 1, 0); PG8_STAGE_A(PG8_SA(0, 1), a2, 1, r2);
;             PG8_WAIT_L(8); PG8_BAR; PG8_WAIT_L(0); PG8_MMA(0, 0, At, B0); PG8_BAR; PG8_SCHED;
;             PG8_LDB(B1, 1, 1); PG8_STAGE(PG8_SB(1, 0), b3, voffB);
;             PG8_BAR; PG8_WAIT_L(0); PG8_MMA(0, 1, At, B1); PG8_BAR;
;             PG8_LDA(At, 1, 1); PG8_STAGE_A(PG8_SA(1, 0), a3, 0, r3);
;             PG8_BAR; PG8_WAIT_L(0); PG8_MMA(1, 0, At, B0); PG8_BAR; PG8_SCHED;
	s_waitcnt lgkmcnt(0)
	s_setprio 1
	s_waitcnt lgkmcnt(0)
	v_mfma_f32_16x16x32_bf16 v[124:127], v[154:157], v[180:183], v[124:127]
	v_mfma_f32_16x16x32_bf16 v[120:123], v[172:175], v[180:183], v[120:123]
	v_mfma_f32_16x16x32_bf16 v[108:111], v[154:157], v[208:211], v[108:111]
	v_mfma_f32_16x16x32_bf16 v[104:107], v[172:175], v[208:211], v[104:107]
	v_mfma_f32_16x16x32_bf16 v[92:95], v[154:157], v[216:219], v[92:95]
	v_mfma_f32_16x16x32_bf16 v[88:91], v[172:175], v[216:219], v[88:91]
	v_mfma_f32_16x16x32_bf16 v[76:79], v[154:157], v[224:227], v[76:79]
	v_mfma_f32_16x16x32_bf16 v[72:75], v[172:175], v[224:227], v[72:75]
	v_mfma_f32_16x16x32_bf16 v[124:127], v[168:171], v[204:207], v[124:127]
	v_mfma_f32_16x16x32_bf16 v[120:123], v[176:179], v[204:207], v[120:123]
	v_mfma_f32_16x16x32_bf16 v[108:111], v[168:171], v[212:215], v[108:111]
	v_mfma_f32_16x16x32_bf16 v[104:107], v[176:179], v[212:215], v[104:107]
	v_mfma_f32_16x16x32_bf16 v[92:95], v[168:171], v[220:223], v[92:95]
	v_mfma_f32_16x16x32_bf16 v[88:91], v[176:179], v[220:223], v[88:91]
	v_mfma_f32_16x16x32_bf16 v[76:79], v[168:171], v[228:231], v[76:79]
	v_mfma_f32_16x16x32_bf16 v[72:75], v[176:179], v[228:231], v[72:75]
	s_setprio 0
	s_barrier
	s_add_i32 s11, 0, 0x1c000
	s_add_i32 s10, s10, s47
	v_add_u32_e32 v190, s11, v145
	v_lshl_add_u64 v[158:159], v[158:159], 0, s[28:29]
	s_mov_b32 m0, s10
	ds_read_b128 v[232:235], v190
	ds_read_b128 v[236:239], v190 offset:1024
	ds_read_b128 v[240:243], v190 offset:2048
	ds_read_b128 v[244:247], v190 offset:3072
	global_load_lds_dwordx4 v[158:159], off
	v_lshl_add_u64 v[158:159], v[184:185], 0, s[28:29]
	s_add_i32 m0, s10, 0x2000
	s_nop 0
	global_load_lds_dwordx4 v[158:159], off
	s_barrier
	s_waitcnt lgkmcnt(0)
	s_setprio 1
	s_waitcnt lgkmcnt(0)
	v_mfma_f32_16x16x32_bf16 v[116:119], v[232:235], v[180:183], v[116:119]
	v_mfma_f32_16x16x32_bf16 v[112:115], v[240:243], v[180:183], v[112:115]
	v_mfma_f32_16x16x32_bf16 v[100:103], v[232:235], v[208:211], v[100:103]
	v_mfma_f32_16x16x32_bf16 v[96:99], v[240:243], v[208:211], v[96:99]
	v_mfma_f32_16x16x32_bf16 v[84:87], v[232:235], v[216:219], v[84:87]
	v_mfma_f32_16x16x32_bf16 v[80:83], v[240:243], v[216:219], v[80:83]
	v_mfma_f32_16x16x32_bf16 v[68:71], v[232:235], v[224:227], v[68:71]
	v_mfma_f32_16x16x32_bf16 v[64:67], v[240:243], v[224:227], v[64:67]
	v_mfma_f32_16x16x32_bf16 v[116:119], v[236:239], v[204:207], v[116:119]
	v_mfma_f32_16x16x32_bf16 v[112:115], v[244:247], v[204:207], v[112:115]
	v_mfma_f32_16x16x32_bf16 v[100:103], v[236:239], v[212:215], v[100:103]
	v_mfma_f32_16x16x32_bf16 v[96:99], v[244:247], v[212:215], v[96:99]
	v_mfma_f32_16x16x32_bf16 v[84:87], v[236:239], v[220:223], v[84:87]
	v_mfma_f32_16x16x32_bf16 v[80:83], v[244:247], v[220:223], v[80:83]
	v_mfma_f32_16x16x32_bf16 v[68:71], v[236:239], v[228:231], v[68:71]
	v_mfma_f32_16x16x32_bf16 v[64:67], v[244:247], v[228:231], v[64:67]
	s_setprio 0
	s_mov_b32 m0, s66
	v_lshl_add_u64 v[158:159], s[16:17], 0, v[128:129]
	s_barrier
	ds_read_b128 v[180:183], v153 offset:49152
	ds_read_b128 v[204:207], v153 offset:50176
	ds_read_b128 v[208:211], v153 offset:51200
	ds_read_b128 v[212:215], v153 offset:52224
	ds_read_b128 v[216:219], v153 offset:53248
	ds_read_b128 v[220:223], v153 offset:54272
	ds_read_b128 v[224:227], v153 offset:55296
	ds_read_b128 v[228:231], v153 offset:56320
	global_load_lds_dwordx4 v[158:159], off
	v_lshl_add_u64 v[158:159], s[16:17], 0, v[132:133]
	s_mov_b32 m0, s67
	s_nop 0
	global_load_lds_dwordx4 v[158:159], off
	s_waitcnt vmcnt(10)
	s_barrier
; __device__ __forceinline__ unsigned cvt_pk_bf16(float lo, float hi) { unsigned r; asm volatile("v_cvt_pk_bf16_f32 %0, %1, %2" : "=v"(r) : "v"(lo), "v"(hi)); return r; }
; #define PG8_STAGE(bufoff, gbase, voff) do { _Pragma("unroll") for (int _i = 0; _i < 2; ++_i) \
;         __builtin_amdgcn_global_load_lds((const unsigned*)((const char*)(gbase) + (voff)[_i]), (LAS unsigned*)(lds + (bufoff) + ldsw + _i * 8192), 16, 0, 0); } while (0)
; #define PG8_MMA(ai, bj, At, Bt) do { __builtin_amdgcn_s_setprio(1); _Pragma("unroll") for (int m = 0; m < 4; ++m) _Pragma("unroll") for (int n = 0; n < 2; ++n) _Pragma("unroll") for (int k = 0; k < 2; ++k) \
;         acc[ai][bj][m][n] = __builtin_amdgcn_mfma_f32_16x16x32_bf16(Bt[n][k], At[m][k], acc[ai][bj][m][n], 0, 0, 0); __builtin_amdgcn_s_setprio(0); } while (0)
; #define PG8_WAIT_V(n) asm volatile("s_waitcnt vmcnt(" #n ")" ::: "memory")
; #define PG8_WAIT_L(n) asm volatile("s_waitcnt lgkmcnt(" #n ")" ::: "memory")
; #define PG8_BAR __builtin_amdgcn_s_barrier()
; #define PG8_SCHED __builtin_amdgcn_sched_barrier(0)
;     ...
;             PG8_BAR; PG8_WAIT_L(0); PG8_MMA(1, 0, At, B0); PG8_BAR; PG8_SCHED;
;             PG8_STAGE(PG8_SB(1, 1), b3 + hb2, voffB);
;             PG8_WAIT_V(6); PG8_BAR; PG8_MMA(1, 1, At, B1); PG8_BAR;
;         }
;     __device__ __forceinline__ void generic(const f32x4 (&acc)[2][2][4][2], const Unit& u, int wr, int wc, int fr, int fq) const {
;     ...
;                     } else if (MODE == 1) {
;                         const int b = u.pn >> 3, g = u.pn & 7, k = (Lb == 4096) ? (2 * ((u.pm & 7) * BM + rt) + (u.pm >> 3)) : (u.pm * BM + rt), rb = rowbase0 + b * (Lb + 1);
;                         u32x4 w; w.x = cvt_pk_bf16(v0[0], v0[1]); w.y = cvt_pk_bf16(v0[2], v0[3]); w.z = cvt_pk_bf16(v1[0], v1[1]); w.w = cvt_pk_bf16(v1[2], v1[3]);
;                         *(u32x4*)(O + (size_t)(rb + k) * 2048 + g * 256 + ct) = w;
;                         if (k == 0) *(u32x4*)(O + (size_t)(rb + Lb) * 2048 + g * 256 + ct) = w;
	s_waitcnt lgkmcnt(0)
	s_setprio 1
	s_waitcnt lgkmcnt(0)
	v_mfma_f32_16x16x32_bf16 v[60:63], v[154:157], v[180:183], v[60:63]
	v_mfma_f32_16x16x32_bf16 v[56:59], v[172:175], v[180:183], v[56:59]
	v_mfma_f32_16x16x32_bf16 v[44:47], v[154:157], v[208:211], v[44:47]
	v_mfma_f32_16x16x32_bf16 v[40:43], v[172:175], v[208:211], v[40:43]
	v_mfma_f32_16x16x32_bf16 v[28:31], v[154:157], v[216:219], v[28:31]
	v_mfma_f32_16x16x32_bf16 v[24:27], v[172:175], v[216:219], v[24:27]
	v_mfma_f32_16x16x32_bf16 v[12:15], v[154:157], v[224:227], v[12:15]
	v_mfma_f32_16x16x32_bf16 v[8:11], v[172:175], v[224:227], v[8:11]
	v_mfma_f32_16x16x32_bf16 v[60:63], v[168:171], v[204:207], v[60:63]
	v_mfma_f32_16x16x32_bf16 v[56:59], v[176:179], v[204:207], v[56:59]
	v_mfma_f32_16x16x32_bf16 v[44:47], v[168:171], v[212:215], v[44:47]
	v_mfma_f32_16x16x32_bf16 v[40:43], v[176:179], v[212:215], v[40:43]
	v_mfma_f32_16x16x32_bf16 v[28:31], v[168:171], v[220:223], v[28:31]
	v_mfma_f32_16x16x32_bf16 v[24:27], v[176:179], v[220:223], v[24:27]
	v_mfma_f32_16x16x32_bf16 v[12:15], v[168:171], v[228:231], v[12:15]
	v_mfma_f32_16x16x32_bf16 v[8:11], v[176:179], v[228:231], v[8:11]
	s_setprio 0
	s_barrier
	s_add_u32 s14, s14, 0x880080
	s_addc_u32 s15, s15, 0
	s_add_i32 s10, s11, s47
	v_lshl_add_u64 v[154:155], s[14:15], 0, v[130:131]
	s_mov_b32 m0, s10
	s_nop 0
	global_load_lds_dwordx4 v[154:155], off
	v_lshl_add_u64 v[154:155], s[14:15], 0, v[134:135]
	s_add_i32 m0, s10, 0x2000
	s_nop 0
	global_load_lds_dwordx4 v[154:155], off
	v_add_u32_e32 v158, 0x10000, v145
	ds_read_b128 v[154:157], v158
	ds_read_b128 v[168:171], v158 offset:1024
	ds_read_b128 v[172:175], v158 offset:2048
	ds_read_b128 v[176:179], v158 offset:3072
	s_waitcnt vmcnt(6)
	s_barrier
	s_setprio 1
	v_mfma_f32_16x16x32_bf16 v[52:55], v[232:235], v[180:183], v[52:55]
	v_mfma_f32_16x16x32_bf16 v[48:51], v[240:243], v[180:183], v[48:51]
	v_mfma_f32_16x16x32_bf16 v[36:39], v[232:235], v[208:211], v[36:39]
	v_mfma_f32_16x16x32_bf16 v[32:35], v[240:243], v[208:211], v[32:35]
	v_mfma_f32_16x16x32_bf16 v[20:23], v[232:235], v[216:219], v[20:23]
	v_mfma_f32_16x16x32_bf16 v[16:19], v[240:243], v[216:219], v[16:19]
	v_mfma_f32_16x16x32_bf16 v[4:7], v[232:235], v[224:227], v[4:7]
	v_mfma_f32_16x16x32_bf16 v[0:3], v[240:243], v[224:227], v[0:3]
	v_mfma_f32_16x16x32_bf16 v[52:55], v[236:239], v[204:207], v[52:55]
	v_mfma_f32_16x16x32_bf16 v[48:51], v[244:247], v[204:207], v[48:51]
	v_mfma_f32_16x16x32_bf16 v[36:39], v[236:239], v[212:215], v[36:39]
	v_mfma_f32_16x16x32_bf16 v[32:35], v[244:247], v[212:215], v[32:35]
	v_mfma_f32_16x16x32_bf16 v[20:23], v[236:239], v[220:223], v[20:23]
	v_mfma_f32_16x16x32_bf16 v[16:19], v[244:247], v[220:223], v[16:19]
	v_mfma_f32_16x16x32_bf16 v[4:7], v[236:239], v[228:231], v[4:7]
	v_mfma_f32_16x16x32_bf16 v[0:3], v[244:247], v[228:231], v[0:3]
	s_setprio 0
	s_add_i32 s44, s44, 2
	s_add_u32 s0, s0, 0x100
	s_addc_u32 s1, s1, 0
	s_cmp_gt_u32 s44, 29
	s_barrier
	s_cbranch_scc0 .LBB0_903
	s_waitcnt lgkmcnt(0)
	s_lshl_b32 s1, s7, 8
	s_and_b32 s8, s1, 0x700
	s_ashr_i32 s0, s6, 3
	v_add_u32_e32 v140, s8, v144
	s_ashr_i32 s7, s7, 3
	v_lshl_add_u32 v140, v140, 1, s7
	s_mulk_i32 s0, 0x1001
	v_cvt_pk_bf16_f32 v124, v124, v125
	v_cvt_pk_bf16_f32 v125, v126, v127
	v_cvt_pk_bf16_f32 v126, v120, v121
	v_add_u32_e32 v120, s0, v140
	v_ashrrev_i32_e32 v121, 31, v120
	s_lshl_b32 s1, s6, 8
	v_lshlrev_b64 v[120:121], 12, v[120:121]
	s_and_b32 s1, s1, 0x700
	v_lshl_add_u64 v[120:121], s[24:25], 0, v[120:121]
	s_lshl_b32 s22, s1, 1
	v_lshl_add_u64 v[120:121], v[120:121], 0, s[22:23]
	v_lshl_add_u64 v[120:121], v[120:121], 0, v[160:161]
	v_cmp_eq_u32_e64 s[44:45], 0, v140
	v_cvt_pk_bf16_f32 v127, v122, v123
	global_store_dwordx4 v[120:121], v[124:127], off
	s_and_saveexec_b64 s[14:15], s[44:45]
	s_cbranch_execz .LBB0_906
	s_ashr_i32 s1, s0, 31
	s_lshl_b64 s[16:17], s[0:1], 12
	s_add_u32 s1, s24, s16
	s_addc_u32 s6, s25, s17
	s_add_u32 s16, s1, s22
	s_addc_u32 s17, s6, 0
	v_lshl_add_u64 v[122:123], s[16:17], 0, v[160:161]
	v_add_co_u32_e32 v122, vcc, 0x1000000, v122
	s_nop 1
	v_addc_co_u32_e32 v123, vcc, 0, v123, vcc
	global_store_dwordx4 v[122:123], v[124:127], off

; #define PG8_STAGE_A(bufoff, ptr, half, rev) do { if (REVA && (rev)) { const char* _p = (ptr) - ((half) ? hstepA : 0); PG8_STAGE(bufoff, _p, voffAr); } else { const char* _p = (ptr) + ((half) ? hstepA : 0); PG8_STAGE(bufoff, _p, voffA); } } while (0)
; #define PG8_LDA(dst, b, h) do { _Pragma("unroll") for (int m = 0; m < 4; ++m) _Pragma("unroll") for (int k = 0; k < 2; ++k) dst[m][k] = *(const LAS bf16x8*)(lds + PG8_SA(b, h) + aoff + m * 2048 + k * 1024); } while (0)
; #define PG8_LDB(dst, b, h) do { _Pragma("unroll") for (int n = 0; n < 2; ++n) _Pragma("unroll") for (int k = 0; k < 2; ++k) dst[n][k] = *(const LAS bf16x8*)(lds + PG8_SB(b, h) + boff + n * 2048 + k * 1024); } while (0)
; #define PG8_WAIT_L(n) asm volatile("s_waitcnt lgkmcnt(" #n ")" ::: "memory")
; #define PG8_BAR __builtin_amdgcn_s_barrier()
; #define PG8_SCHED __builtin_amdgcn_sched_barrier(0)
;     ...
;     for (;;) {
;         const bool has_next = next_unit(ui + 1, nM, nN, MP, nxt, rot);
;         const char* nA = has_next ? nxt.a : cA; const char* nB = has_next ? nxt.b : cB; const char* nAr = has_next ? nxt.ar : cAr; const size_t nHb = has_next ? nxt.hb : cHb;
;         for (int t = 0; t < nt; t += 2) {
;             const bool last = (t == nt - 2);
;             const char* a1 = PG8_APTR(cA, cAr, t + 1); const bool r1 = REVA && ((t + 1) & 4);
;             const char* a2 = last ? nA : PG8_APTR(cA, cAr, t + 2); const bool r2 = REVA && !last && ((t + 2) & 4);
;             const char* a3 = last ? nA + kstep : PG8_APTR(cA, cAr, t + 3); const bool r3 = REVA && !last && ((t + 3) & 4);
;             const char* b2 = last ? nB : cB + (size_t)(t + 2) * kstep; const char* b3 = b2 + kstep; const size_t hb2 = last ? nHb : cHb;
;             PG8_LDB(B0, 0, 0); PG8_SCHED; PG8_LDA(At, 0, 0); PG8_STAGE_A(PG8_SA(1, 1), a1, 1, r1);
;             PG8_WAIT_L(8); PG8_BAR; PG8_WAIT_L(0); PG8_MMA(0, 0, At, B0); PG8_BAR; PG8_SCHED;
;     ...
; #pragma unroll
;         for (int a = 0; a < 2; ++a)
; #pragma unroll
;             for (int b = 0; b < 2; ++b)
; #pragma unroll
;                 for (int m = 0; m < 4; ++m)
; #pragma unroll
;                     for (int n = 0; n < 2; ++n) acc[a][b][m][n] = (f32x4){0.f, 0.f, 0.f, 0.f};
;         cur = nxt; cA = nA; cB = nB; cAr = nAr; cHb = nHb; ++ui;
.LBB0_1131:
	s_add_u32 s6, s78, 0x80
	s_addc_u32 s7, s79, 0
	s_add_u32 s8, s0, 0x80080
	s_addc_u32 s9, s1, 0
	v_lshl_add_u64 v[96:97], s[8:9], 0, v[176:177]
	v_lshl_add_u64 v[98:99], s[8:9], 0, v[178:179]
	s_add_u32 s8, s2, 0x100
	v_mov_b32_e32 v0, 0
	s_addc_u32 s9, s3, 0
	s_mov_b32 s26, -2
	s_mov_b64 s[2:3], 0
	v_mov_b32_e32 v1, v0
	v_mov_b32_e32 v2, v0
	v_mov_b32_e32 v3, v0
	v_mov_b32_e32 v4, v0
	v_mov_b32_e32 v5, v0
	v_mov_b32_e32 v6, v0
	v_mov_b32_e32 v7, v0
	v_mov_b32_e32 v16, v0
	v_mov_b32_e32 v17, v0
	v_mov_b32_e32 v18, v0
	v_mov_b32_e32 v19, v0
	v_mov_b32_e32 v20, v0
	v_mov_b32_e32 v21, v0
	v_mov_b32_e32 v22, v0
	v_mov_b32_e32 v23, v0
	v_mov_b32_e32 v32, v0
	v_mov_b32_e32 v33, v0
	v_mov_b32_e32 v34, v0
	v_mov_b32_e32 v35, v0
	v_mov_b32_e32 v36, v0
	v_mov_b32_e32 v37, v0
	v_mov_b32_e32 v38, v0
	v_mov_b32_e32 v39, v0
	v_mov_b32_e32 v48, v0
	v_mov_b32_e32 v49, v0
	v_mov_b32_e32 v50, v0
	v_mov_b32_e32 v51, v0
	v_mov_b32_e32 v52, v0
	v_mov_b32_e32 v53, v0
	v_mov_b32_e32 v54, v0
	v_mov_b32_e32 v55, v0
	v_mov_b32_e32 v8, v0
	v_mov_b32_e32 v9, v0
	v_mov_b32_e32 v10, v0
	v_mov_b32_e32 v11, v0
	v_mov_b32_e32 v12, v0
	v_mov_b32_e32 v13, v0
	v_mov_b32_e32 v14, v0
	v_mov_b32_e32 v15, v0
	v_mov_b32_e32 v24, v0
	v_mov_b32_e32 v25, v0
	v_mov_b32_e32 v26, v0
	v_mov_b32_e32 v27, v0
	v_mov_b32_e32 v28, v0
	v_mov_b32_e32 v29, v0
	v_mov_b32_e32 v30, v0
	v_mov_b32_e32 v31, v0
	v_mov_b32_e32 v40, v0
	v_mov_b32_e32 v41, v0
	v_mov_b32_e32 v42, v0
	v_mov_b32_e32 v43, v0
	v_mov_b32_e32 v44, v0
	v_mov_b32_e32 v45, v0
	v_mov_b32_e32 v46, v0
	v_mov_b32_e32 v47, v0
	v_mov_b32_e32 v56, v0
	v_mov_b32_e32 v57, v0
	v_mov_b32_e32 v58, v0
	v_mov_b32_e32 v59, v0
	v_mov_b32_e32 v60, v0
	v_mov_b32_e32 v61, v0
	v_mov_b32_e32 v62, v0
	v_mov_b32_e32 v63, v0
	v_mov_b32_e32 v64, v0
	v_mov_b32_e32 v65, v0
	v_mov_b32_e32 v66, v0
	v_mov_b32_e32 v67, v0
	v_mov_b32_e32 v68, v0
	v_mov_b32_e32 v69, v0
	v_mov_b32_e32 v70, v0
	v_mov_b32_e32 v71, v0
	v_mov_b32_e32 v80, v0
	v_mov_b32_e32 v81, v0
	v_mov_b32_e32 v82, v0
	v_mov_b32_e32 v83, v0
	v_mov_b32_e32 v84, v0
	v_mov_b32_e32 v85, v0
	v_mov_b32_e32 v86, v0
	v_mov_b32_e32 v87, v0
	v_mov_b32_e32 v100, v0
	v_mov_b32_e32 v101, v0
	v_mov_b32_e32 v102, v0
	v_mov_b32_e32 v103, v0
	v_mov_b32_e32 v104, v0
	v_mov_b32_e32 v105, v0
	v_mov_b32_e32 v106, v0
	v_mov_b32_e32 v107, v0
	v_mov_b32_e32 v124, v0
	v_mov_b32_e32 v125, v0
	v_mov_b32_e32 v126, v0
	v_mov_b32_e32 v127, v0
	v_mov_b32_e32 v128, v0
	v_mov_b32_e32 v129, v0
	v_mov_b32_e32 v130, v0
	v_mov_b32_e32 v131, v0
	v_mov_b32_e32 v72, v0
	v_mov_b32_e32 v73, v0
	v_mov_b32_e32 v74, v0
	v_mov_b32_e32 v75, v0
	v_mov_b32_e32 v76, v0
	v_mov_b32_e32 v77, v0
	v_mov_b32_e32 v78, v0
	v_mov_b32_e32 v79, v0
	v_mov_b32_e32 v88, v0
	v_mov_b32_e32 v89, v0
	v_mov_b32_e32 v90, v0
	v_mov_b32_e32 v91, v0
	v_mov_b32_e32 v92, v0
	v_mov_b32_e32 v93, v0
	v_mov_b32_e32 v94, v0
	v_mov_b32_e32 v95, v0
	v_mov_b32_e32 v112, v0
	v_mov_b32_e32 v113, v0
	v_mov_b32_e32 v114, v0
	v_mov_b32_e32 v115, v0
	v_mov_b32_e32 v116, v0
	v_mov_b32_e32 v117, v0
	v_mov_b32_e32 v118, v0
	v_mov_b32_e32 v119, v0
	v_mov_b32_e32 v136, v0
	v_mov_b32_e32 v137, v0
	v_mov_b32_e32 v138, v0
	v_mov_b32_e32 v139, v0
	v_mov_b32_e32 v144, v0
	v_mov_b32_e32 v145, v0
	v_mov_b32_e32 v146, v0
	v_mov_b32_e32 v147, v0
	v_add_u32_e32 v140, 0x10000, v205
	ds_read_b128 v[108:111], v140
	ds_read_b128 v[120:123], v140 offset:1024
	ds_read_b128 v[132:135], v140 offset:2048
	ds_read_b128 v[140:143], v140 offset:3072
.LBB0_1132:
	s_add_u32 s10, s0, s2
	s_addc_u32 s11, s1, s3
	s_add_u32 s16, s10, 0x100
	s_addc_u32 s17, s11, 0
	s_add_u32 s10, s10, 0x180
	s_addc_u32 s11, s11, 0
	s_add_u32 s14, s8, s2
	s_addc_u32 s15, s9, s3
	s_add_i32 s27, 0, 0x10000
	s_cmpk_eq_i32 s2, 0xf00
	s_cselect_b32 s15, s25, s15
	s_cselect_b32 s14, s24, s14
	s_cselect_b32 s21, s79, s17
	s_cselect_b32 s20, s78, s16
	s_cselect_b32 s17, s7, s11
	s_cselect_b32 s16, s6, s10
	v_lshl_add_u64 v[184:185], v[96:97], 0, s[2:3]
	s_add_i32 m0, s70, 0xc000
	ds_read_b128 v[148:151], v209
	ds_read_b128 v[152:155], v209 offset:1024
	ds_read_b128 v[156:159], v209 offset:2048
	ds_read_b128 v[180:183], v209 offset:3072
	ds_read_b128 v[210:213], v209 offset:4096
	ds_read_b128 v[214:217], v209 offset:5120
	ds_read_b128 v[218:221], v209 offset:6144
	ds_read_b128 v[222:225], v209 offset:7168
	global_load_lds_dwordx4 v[184:185], off
	v_lshl_add_u64 v[184:185], v[98:99], 0, s[2:3]
	s_add_i32 m0, s70, 0xe000
	s_nop 0
	global_load_lds_dwordx4 v[184:185], off
	s_waitcnt lgkmcnt(8)
	s_barrier
	s_waitcnt lgkmcnt(0)
	s_setprio 1
	s_waitcnt lgkmcnt(0)
	v_mfma_f32_16x16x32_bf16 v[144:147], v[108:111], v[148:151], v[144:147]
	v_mfma_f32_16x16x32_bf16 v[136:139], v[132:135], v[148:151], v[136:139]
	v_mfma_f32_16x16x32_bf16 v[116:119], v[108:111], v[156:159], v[116:119]
	v_mfma_f32_16x16x32_bf16 v[112:115], v[132:135], v[156:159], v[112:115]
	v_mfma_f32_16x16x32_bf16 v[92:95], v[108:111], v[210:213], v[92:95]
	v_mfma_f32_16x16x32_bf16 v[88:91], v[132:135], v[210:213], v[88:91]
	v_mfma_f32_16x16x32_bf16 v[76:79], v[108:111], v[218:221], v[76:79]
	v_mfma_f32_16x16x32_bf16 v[72:75], v[132:135], v[218:221], v[72:75]
	v_mfma_f32_16x16x32_bf16 v[144:147], v[120:123], v[152:155], v[144:147]
	v_mfma_f32_16x16x32_bf16 v[136:139], v[140:143], v[152:155], v[136:139]
	v_mfma_f32_16x16x32_bf16 v[116:119], v[120:123], v[180:183], v[116:119]
	v_mfma_f32_16x16x32_bf16 v[112:115], v[140:143], v[180:183], v[112:115]
	v_mfma_f32_16x16x32_bf16 v[92:95], v[120:123], v[214:217], v[92:95]
	v_mfma_f32_16x16x32_bf16 v[88:91], v[140:143], v[214:217], v[88:91]
	v_mfma_f32_16x16x32_bf16 v[76:79], v[120:123], v[222:225], v[76:79]
	v_mfma_f32_16x16x32_bf16 v[72:75], v[140:143], v[222:225], v[72:75]
	s_setprio 0
	s_barrier
; #define PG8_STAGE(bufoff, gbase, voff) do { _Pragma("unroll") for (int _i = 0; _i < 2; ++_i) \
;         __builtin_amdgcn_global_load_lds((const unsigned*)((const char*)(gbase) + (voff)[_i]), (LAS unsigned*)(lds + (bufoff) + ldsw + _i * 8192), 16, 0, 0); } while (0)
; #define PG8_STAGE_A(bufoff, ptr, half, rev) do { if (REVA && (rev)) { const char* _p = (ptr) - ((half) ? hstepA : 0); PG8_STAGE(bufoff, _p, voffAr); } else { const char* _p = (ptr) + ((half) ? hstepA : 0); PG8_STAGE(bufoff, _p, voffA); } } while (0)
; #define PG8_LDA(dst, b, h) do { _Pragma("unroll") for (int m = 0; m < 4; ++m) _Pragma("unroll") for (int k = 0; k < 2; ++k) dst[m][k] = *(const LAS bf16x8*)(lds + PG8_SA(b, h) + aoff + m * 2048 + k * 1024); } while (0)
; #define PG8_LDB(dst, b, h) do { _Pragma("unroll") for (int n = 0; n < 2; ++n) _Pragma("unroll") for (int k = 0; k < 2; ++k) dst[n][k] = *(const LAS bf16x8*)(lds + PG8_SB(b, h) + boff + n * 2048 + k * 1024); } while (0)
; #define PG8_MMA(ai, bj, At, Bt) do { __builtin_amdgcn_s_setprio(1); _Pragma("unroll") for (int m = 0; m < 4; ++m) _Pragma("unroll") for (int n = 0; n < 2; ++n) _Pragma("unroll") for (int k = 0; k < 2; ++k) \
;         acc[ai][bj][m][n] = __builtin_amdgcn_mfma_f32_16x16x32_bf16(Bt[n][k], At[m][k], acc[ai][bj][m][n], 0, 0, 0); __builtin_amdgcn_s_setprio(0); } while (0)
; #define PG8_WAIT_V(n) asm volatile("s_waitcnt vmcnt(" #n ")" ::: "memory")
; #define PG8_WAIT_L(n) asm volatile("s_waitcnt lgkmcnt(" #n ")" ::: "memory")
; #define PG8_BAR __builtin_amdgcn_s_barrier()
; #define PG8_SCHED __builtin_amdgcn_sched_barrier(0)
;     ...
;             PG8_LDB(B1, 0, 1); PG8_STAGE(PG8_SB(0, 0), b2, voffB);
;             PG8_BAR; PG8_WAIT_L(0); PG8_MMA(0, 1, At, B1); PG8_BAR;
;             PG8_LDA(At, 0, 1); PG8_STAGE_A(PG8_SA(0, 0), a2, 0, r2);
;             PG8_BAR; PG8_WAIT_L(0); PG8_MMA(1, 0, At, B0); PG8_BAR; PG8_SCHED;
;             PG8_STAGE(PG8_SB(0, 1), b2 + hb2, voffB);
;             PG8_WAIT_V(6); PG8_BAR; PG8_MMA(1, 1, At, B1); PG8_BAR;
;             PG8_LDB(B0, 1, 0); PG8_SCHED; PG8_LDA(At, 1, 0); PG8_STAGE_A(PG8_SA(0, 1), a2, 1, r2);
;             PG8_WAIT_L(8); PG8_BAR; PG8_WAIT_L(0); PG8_MMA(0, 0, At, B0); PG8_BAR; PG8_SCHED;
	s_add_i32 s10, 0, 0x14000
	v_add_u32_e32 v184, s10, v205
	s_add_i32 s11, s27, s69
	ds_read_b128 v[226:229], v184
	ds_read_b128 v[230:233], v184 offset:1024
	ds_read_b128 v[234:237], v184 offset:2048
	ds_read_b128 v[238:241], v184 offset:3072
	v_lshl_add_u64 v[184:185], s[14:15], 0, v[172:173]
	s_mov_b32 m0, s11
	v_lshl_add_u64 v[190:191], s[14:15], 0, v[168:169]
	global_load_lds_dwordx4 v[184:185], off
	s_add_i32 m0, s11, 0x2000
	s_nop 0
	global_load_lds_dwordx4 v[190:191], off
	s_barrier
	s_waitcnt lgkmcnt(0)
	s_setprio 1
	s_waitcnt lgkmcnt(0)
	v_mfma_f32_16x16x32_bf16 v[128:131], v[226:229], v[148:151], v[128:131]
	v_mfma_f32_16x16x32_bf16 v[124:127], v[234:237], v[148:151], v[124:127]
	v_mfma_f32_16x16x32_bf16 v[104:107], v[226:229], v[156:159], v[104:107]
	v_mfma_f32_16x16x32_bf16 v[100:103], v[234:237], v[156:159], v[100:103]
	v_mfma_f32_16x16x32_bf16 v[84:87], v[226:229], v[210:213], v[84:87]
	v_mfma_f32_16x16x32_bf16 v[80:83], v[234:237], v[210:213], v[80:83]
	v_mfma_f32_16x16x32_bf16 v[68:71], v[226:229], v[218:221], v[68:71]
	v_mfma_f32_16x16x32_bf16 v[64:67], v[234:237], v[218:221], v[64:67]
	v_mfma_f32_16x16x32_bf16 v[128:131], v[230:233], v[152:155], v[128:131]
	v_mfma_f32_16x16x32_bf16 v[124:127], v[238:241], v[152:155], v[124:127]
	v_mfma_f32_16x16x32_bf16 v[104:107], v[230:233], v[180:183], v[104:107]
	v_mfma_f32_16x16x32_bf16 v[100:103], v[238:241], v[180:183], v[100:103]
	v_mfma_f32_16x16x32_bf16 v[84:87], v[230:233], v[214:217], v[84:87]
	v_mfma_f32_16x16x32_bf16 v[80:83], v[238:241], v[214:217], v[80:83]
	v_mfma_f32_16x16x32_bf16 v[68:71], v[230:233], v[222:225], v[68:71]
	v_mfma_f32_16x16x32_bf16 v[64:67], v[238:241], v[222:225], v[64:67]
	s_setprio 0
	s_mov_b32 m0, s70
	v_lshl_add_u64 v[242:243], s[20:21], 0, v[174:175]
	s_barrier
	ds_read_b128 v[148:151], v209 offset:16384
	ds_read_b128 v[152:155], v209 offset:17408
	ds_read_b128 v[156:159], v209 offset:18432
	ds_read_b128 v[180:183], v209 offset:19456
	ds_read_b128 v[210:213], v209 offset:20480
	ds_read_b128 v[214:217], v209 offset:21504
	ds_read_b128 v[218:221], v209 offset:22528
	ds_read_b128 v[222:225], v209 offset:23552
	global_load_lds_dwordx4 v[242:243], off
	v_lshl_add_u64 v[242:243], s[20:21], 0, v[170:171]
	s_mov_b32 m0, s71
	s_nop 0
	global_load_lds_dwordx4 v[242:243], off
	s_waitcnt vmcnt(10)
	s_barrier
	s_waitcnt lgkmcnt(0)
	s_setprio 1
	s_waitcnt lgkmcnt(0)
	v_mfma_f32_16x16x32_bf16 v[60:63], v[108:111], v[148:151], v[60:63]
	v_mfma_f32_16x16x32_bf16 v[56:59], v[132:135], v[148:151], v[56:59]
	v_mfma_f32_16x16x32_bf16 v[44:47], v[108:111], v[156:159], v[44:47]
	v_mfma_f32_16x16x32_bf16 v[40:43], v[132:135], v[156:159], v[40:43]
	v_mfma_f32_16x16x32_bf16 v[28:31], v[108:111], v[210:213], v[28:31]
	v_mfma_f32_16x16x32_bf16 v[24:27], v[132:135], v[210:213], v[24:27]
	v_mfma_f32_16x16x32_bf16 v[12:15], v[108:111], v[218:221], v[12:15]
	v_mfma_f32_16x16x32_bf16 v[8:11], v[132:135], v[218:221], v[8:11]
	v_mfma_f32_16x16x32_bf16 v[60:63], v[120:123], v[152:155], v[60:63]
	v_mfma_f32_16x16x32_bf16 v[56:59], v[140:143], v[152:155], v[56:59]
	v_mfma_f32_16x16x32_bf16 v[44:47], v[120:123], v[180:183], v[44:47]
	v_mfma_f32_16x16x32_bf16 v[40:43], v[140:143], v[180:183], v[40:43]
	v_mfma_f32_16x16x32_bf16 v[28:31], v[120:123], v[214:217], v[28:31]
	v_mfma_f32_16x16x32_bf16 v[24:27], v[140:143], v[214:217], v[24:27]
	v_mfma_f32_16x16x32_bf16 v[12:15], v[120:123], v[222:225], v[12:15]
	v_mfma_f32_16x16x32_bf16 v[8:11], v[140:143], v[222:225], v[8:11]
	s_setprio 0
	s_barrier
	s_add_u32 s36, s14, 0x80000
	s_addc_u32 s37, s15, 0
	s_add_i32 s10, s10, s69
	v_lshl_add_u64 v[108:109], s[36:37], 0, v[172:173]
	s_mov_b32 m0, s10
	s_nop 0
	global_load_lds_dwordx4 v[108:109], off
	v_lshl_add_u64 v[108:109], s[36:37], 0, v[168:169]
	s_add_i32 m0, s10, 0x2000
	s_nop 0
	global_load_lds_dwordx4 v[108:109], off
	v_add_u32_e32 v140, 0x18000, v205
	ds_read_b128 v[108:111], v140
	ds_read_b128 v[120:123], v140 offset:1024
	ds_read_b128 v[132:135], v140 offset:2048
	ds_read_b128 v[140:143], v140 offset:3072
	s_waitcnt vmcnt(6)
	s_barrier
	s_setprio 1
	v_mfma_f32_16x16x32_bf16 v[52:55], v[226:229], v[148:151], v[52:55]
	v_mfma_f32_16x16x32_bf16 v[48:51], v[234:237], v[148:151], v[48:51]
	v_mfma_f32_16x16x32_bf16 v[36:39], v[226:229], v[156:159], v[36:39]
	v_mfma_f32_16x16x32_bf16 v[32:35], v[234:237], v[156:159], v[32:35]
	v_mfma_f32_16x16x32_bf16 v[20:23], v[226:229], v[210:213], v[20:23]
	v_mfma_f32_16x16x32_bf16 v[16:19], v[234:237], v[210:213], v[16:19]
	v_mfma_f32_16x16x32_bf16 v[4:7], v[226:229], v[218:221], v[4:7]
	v_mfma_f32_16x16x32_bf16 v[0:3], v[234:237], v[218:221], v[0:3]
	v_mfma_f32_16x16x32_bf16 v[52:55], v[230:233], v[152:155], v[52:55]
	v_mfma_f32_16x16x32_bf16 v[48:51], v[238:241], v[152:155], v[48:51]
	v_mfma_f32_16x16x32_bf16 v[36:39], v[230:233], v[180:183], v[36:39]
	v_mfma_f32_16x16x32_bf16 v[32:35], v[238:241], v[180:183], v[32:35]
	v_mfma_f32_16x16x32_bf16 v[20:23], v[230:233], v[214:217], v[20:23]
	v_mfma_f32_16x16x32_bf16 v[16:19], v[238:241], v[214:217], v[16:19]
	v_mfma_f32_16x16x32_bf16 v[4:7], v[230:233], v[222:225], v[4:7]
	v_mfma_f32_16x16x32_bf16 v[0:3], v[238:241], v[222:225], v[0:3]
	s_setprio 0
	s_add_i32 s10, 0, 0x18000
	s_barrier
	s_add_u32 s20, s20, 0x80000
	s_addc_u32 s21, s21, 0
	s_mov_b32 m0, s89
	v_lshl_add_u64 v[226:227], s[20:21], 0, v[174:175]
	ds_read_b128 v[148:151], v209 offset:32768
	ds_read_b128 v[152:155], v209 offset:33792
	ds_read_b128 v[156:159], v209 offset:34816
	ds_read_b128 v[180:183], v209 offset:35840
	ds_read_b128 v[210:213], v209 offset:36864
	ds_read_b128 v[214:217], v209 offset:37888
	ds_read_b128 v[218:221], v209 offset:38912
	ds_read_b128 v[222:225], v209 offset:39936
	global_load_lds_dwordx4 v[226:227], off
	v_lshl_add_u64 v[226:227], s[20:21], 0, v[170:171]
	s_mov_b32 m0, s90
	s_nop 0
	global_load_lds_dwordx4 v[226:227], off
	s_waitcnt lgkmcnt(8)
	s_barrier
; #define PG8_STAGE(bufoff, gbase, voff) do { _Pragma("unroll") for (int _i = 0; _i < 2; ++_i) \
;         __builtin_amdgcn_global_load_lds((const unsigned*)((const char*)(gbase) + (voff)[_i]), (LAS unsigned*)(lds + (bufoff) + ldsw + _i * 8192), 16, 0, 0); } while (0)
; #define PG8_STAGE_A(bufoff, ptr, half, rev) do { if (REVA && (rev)) { const char* _p = (ptr) - ((half) ? hstepA : 0); PG8_STAGE(bufoff, _p, voffAr); } else { const char* _p = (ptr) + ((half) ? hstepA : 0); PG8_STAGE(bufoff, _p, voffA); } } while (0)
; #define PG8_LDA(dst, b, h) do { _Pragma("unroll") for (int m = 0; m < 4; ++m) _Pragma("unroll") for (int k = 0; k < 2; ++k) dst[m][k] = *(const LAS bf16x8*)(lds + PG8_SA(b, h) + aoff + m * 2048 + k * 1024); } while (0)
; #define PG8_LDB(dst, b, h) do { _Pragma("unroll") for (int n = 0; n < 2; ++n) _Pragma("unroll") for (int k = 0; k < 2; ++k) dst[n][k] = *(const LAS bf16x8*)(lds + PG8_SB(b, h) + boff + n * 2048 + k * 1024); } while (0)
; #define PG8_MMA(ai, bj, At, Bt) do { __builtin_amdgcn_s_setprio(1); _Pragma("unroll") for (int m = 0; m < 4; ++m) _Pragma("unroll") for (int n = 0; n < 2; ++n) _Pragma("unroll") for (int k = 0; k < 2; ++k) \
;         acc[ai][bj][m][n] = __builtin_amdgcn_mfma_f32_16x16x32_bf16(Bt[n][k], At[m][k], acc[ai][bj][m][n], 0, 0, 0); __builtin_amdgcn_s_setprio(0); } while (0)
; #define PG8_WAIT_L(n) asm volatile("s_waitcnt lgkmcnt(" #n ")" ::: "memory")
; #define PG8_BAR __builtin_amdgcn_s_barrier()
; #define PG8_SCHED __builtin_amdgcn_sched_barrier(0)
;     ...
;             PG8_WAIT_L(8); PG8_BAR; PG8_WAIT_L(0); PG8_MMA(0, 0, At, B0); PG8_BAR; PG8_SCHED;
;             PG8_LDB(B1, 1, 1); PG8_STAGE(PG8_SB(1, 0), b3, voffB);
;             PG8_BAR; PG8_WAIT_L(0); PG8_MMA(0, 1, At, B1); PG8_BAR;
;             PG8_LDA(At, 1, 1); PG8_STAGE_A(PG8_SA(1, 0), a3, 0, r3);
;             PG8_BAR; PG8_WAIT_L(0); PG8_MMA(1, 0, At, B0); PG8_BAR; PG8_SCHED;
	s_waitcnt lgkmcnt(0)
	s_setprio 1
	s_waitcnt lgkmcnt(0)
	v_mfma_f32_16x16x32_bf16 v[144:147], v[108:111], v[148:151], v[144:147]
	v_mfma_f32_16x16x32_bf16 v[136:139], v[132:135], v[148:151], v[136:139]
	v_mfma_f32_16x16x32_bf16 v[116:119], v[108:111], v[156:159], v[116:119]
	v_mfma_f32_16x16x32_bf16 v[112:115], v[132:135], v[156:159], v[112:115]
	v_mfma_f32_16x16x32_bf16 v[92:95], v[108:111], v[210:213], v[92:95]
	v_mfma_f32_16x16x32_bf16 v[88:91], v[132:135], v[210:213], v[88:91]
	v_mfma_f32_16x16x32_bf16 v[76:79], v[108:111], v[218:221], v[76:79]
	v_mfma_f32_16x16x32_bf16 v[72:75], v[132:135], v[218:221], v[72:75]
	v_mfma_f32_16x16x32_bf16 v[144:147], v[120:123], v[152:155], v[144:147]
	v_mfma_f32_16x16x32_bf16 v[136:139], v[140:143], v[152:155], v[136:139]
	v_mfma_f32_16x16x32_bf16 v[116:119], v[120:123], v[180:183], v[116:119]
	v_mfma_f32_16x16x32_bf16 v[112:115], v[140:143], v[180:183], v[112:115]
	v_mfma_f32_16x16x32_bf16 v[92:95], v[120:123], v[214:217], v[92:95]
	v_mfma_f32_16x16x32_bf16 v[88:91], v[140:143], v[214:217], v[88:91]
	v_mfma_f32_16x16x32_bf16 v[76:79], v[120:123], v[222:225], v[76:79]
	v_mfma_f32_16x16x32_bf16 v[72:75], v[140:143], v[222:225], v[72:75]
	s_setprio 0
	s_barrier
	s_add_i32 s11, 0, 0x1c000
	s_add_i32 s10, s10, s69
	v_add_u32_e32 v238, s11, v205
	v_lshl_add_u64 v[184:185], v[184:185], 0, s[28:29]
	s_mov_b32 m0, s10
	ds_read_b128 v[226:229], v238
	ds_read_b128 v[230:233], v238 offset:1024
	ds_read_b128 v[234:237], v238 offset:2048
	ds_read_b128 v[238:241], v238 offset:3072
	global_load_lds_dwordx4 v[184:185], off
	v_lshl_add_u64 v[184:185], v[190:191], 0, s[28:29]
	s_add_i32 m0, s10, 0x2000
	s_nop 0
	global_load_lds_dwordx4 v[184:185], off
	s_barrier
	s_waitcnt lgkmcnt(0)
	s_setprio 1
	s_waitcnt lgkmcnt(0)
	v_mfma_f32_16x16x32_bf16 v[128:131], v[226:229], v[148:151], v[128:131]
	v_mfma_f32_16x16x32_bf16 v[124:127], v[234:237], v[148:151], v[124:127]
	v_mfma_f32_16x16x32_bf16 v[104:107], v[226:229], v[156:159], v[104:107]
	v_mfma_f32_16x16x32_bf16 v[100:103], v[234:237], v[156:159], v[100:103]
	v_mfma_f32_16x16x32_bf16 v[84:87], v[226:229], v[210:213], v[84:87]
	v_mfma_f32_16x16x32_bf16 v[80:83], v[234:237], v[210:213], v[80:83]
	v_mfma_f32_16x16x32_bf16 v[68:71], v[226:229], v[218:221], v[68:71]
	v_mfma_f32_16x16x32_bf16 v[64:67], v[234:237], v[218:221], v[64:67]
	v_mfma_f32_16x16x32_bf16 v[128:131], v[230:233], v[152:155], v[128:131]
	v_mfma_f32_16x16x32_bf16 v[124:127], v[238:241], v[152:155], v[124:127]
	v_mfma_f32_16x16x32_bf16 v[104:107], v[230:233], v[180:183], v[104:107]
	v_mfma_f32_16x16x32_bf16 v[100:103], v[238:241], v[180:183], v[100:103]
	v_mfma_f32_16x16x32_bf16 v[84:87], v[230:233], v[214:217], v[84:87]
	v_mfma_f32_16x16x32_bf16 v[80:83], v[238:241], v[214:217], v[80:83]
	v_mfma_f32_16x16x32_bf16 v[68:71], v[230:233], v[222:225], v[68:71]
	v_mfma_f32_16x16x32_bf16 v[64:67], v[238:241], v[222:225], v[64:67]
	s_setprio 0
	s_mov_b32 m0, s97
	v_lshl_add_u64 v[184:185], s[16:17], 0, v[174:175]
	s_barrier
	ds_read_b128 v[148:151], v209 offset:49152
	ds_read_b128 v[152:155], v209 offset:50176
	ds_read_b128 v[156:159], v209 offset:51200
	ds_read_b128 v[180:183], v209 offset:52224
	ds_read_b128 v[210:213], v209 offset:53248
	ds_read_b128 v[214:217], v209 offset:54272
	ds_read_b128 v[218:221], v209 offset:55296
	ds_read_b128 v[222:225], v209 offset:56320
	global_load_lds_dwordx4 v[184:185], off
	v_lshl_add_u64 v[184:185], s[16:17], 0, v[170:171]
	s_mov_b32 m0, s52
	s_nop 0
	global_load_lds_dwordx4 v[184:185], off
	s_waitcnt vmcnt(10)
	s_barrier
; #define PG8_STAGE(bufoff, gbase, voff) do { _Pragma("unroll") for (int _i = 0; _i < 2; ++_i) \
;         __builtin_amdgcn_global_load_lds((const unsigned*)((const char*)(gbase) + (voff)[_i]), (LAS unsigned*)(lds + (bufoff) + ldsw + _i * 8192), 16, 0, 0); } while (0)
; #define PG8_MMA(ai, bj, At, Bt) do { __builtin_amdgcn_s_setprio(1); _Pragma("unroll") for (int m = 0; m < 4; ++m) _Pragma("unroll") for (int n = 0; n < 2; ++n) _Pragma("unroll") for (int k = 0; k < 2; ++k) \
;         acc[ai][bj][m][n] = __builtin_amdgcn_mfma_f32_16x16x32_bf16(Bt[n][k], At[m][k], acc[ai][bj][m][n], 0, 0, 0); __builtin_amdgcn_s_setprio(0); } while (0)
; #define PG8_WAIT_V(n) asm volatile("s_waitcnt vmcnt(" #n ")" ::: "memory")
; #define PG8_WAIT_L(n) asm volatile("s_waitcnt lgkmcnt(" #n ")" ::: "memory")
; #define PG8_BAR __builtin_amdgcn_s_barrier()
; #define PG8_SCHED __builtin_amdgcn_sched_barrier(0)
;     ...
;             PG8_BAR; PG8_WAIT_L(0); PG8_MMA(1, 0, At, B0); PG8_BAR; PG8_SCHED;
;             PG8_STAGE(PG8_SB(1, 1), b3 + hb2, voffB);
;             PG8_WAIT_V(6); PG8_BAR; PG8_MMA(1, 1, At, B1); PG8_BAR;
;     __device__ __forceinline__ void gates(const f32x4 (&acc)[2][2][4][2], const Unit& u, int wr, int wc, int fr, int fq) const {
;         const bool ret = u.pn < 8;
;         const bf16_t* mulp = ret ? (OFp + u.pn * BM) : (Y + (u.pn - 8) * BM);
; #pragma unroll
;         for (int ai = 0; ai < 2; ++ai) {
;             u32x4 yv[4][2]; float rs[4];
; #pragma unroll
;             for (int m = 0; m < 4; ++m) {
;                 const size_t row = (size_t)(u.pm * BM + ai * HALF + wr * 64 + m * 16 + fr);
; #pragma unroll
;                 for (int bj = 0; bj < 2; ++bj) yv[m][bj] = *(const u32x4*)(mulp + row * 2048 + bj * HALF + wc * 32 + 8 * fq);
;                 rs[m] = 1.0f;
;                 if (ret) { const f32x4 sq = *(const f32x4*)(SSp + row * 32 + u.pn * 4); rs[m] = rsqrtf((sq[0] + sq[1] + sq[2] + sq[3]) * (1.0f / 256.0f) + 1e-6f); }
;             }
	s_waitcnt lgkmcnt(0)
	s_setprio 1
	s_waitcnt lgkmcnt(0)
	v_mfma_f32_16x16x32_bf16 v[60:63], v[108:111], v[148:151], v[60:63]
	v_mfma_f32_16x16x32_bf16 v[56:59], v[132:135], v[148:151], v[56:59]
	v_mfma_f32_16x16x32_bf16 v[44:47], v[108:111], v[156:159], v[44:47]
	v_mfma_f32_16x16x32_bf16 v[40:43], v[132:135], v[156:159], v[40:43]
	v_mfma_f32_16x16x32_bf16 v[28:31], v[108:111], v[210:213], v[28:31]
	v_mfma_f32_16x16x32_bf16 v[24:27], v[132:135], v[210:213], v[24:27]
	v_mfma_f32_16x16x32_bf16 v[12:15], v[108:111], v[218:221], v[12:15]
	v_mfma_f32_16x16x32_bf16 v[8:11], v[132:135], v[218:221], v[8:11]
	v_mfma_f32_16x16x32_bf16 v[60:63], v[120:123], v[152:155], v[60:63]
	v_mfma_f32_16x16x32_bf16 v[56:59], v[140:143], v[152:155], v[56:59]
	v_mfma_f32_16x16x32_bf16 v[44:47], v[120:123], v[180:183], v[44:47]
	v_mfma_f32_16x16x32_bf16 v[40:43], v[140:143], v[180:183], v[40:43]
	v_mfma_f32_16x16x32_bf16 v[28:31], v[120:123], v[214:217], v[28:31]
	v_mfma_f32_16x16x32_bf16 v[24:27], v[140:143], v[214:217], v[24:27]
	v_mfma_f32_16x16x32_bf16 v[12:15], v[120:123], v[222:225], v[12:15]
	v_mfma_f32_16x16x32_bf16 v[8:11], v[140:143], v[222:225], v[8:11]
	s_setprio 0
	s_barrier
	s_add_u32 s14, s14, 0x80080
	s_addc_u32 s15, s15, 0
	s_add_i32 s10, s11, s69
	v_lshl_add_u64 v[108:109], s[14:15], 0, v[172:173]
	s_mov_b32 m0, s10
	s_nop 0
	global_load_lds_dwordx4 v[108:109], off
	v_lshl_add_u64 v[108:109], s[14:15], 0, v[168:169]
	s_add_i32 m0, s10, 0x2000
	s_nop 0
	global_load_lds_dwordx4 v[108:109], off
	v_add_u32_e32 v140, 0x10000, v205
	ds_read_b128 v[108:111], v140
	ds_read_b128 v[120:123], v140 offset:1024
	ds_read_b128 v[132:135], v140 offset:2048
	ds_read_b128 v[140:143], v140 offset:3072
	s_waitcnt vmcnt(6)
	s_barrier
	s_setprio 1
	v_mfma_f32_16x16x32_bf16 v[52:55], v[226:229], v[148:151], v[52:55]
	v_mfma_f32_16x16x32_bf16 v[48:51], v[234:237], v[148:151], v[48:51]
	v_mfma_f32_16x16x32_bf16 v[36:39], v[226:229], v[156:159], v[36:39]
	v_mfma_f32_16x16x32_bf16 v[32:35], v[234:237], v[156:159], v[32:35]
	v_mfma_f32_16x16x32_bf16 v[20:23], v[226:229], v[210:213], v[20:23]
	v_mfma_f32_16x16x32_bf16 v[16:19], v[234:237], v[210:213], v[16:19]
	v_mfma_f32_16x16x32_bf16 v[4:7], v[226:229], v[218:221], v[4:7]
	v_mfma_f32_16x16x32_bf16 v[0:3], v[234:237], v[218:221], v[0:3]
	v_mfma_f32_16x16x32_bf16 v[52:55], v[230:233], v[152:155], v[52:55]
	v_mfma_f32_16x16x32_bf16 v[48:51], v[238:241], v[152:155], v[48:51]
	v_mfma_f32_16x16x32_bf16 v[36:39], v[230:233], v[180:183], v[36:39]
	v_mfma_f32_16x16x32_bf16 v[32:35], v[238:241], v[180:183], v[32:35]
	v_mfma_f32_16x16x32_bf16 v[20:23], v[230:233], v[214:217], v[20:23]
	v_mfma_f32_16x16x32_bf16 v[16:19], v[238:241], v[214:217], v[16:19]
	v_mfma_f32_16x16x32_bf16 v[4:7], v[230:233], v[222:225], v[4:7]
	v_mfma_f32_16x16x32_bf16 v[0:3], v[238:241], v[222:225], v[0:3]
	s_setprio 0
	s_add_i32 s26, s26, 2
	s_add_u32 s2, s2, 0x100
	s_addc_u32 s3, s3, 0
	s_cmp_gt_u32 s26, 29
	s_barrier
	s_cbranch_scc0 .LBB0_1132
	s_waitcnt lgkmcnt(0)
	s_lshl_b32 s0, s4, 8
	s_ashr_i32 s1, s0, 31
	s_lshl_b64 s[26:27], s[0:1], 1
	s_add_u32 s6, s93, s26
	s_addc_u32 s7, s94, s27
	s_addk_i32 s0, 0xf800
	s_mov_b32 s1, s23
	s_lshl_b64 s[0:1], s[0:1], 1
	s_add_u32 s8, s91, s0
	s_addc_u32 s9, s92, s1
	s_cmp_lt_i32 s4, 8
	s_cselect_b64 s[0:1], -1, 0
	s_and_b64 s[2:3], s[0:1], exec
	s_cselect_b32 s3, s6, s8
	s_cselect_b32 s2, s7, s9
	s_add_u32 s6, s3, s22
	s_addc_u32 s7, s2, 0
	s_lshl_b32 s2, s5, 8
	v_add_u32_e32 v180, s2, v204
	v_ashrrev_i32_e32 v181, 31, v180
	v_lshl_add_u64 v[182:183], s[6:7], 0, v[160:161]
	v_lshlrev_b64 v[96:97], 12, v[180:181]
	v_lshl_add_u64 v[96:97], v[182:183], 0, v[96:97]
	global_load_dwordx4 v[156:159], v[96:97], off
	global_load_dwordx4 v[152:155], v[96:97], off offset:256
	s_lshl_b32 s6, s4, 2
	s_ashr_i32 s7, s6, 31
	s_lshl_b64 s[6:7], s[6:7], 2
	s_add_u32 s36, s95, s6
	s_addc_u32 s37, s96, s7
	s_cmp_gt_i32 s4, 7
	v_mov_b32_e32 v212, 1.0
	v_mov_b32_e32 v213, 1.0
	s_cbranch_scc1 .LBB0_1135
	v_lshlrev_b64 v[96:97], 7, v[180:181]
	v_lshl_add_u64 v[96:97], s[36:37], 0, v[96:97]
	global_load_dwordx4 v[96:99], v[96:97], off
	s_waitcnt vmcnt(0)
	v_add_f32_e32 v96, v96, v97
	v_add_f32_e32 v96, v98, v96
	v_add_f32_e32 v96, v99, v96
	v_fmamk_f32 v96, v96, 0x3b800000, v194
	v_mul_f32_e32 v97, 0x4b800000, v96
	v_cmp_gt_f32_e32 vcc, s55, v96
	s_nop 1
	v_cndmask_b32_e32 v96, v96, v97, vcc
	v_rsq_f32_e32 v96, v96
	s_nop 0
	v_mul_f32_e32 v97, 0x45800000, v96
	v_cndmask_b32_e32 v213, v96, v97, vcc

; #define PG8_STAGE_A(bufoff, ptr, half, rev) do { if (REVA && (rev)) { const char* _p = (ptr) - ((half) ? hstepA : 0); PG8_STAGE(bufoff, _p, voffAr); } else { const char* _p = (ptr) + ((half) ? hstepA : 0); PG8_STAGE(bufoff, _p, voffA); } } while (0)
; #define PG8_LDA(dst, b, h) do { _Pragma("unroll") for (int m = 0; m < 4; ++m) _Pragma("unroll") for (int k = 0; k < 2; ++k) dst[m][k] = *(const LAS bf16x8*)(lds + PG8_SA(b, h) + aoff + m * 2048 + k * 1024); } while (0)
; #define PG8_LDB(dst, b, h) do { _Pragma("unroll") for (int n = 0; n < 2; ++n) _Pragma("unroll") for (int k = 0; k < 2; ++k) dst[n][k] = *(const LAS bf16x8*)(lds + PG8_SB(b, h) + boff + n * 2048 + k * 1024); } while (0)
; #define PG8_WAIT_L(n) asm volatile("s_waitcnt lgkmcnt(" #n ")" ::: "memory")
; #define PG8_BAR __builtin_amdgcn_s_barrier()
; #define PG8_SCHED __builtin_amdgcn_sched_barrier(0)
;     ...
;     for (;;) {
;         const bool has_next = next_unit(ui + 1, nM, nN, MP, nxt, rot);
;         const char* nA = has_next ? nxt.a : cA; const char* nB = has_next ? nxt.b : cB; const char* nAr = has_next ? nxt.ar : cAr; const size_t nHb = has_next ? nxt.hb : cHb;
;         for (int t = 0; t < nt; t += 2) {
;             const bool last = (t == nt - 2);
;             const char* a1 = PG8_APTR(cA, cAr, t + 1); const bool r1 = REVA && ((t + 1) & 4);
;             const char* a2 = last ? nA : PG8_APTR(cA, cAr, t + 2); const bool r2 = REVA && !last && ((t + 2) & 4);
;             const char* a3 = last ? nA + kstep : PG8_APTR(cA, cAr, t + 3); const bool r3 = REVA && !last && ((t + 3) & 4);
;             const char* b2 = last ? nB : cB + (size_t)(t + 2) * kstep; const char* b3 = b2 + kstep; const size_t hb2 = last ? nHb : cHb;
;             PG8_LDB(B0, 0, 0); PG8_SCHED; PG8_LDA(At, 0, 0); PG8_STAGE_A(PG8_SA(1, 1), a1, 1, r1);
;             PG8_WAIT_L(8); PG8_BAR; PG8_WAIT_L(0); PG8_MMA(0, 0, At, B0); PG8_BAR; PG8_SCHED;
;     ...
; #pragma unroll
;         for (int a = 0; a < 2; ++a)
; #pragma unroll
;             for (int b = 0; b < 2; ++b)
; #pragma unroll
;                 for (int m = 0; m < 4; ++m)
; #pragma unroll
;                     for (int n = 0; n < 2; ++n) acc[a][b][m][n] = (f32x4){0.f, 0.f, 0.f, 0.f};
;         cur = nxt; cA = nA; cB = nB; cAr = nAr; cHb = nHb; ++ui;
.LBB0_1228:
	s_add_u32 s3, s36, 0x80
	s_addc_u32 s27, s37, 0
	s_add_u32 s14, s0, 0x100080
	s_addc_u32 s15, s1, 0
	s_add_u32 s69, s20, 0x100
	v_mov_b32_e32 v0, 0
	v_lshl_add_u64 v[128:129], s[14:15], 0, v[154:155]
	v_lshl_add_u64 v[130:131], s[14:15], 0, v[156:157]
	s_addc_u32 s70, s21, 0
	s_mov_b32 s71, -2
	s_mov_b64 s[42:43], 0
	v_mov_b32_e32 v1, v0
	v_mov_b32_e32 v2, v0
	v_mov_b32_e32 v3, v0
	v_mov_b32_e32 v4, v0
	v_mov_b32_e32 v5, v0
	v_mov_b32_e32 v6, v0
	v_mov_b32_e32 v7, v0
	v_mov_b32_e32 v12, v0
	v_mov_b32_e32 v13, v0
	v_mov_b32_e32 v14, v0
	v_mov_b32_e32 v15, v0
	v_mov_b32_e32 v16, v0
	v_mov_b32_e32 v17, v0
	v_mov_b32_e32 v18, v0
	v_mov_b32_e32 v19, v0
	v_mov_b32_e32 v32, v0
	v_mov_b32_e32 v33, v0
	v_mov_b32_e32 v34, v0
	v_mov_b32_e32 v35, v0
	v_mov_b32_e32 v36, v0
	v_mov_b32_e32 v37, v0
	v_mov_b32_e32 v38, v0
	v_mov_b32_e32 v39, v0
	v_mov_b32_e32 v44, v0
	v_mov_b32_e32 v45, v0
	v_mov_b32_e32 v46, v0
	v_mov_b32_e32 v47, v0
	v_mov_b32_e32 v48, v0
	v_mov_b32_e32 v49, v0
	v_mov_b32_e32 v50, v0
	v_mov_b32_e32 v51, v0
	v_mov_b32_e32 v8, v0
	v_mov_b32_e32 v9, v0
	v_mov_b32_e32 v10, v0
	v_mov_b32_e32 v11, v0
	v_mov_b32_e32 v20, v0
	v_mov_b32_e32 v21, v0
	v_mov_b32_e32 v22, v0
	v_mov_b32_e32 v23, v0
	v_mov_b32_e32 v24, v0
	v_mov_b32_e32 v25, v0
	v_mov_b32_e32 v26, v0
	v_mov_b32_e32 v27, v0
	v_mov_b32_e32 v28, v0
	v_mov_b32_e32 v29, v0
	v_mov_b32_e32 v30, v0
	v_mov_b32_e32 v31, v0
	v_mov_b32_e32 v40, v0
	v_mov_b32_e32 v41, v0
	v_mov_b32_e32 v42, v0
	v_mov_b32_e32 v43, v0
	v_mov_b32_e32 v52, v0
	v_mov_b32_e32 v53, v0
	v_mov_b32_e32 v54, v0
	v_mov_b32_e32 v55, v0
	v_mov_b32_e32 v56, v0
	v_mov_b32_e32 v57, v0
	v_mov_b32_e32 v58, v0
	v_mov_b32_e32 v59, v0
	v_mov_b32_e32 v60, v0
	v_mov_b32_e32 v61, v0
	v_mov_b32_e32 v62, v0
	v_mov_b32_e32 v63, v0
	v_mov_b32_e32 v64, v0
	v_mov_b32_e32 v65, v0
	v_mov_b32_e32 v66, v0
	v_mov_b32_e32 v67, v0
	v_mov_b32_e32 v68, v0
	v_mov_b32_e32 v69, v0
	v_mov_b32_e32 v70, v0
	v_mov_b32_e32 v71, v0
	v_mov_b32_e32 v72, v0
	v_mov_b32_e32 v73, v0
	v_mov_b32_e32 v74, v0
	v_mov_b32_e32 v75, v0
	v_mov_b32_e32 v80, v0
	v_mov_b32_e32 v81, v0
	v_mov_b32_e32 v82, v0
	v_mov_b32_e32 v83, v0
	v_mov_b32_e32 v96, v0
	v_mov_b32_e32 v97, v0
	v_mov_b32_e32 v98, v0
	v_mov_b32_e32 v99, v0
	v_mov_b32_e32 v100, v0
	v_mov_b32_e32 v101, v0
	v_mov_b32_e32 v102, v0
	v_mov_b32_e32 v103, v0
	v_mov_b32_e32 v104, v0
	v_mov_b32_e32 v105, v0
	v_mov_b32_e32 v106, v0
	v_mov_b32_e32 v107, v0
	v_mov_b32_e32 v116, v0
	v_mov_b32_e32 v117, v0
	v_mov_b32_e32 v118, v0
	v_mov_b32_e32 v119, v0
	v_mov_b32_e32 v76, v0
	v_mov_b32_e32 v77, v0
	v_mov_b32_e32 v78, v0
	v_mov_b32_e32 v79, v0
	v_mov_b32_e32 v84, v0
	v_mov_b32_e32 v85, v0
	v_mov_b32_e32 v86, v0
	v_mov_b32_e32 v87, v0
	v_mov_b32_e32 v88, v0
	v_mov_b32_e32 v89, v0
	v_mov_b32_e32 v90, v0
	v_mov_b32_e32 v91, v0
	v_mov_b32_e32 v92, v0
	v_mov_b32_e32 v93, v0
	v_mov_b32_e32 v94, v0
	v_mov_b32_e32 v95, v0
	v_mov_b32_e32 v108, v0
	v_mov_b32_e32 v109, v0
	v_mov_b32_e32 v110, v0
	v_mov_b32_e32 v111, v0
	v_mov_b32_e32 v112, v0
	v_mov_b32_e32 v113, v0
	v_mov_b32_e32 v114, v0
	v_mov_b32_e32 v115, v0
	v_mov_b32_e32 v120, v0
	v_mov_b32_e32 v121, v0
	v_mov_b32_e32 v122, v0
	v_mov_b32_e32 v123, v0
	v_mov_b32_e32 v124, v0
	v_mov_b32_e32 v125, v0
	v_mov_b32_e32 v126, v0
	v_mov_b32_e32 v127, v0
	v_add_u32_e32 v158, 0x10000, v171
	ds_read_b128 v[132:135], v158
	ds_read_b128 v[136:139], v158 offset:1024
	ds_read_b128 v[140:143], v158 offset:2048
	ds_read_b128 v[174:177], v158 offset:3072
.LBB0_1229:
	s_add_u32 s10, s0, s42
	s_addc_u32 s11, s1, s43
	s_add_u32 s16, s10, 0x100
	s_addc_u32 s17, s11, 0
	s_add_u32 s10, s10, 0x180
	s_addc_u32 s11, s11, 0
	s_add_u32 s14, s69, s42
	s_addc_u32 s15, s70, s43
	s_add_i32 s78, 0, 0x10000
	s_cmpk_eq_i32 s42, 0x1f00
	s_cselect_b32 s15, s39, s15
	s_cselect_b32 s14, s38, s14
	s_cselect_b32 s21, s37, s17
	s_cselect_b32 s20, s36, s16
	s_cselect_b32 s17, s27, s11
	s_cselect_b32 s16, s3, s10
	v_lshl_add_u64 v[158:159], v[128:129], 0, s[42:43]
	s_add_i32 m0, s48, 0xc000
	ds_read_b128 v[178:181], v172
	ds_read_b128 v[182:185], v172 offset:1024
	ds_read_b128 v[204:207], v172 offset:2048
	ds_read_b128 v[208:211], v172 offset:3072
	ds_read_b128 v[212:215], v172 offset:4096
	ds_read_b128 v[216:219], v172 offset:5120
	ds_read_b128 v[220:223], v172 offset:6144
	ds_read_b128 v[224:227], v172 offset:7168
	global_load_lds_dwordx4 v[158:159], off
	v_lshl_add_u64 v[158:159], v[130:131], 0, s[42:43]
	s_add_i32 m0, s48, 0xe000
	s_nop 0
	global_load_lds_dwordx4 v[158:159], off
	s_waitcnt lgkmcnt(8)
	s_barrier
	s_waitcnt lgkmcnt(0)
	s_setprio 1
	s_waitcnt lgkmcnt(0)
	v_mfma_f32_16x16x32_bf16 v[124:127], v[132:135], v[178:181], v[124:127]
	v_mfma_f32_16x16x32_bf16 v[120:123], v[140:143], v[178:181], v[120:123]
	v_mfma_f32_16x16x32_bf16 v[112:115], v[132:135], v[204:207], v[112:115]
	v_mfma_f32_16x16x32_bf16 v[108:111], v[140:143], v[204:207], v[108:111]
	v_mfma_f32_16x16x32_bf16 v[92:95], v[132:135], v[212:215], v[92:95]
	v_mfma_f32_16x16x32_bf16 v[88:91], v[140:143], v[212:215], v[88:91]
	v_mfma_f32_16x16x32_bf16 v[84:87], v[132:135], v[220:223], v[84:87]
	v_mfma_f32_16x16x32_bf16 v[76:79], v[140:143], v[220:223], v[76:79]
	v_mfma_f32_16x16x32_bf16 v[124:127], v[136:139], v[182:185], v[124:127]
	v_mfma_f32_16x16x32_bf16 v[120:123], v[174:177], v[182:185], v[120:123]
	v_mfma_f32_16x16x32_bf16 v[112:115], v[136:139], v[208:211], v[112:115]
	v_mfma_f32_16x16x32_bf16 v[108:111], v[174:177], v[208:211], v[108:111]
	v_mfma_f32_16x16x32_bf16 v[92:95], v[136:139], v[216:219], v[92:95]
	v_mfma_f32_16x16x32_bf16 v[88:91], v[174:177], v[216:219], v[88:91]
	v_mfma_f32_16x16x32_bf16 v[84:87], v[136:139], v[224:227], v[84:87]
	v_mfma_f32_16x16x32_bf16 v[76:79], v[174:177], v[224:227], v[76:79]
	s_setprio 0
	s_barrier
; #define PG8_STAGE(bufoff, gbase, voff) do { _Pragma("unroll") for (int _i = 0; _i < 2; ++_i) \
;         __builtin_amdgcn_global_load_lds((const unsigned*)((const char*)(gbase) + (voff)[_i]), (LAS unsigned*)(lds + (bufoff) + ldsw + _i * 8192), 16, 0, 0); } while (0)
; #define PG8_STAGE_A(bufoff, ptr, half, rev) do { if (REVA && (rev)) { const char* _p = (ptr) - ((half) ? hstepA : 0); PG8_STAGE(bufoff, _p, voffAr); } else { const char* _p = (ptr) + ((half) ? hstepA : 0); PG8_STAGE(bufoff, _p, voffA); } } while (0)
; #define PG8_LDA(dst, b, h) do { _Pragma("unroll") for (int m = 0; m < 4; ++m) _Pragma("unroll") for (int k = 0; k < 2; ++k) dst[m][k] = *(const LAS bf16x8*)(lds + PG8_SA(b, h) + aoff + m * 2048 + k * 1024); } while (0)
; #define PG8_LDB(dst, b, h) do { _Pragma("unroll") for (int n = 0; n < 2; ++n) _Pragma("unroll") for (int k = 0; k < 2; ++k) dst[n][k] = *(const LAS bf16x8*)(lds + PG8_SB(b, h) + boff + n * 2048 + k * 1024); } while (0)
; #define PG8_MMA(ai, bj, At, Bt) do { __builtin_amdgcn_s_setprio(1); _Pragma("unroll") for (int m = 0; m < 4; ++m) _Pragma("unroll") for (int n = 0; n < 2; ++n) _Pragma("unroll") for (int k = 0; k < 2; ++k) \
;         acc[ai][bj][m][n] = __builtin_amdgcn_mfma_f32_16x16x32_bf16(Bt[n][k], At[m][k], acc[ai][bj][m][n], 0, 0, 0); __builtin_amdgcn_s_setprio(0); } while (0)
; #define PG8_WAIT_V(n) asm volatile("s_waitcnt vmcnt(" #n ")" ::: "memory")
; #define PG8_WAIT_L(n) asm volatile("s_waitcnt lgkmcnt(" #n ")" ::: "memory")
; #define PG8_BAR __builtin_amdgcn_s_barrier()
; #define PG8_SCHED __builtin_amdgcn_sched_barrier(0)
;     ...
;             PG8_LDB(B1, 0, 1); PG8_STAGE(PG8_SB(0, 0), b2, voffB);
;             PG8_BAR; PG8_WAIT_L(0); PG8_MMA(0, 1, At, B1); PG8_BAR;
;             PG8_LDA(At, 0, 1); PG8_STAGE_A(PG8_SA(0, 0), a2, 0, r2);
;             PG8_BAR; PG8_WAIT_L(0); PG8_MMA(1, 0, At, B0); PG8_BAR; PG8_SCHED;
;             PG8_STAGE(PG8_SB(0, 1), b2 + hb2, voffB);
;             PG8_WAIT_V(6); PG8_BAR; PG8_MMA(1, 1, At, B1); PG8_BAR;
;             PG8_LDB(B0, 1, 0); PG8_SCHED; PG8_LDA(At, 1, 0); PG8_STAGE_A(PG8_SA(0, 1), a2, 1, r2);
;             PG8_WAIT_L(8); PG8_BAR; PG8_WAIT_L(0); PG8_MMA(0, 0, At, B0); PG8_BAR; PG8_SCHED;
	s_add_i32 s10, 0, 0x14000
	v_add_u32_e32 v158, s10, v171
	s_add_i32 s11, s78, s5
	ds_read_b128 v[228:231], v158
	ds_read_b128 v[232:235], v158 offset:1024
	ds_read_b128 v[236:239], v158 offset:2048
	ds_read_b128 v[240:243], v158 offset:3072
	v_lshl_add_u64 v[158:159], s[14:15], 0, v[150:151]
	s_mov_b32 m0, s11
	v_lshl_add_u64 v[168:169], s[14:15], 0, v[148:149]
	global_load_lds_dwordx4 v[158:159], off
	s_add_i32 m0, s11, 0x2000
	s_nop 0
	global_load_lds_dwordx4 v[168:169], off
	s_barrier
	s_waitcnt lgkmcnt(0)
	s_setprio 1
	s_waitcnt lgkmcnt(0)
	v_mfma_f32_16x16x32_bf16 v[116:119], v[228:231], v[178:181], v[116:119]
	v_mfma_f32_16x16x32_bf16 v[104:107], v[236:239], v[178:181], v[104:107]
	v_mfma_f32_16x16x32_bf16 v[100:103], v[228:231], v[204:207], v[100:103]
	v_mfma_f32_16x16x32_bf16 v[96:99], v[236:239], v[204:207], v[96:99]
	v_mfma_f32_16x16x32_bf16 v[80:83], v[228:231], v[212:215], v[80:83]
	v_mfma_f32_16x16x32_bf16 v[72:75], v[236:239], v[212:215], v[72:75]
	v_mfma_f32_16x16x32_bf16 v[68:71], v[228:231], v[220:223], v[68:71]
	v_mfma_f32_16x16x32_bf16 v[64:67], v[236:239], v[220:223], v[64:67]
	v_mfma_f32_16x16x32_bf16 v[116:119], v[232:235], v[182:185], v[116:119]
	v_mfma_f32_16x16x32_bf16 v[104:107], v[240:243], v[182:185], v[104:107]
	v_mfma_f32_16x16x32_bf16 v[100:103], v[232:235], v[208:211], v[100:103]
	v_mfma_f32_16x16x32_bf16 v[96:99], v[240:243], v[208:211], v[96:99]
	v_mfma_f32_16x16x32_bf16 v[80:83], v[232:235], v[216:219], v[80:83]
	v_mfma_f32_16x16x32_bf16 v[72:75], v[240:243], v[216:219], v[72:75]
	v_mfma_f32_16x16x32_bf16 v[68:71], v[232:235], v[224:227], v[68:71]
	v_mfma_f32_16x16x32_bf16 v[64:67], v[240:243], v[224:227], v[64:67]
	s_setprio 0
	s_mov_b32 m0, s48
	v_lshl_add_u64 v[190:191], s[20:21], 0, v[150:151]
	s_barrier
	ds_read_b128 v[178:181], v172 offset:16384
	ds_read_b128 v[182:185], v172 offset:17408
	ds_read_b128 v[204:207], v172 offset:18432
	ds_read_b128 v[208:211], v172 offset:19456
	ds_read_b128 v[212:215], v172 offset:20480
	ds_read_b128 v[216:219], v172 offset:21504
	ds_read_b128 v[220:223], v172 offset:22528
	ds_read_b128 v[224:227], v172 offset:23552
	global_load_lds_dwordx4 v[190:191], off
	v_lshl_add_u64 v[190:191], s[20:21], 0, v[148:149]
	s_mov_b32 m0, s49
	s_nop 0
	global_load_lds_dwordx4 v[190:191], off
	s_waitcnt vmcnt(10)
	s_barrier
	s_waitcnt lgkmcnt(0)
	s_setprio 1
	s_waitcnt lgkmcnt(0)
	v_mfma_f32_16x16x32_bf16 v[60:63], v[132:135], v[178:181], v[60:63]
	v_mfma_f32_16x16x32_bf16 v[56:59], v[140:143], v[178:181], v[56:59]
	v_mfma_f32_16x16x32_bf16 v[52:55], v[132:135], v[204:207], v[52:55]
	v_mfma_f32_16x16x32_bf16 v[40:43], v[140:143], v[204:207], v[40:43]
	v_mfma_f32_16x16x32_bf16 v[28:31], v[132:135], v[212:215], v[28:31]
	v_mfma_f32_16x16x32_bf16 v[24:27], v[140:143], v[212:215], v[24:27]
	v_mfma_f32_16x16x32_bf16 v[20:23], v[132:135], v[220:223], v[20:23]
	v_mfma_f32_16x16x32_bf16 v[8:11], v[140:143], v[220:223], v[8:11]
	v_mfma_f32_16x16x32_bf16 v[60:63], v[136:139], v[182:185], v[60:63]
	v_mfma_f32_16x16x32_bf16 v[56:59], v[174:177], v[182:185], v[56:59]
	v_mfma_f32_16x16x32_bf16 v[52:55], v[136:139], v[208:211], v[52:55]
	v_mfma_f32_16x16x32_bf16 v[40:43], v[174:177], v[208:211], v[40:43]
	v_mfma_f32_16x16x32_bf16 v[28:31], v[136:139], v[216:219], v[28:31]
	v_mfma_f32_16x16x32_bf16 v[24:27], v[174:177], v[216:219], v[24:27]
	v_mfma_f32_16x16x32_bf16 v[20:23], v[136:139], v[224:227], v[20:23]
	v_mfma_f32_16x16x32_bf16 v[8:11], v[174:177], v[224:227], v[8:11]
	s_setprio 0
	s_barrier
	s_add_u32 s78, s14, 0x100000
	s_addc_u32 s79, s15, 0
	s_add_i32 s10, s10, s5
	v_lshl_add_u64 v[132:133], s[78:79], 0, v[150:151]
	s_mov_b32 m0, s10
	s_nop 0
	global_load_lds_dwordx4 v[132:133], off
	v_lshl_add_u64 v[132:133], s[78:79], 0, v[148:149]
	s_add_i32 m0, s10, 0x2000
	s_nop 0
	global_load_lds_dwordx4 v[132:133], off
	v_add_u32_e32 v173, 0x18000, v171
	ds_read_b128 v[132:135], v173
	ds_read_b128 v[136:139], v173 offset:1024
	ds_read_b128 v[140:143], v173 offset:2048
	ds_read_b128 v[174:177], v173 offset:3072
	s_waitcnt vmcnt(6)
	s_barrier
	s_setprio 1
	v_mfma_f32_16x16x32_bf16 v[48:51], v[228:231], v[178:181], v[48:51]
	v_mfma_f32_16x16x32_bf16 v[44:47], v[236:239], v[178:181], v[44:47]
	v_mfma_f32_16x16x32_bf16 v[36:39], v[228:231], v[204:207], v[36:39]
	v_mfma_f32_16x16x32_bf16 v[32:35], v[236:239], v[204:207], v[32:35]
	v_mfma_f32_16x16x32_bf16 v[16:19], v[228:231], v[212:215], v[16:19]
	v_mfma_f32_16x16x32_bf16 v[12:15], v[236:239], v[212:215], v[12:15]
	v_mfma_f32_16x16x32_bf16 v[4:7], v[228:231], v[220:223], v[4:7]
	v_mfma_f32_16x16x32_bf16 v[0:3], v[236:239], v[220:223], v[0:3]
	v_mfma_f32_16x16x32_bf16 v[48:51], v[232:235], v[182:185], v[48:51]
	v_mfma_f32_16x16x32_bf16 v[44:47], v[240:243], v[182:185], v[44:47]
	v_mfma_f32_16x16x32_bf16 v[36:39], v[232:235], v[208:211], v[36:39]
	v_mfma_f32_16x16x32_bf16 v[32:35], v[240:243], v[208:211], v[32:35]
	v_mfma_f32_16x16x32_bf16 v[16:19], v[232:235], v[216:219], v[16:19]
	v_mfma_f32_16x16x32_bf16 v[12:15], v[240:243], v[216:219], v[12:15]
	v_mfma_f32_16x16x32_bf16 v[4:7], v[232:235], v[224:227], v[4:7]
	v_mfma_f32_16x16x32_bf16 v[0:3], v[240:243], v[224:227], v[0:3]
	s_setprio 0
	s_add_i32 s10, 0, 0x18000
	s_barrier
	s_add_u32 s20, s20, 0x100000
	s_addc_u32 s21, s21, 0
	s_mov_b32 m0, s50
	v_lshl_add_u64 v[190:191], s[20:21], 0, v[150:151]
	ds_read_b128 v[178:181], v172 offset:32768
	ds_read_b128 v[182:185], v172 offset:33792
	ds_read_b128 v[204:207], v172 offset:34816
	ds_read_b128 v[208:211], v172 offset:35840
	ds_read_b128 v[212:215], v172 offset:36864
	ds_read_b128 v[216:219], v172 offset:37888
	ds_read_b128 v[220:223], v172 offset:38912
	ds_read_b128 v[224:227], v172 offset:39936
	global_load_lds_dwordx4 v[190:191], off
	v_lshl_add_u64 v[190:191], s[20:21], 0, v[148:149]
	s_mov_b32 m0, s51
	s_nop 0
	global_load_lds_dwordx4 v[190:191], off
	s_waitcnt lgkmcnt(8)
	s_barrier
; #define PG8_STAGE(bufoff, gbase, voff) do { _Pragma("unroll") for (int _i = 0; _i < 2; ++_i) \
;         __builtin_amdgcn_global_load_lds((const unsigned*)((const char*)(gbase) + (voff)[_i]), (LAS unsigned*)(lds + (bufoff) + ldsw + _i * 8192), 16, 0, 0); } while (0)
; #define PG8_STAGE_A(bufoff, ptr, half, rev) do { if (REVA && (rev)) { const char* _p = (ptr) - ((half) ? hstepA : 0); PG8_STAGE(bufoff, _p, voffAr); } else { const char* _p = (ptr) + ((half) ? hstepA : 0); PG8_STAGE(bufoff, _p, voffA); } } while (0)
; #define PG8_LDA(dst, b, h) do { _Pragma("unroll") for (int m = 0; m < 4; ++m) _Pragma("unroll") for (int k = 0; k < 2; ++k) dst[m][k] = *(const LAS bf16x8*)(lds + PG8_SA(b, h) + aoff + m * 2048 + k * 1024); } while (0)
; #define PG8_LDB(dst, b, h) do { _Pragma("unroll") for (int n = 0; n < 2; ++n) _Pragma("unroll") for (int k = 0; k < 2; ++k) dst[n][k] = *(const LAS bf16x8*)(lds + PG8_SB(b, h) + boff + n * 2048 + k * 1024); } while (0)
; #define PG8_MMA(ai, bj, At, Bt) do { __builtin_amdgcn_s_setprio(1); _Pragma("unroll") for (int m = 0; m < 4; ++m) _Pragma("unroll") for (int n = 0; n < 2; ++n) _Pragma("unroll") for (int k = 0; k < 2; ++k) \
;         acc[ai][bj][m][n] = __builtin_amdgcn_mfma_f32_16x16x32_bf16(Bt[n][k], At[m][k], acc[ai][bj][m][n], 0, 0, 0); __builtin_amdgcn_s_setprio(0); } while (0)
; #define PG8_WAIT_V(n) asm volatile("s_waitcnt vmcnt(" #n ")" ::: "memory")
; #define PG8_WAIT_L(n) asm volatile("s_waitcnt lgkmcnt(" #n ")" ::: "memory")
; #define PG8_BAR __builtin_amdgcn_s_barrier()
; #define PG8_SCHED __builtin_amdgcn_sched_barrier(0)
;     ...
;             PG8_WAIT_L(8); PG8_BAR; PG8_WAIT_L(0); PG8_MMA(0, 0, At, B0); PG8_BAR; PG8_SCHED;
;             PG8_LDB(B1, 1, 1); PG8_STAGE(PG8_SB(1, 0), b3, voffB);
;             PG8_BAR; PG8_WAIT_L(0); PG8_MMA(0, 1, At, B1); PG8_BAR;
;             PG8_LDA(At, 1, 1); PG8_STAGE_A(PG8_SA(1, 0), a3, 0, r3);
;             PG8_BAR; PG8_WAIT_L(0); PG8_MMA(1, 0, At, B0); PG8_BAR; PG8_SCHED;
;             PG8_STAGE(PG8_SB(1, 1), b3 + hb2, voffB);
;             PG8_WAIT_V(6); PG8_BAR; PG8_MMA(1, 1, At, B1); PG8_BAR;
	s_waitcnt lgkmcnt(0)
	s_setprio 1
	s_waitcnt lgkmcnt(0)
	v_mfma_f32_16x16x32_bf16 v[124:127], v[132:135], v[178:181], v[124:127]
	v_mfma_f32_16x16x32_bf16 v[120:123], v[140:143], v[178:181], v[120:123]
	v_mfma_f32_16x16x32_bf16 v[112:115], v[132:135], v[204:207], v[112:115]
	v_mfma_f32_16x16x32_bf16 v[108:111], v[140:143], v[204:207], v[108:111]
	v_mfma_f32_16x16x32_bf16 v[92:95], v[132:135], v[212:215], v[92:95]
	v_mfma_f32_16x16x32_bf16 v[88:91], v[140:143], v[212:215], v[88:91]
	v_mfma_f32_16x16x32_bf16 v[84:87], v[132:135], v[220:223], v[84:87]
	v_mfma_f32_16x16x32_bf16 v[76:79], v[140:143], v[220:223], v[76:79]
	v_mfma_f32_16x16x32_bf16 v[124:127], v[136:139], v[182:185], v[124:127]
	v_mfma_f32_16x16x32_bf16 v[120:123], v[174:177], v[182:185], v[120:123]
	v_mfma_f32_16x16x32_bf16 v[112:115], v[136:139], v[208:211], v[112:115]
	v_mfma_f32_16x16x32_bf16 v[108:111], v[174:177], v[208:211], v[108:111]
	v_mfma_f32_16x16x32_bf16 v[92:95], v[136:139], v[216:219], v[92:95]
	v_mfma_f32_16x16x32_bf16 v[88:91], v[174:177], v[216:219], v[88:91]
	v_mfma_f32_16x16x32_bf16 v[84:87], v[136:139], v[224:227], v[84:87]
	v_mfma_f32_16x16x32_bf16 v[76:79], v[174:177], v[224:227], v[76:79]
	s_setprio 0
	s_barrier
	s_add_i32 s11, 0, 0x1c000
	s_add_i32 s10, s10, s5
	v_add_u32_e32 v173, s11, v171
	v_lshl_add_u64 v[158:159], v[158:159], 0, s[28:29]
	s_mov_b32 m0, s10
	ds_read_b128 v[228:231], v173
	ds_read_b128 v[232:235], v173 offset:1024
	ds_read_b128 v[236:239], v173 offset:2048
	ds_read_b128 v[240:243], v173 offset:3072
	global_load_lds_dwordx4 v[158:159], off
	v_lshl_add_u64 v[158:159], v[168:169], 0, s[28:29]
	s_add_i32 m0, s10, 0x2000
	s_nop 0
	global_load_lds_dwordx4 v[158:159], off
	s_barrier
	s_waitcnt lgkmcnt(0)
	s_setprio 1
	s_waitcnt lgkmcnt(0)
	v_mfma_f32_16x16x32_bf16 v[116:119], v[228:231], v[178:181], v[116:119]
	v_mfma_f32_16x16x32_bf16 v[104:107], v[236:239], v[178:181], v[104:107]
	v_mfma_f32_16x16x32_bf16 v[100:103], v[228:231], v[204:207], v[100:103]
	v_mfma_f32_16x16x32_bf16 v[96:99], v[236:239], v[204:207], v[96:99]
	v_mfma_f32_16x16x32_bf16 v[80:83], v[228:231], v[212:215], v[80:83]
	v_mfma_f32_16x16x32_bf16 v[72:75], v[236:239], v[212:215], v[72:75]
	v_mfma_f32_16x16x32_bf16 v[68:71], v[228:231], v[220:223], v[68:71]
	v_mfma_f32_16x16x32_bf16 v[64:67], v[236:239], v[220:223], v[64:67]
	v_mfma_f32_16x16x32_bf16 v[116:119], v[232:235], v[182:185], v[116:119]
	v_mfma_f32_16x16x32_bf16 v[104:107], v[240:243], v[182:185], v[104:107]
	v_mfma_f32_16x16x32_bf16 v[100:103], v[232:235], v[208:211], v[100:103]
	v_mfma_f32_16x16x32_bf16 v[96:99], v[240:243], v[208:211], v[96:99]
	v_mfma_f32_16x16x32_bf16 v[80:83], v[232:235], v[216:219], v[80:83]
	v_mfma_f32_16x16x32_bf16 v[72:75], v[240:243], v[216:219], v[72:75]
	v_mfma_f32_16x16x32_bf16 v[68:71], v[232:235], v[224:227], v[68:71]
	v_mfma_f32_16x16x32_bf16 v[64:67], v[240:243], v[224:227], v[64:67]
	s_setprio 0
	s_mov_b32 m0, s66
	v_lshl_add_u64 v[158:159], s[16:17], 0, v[150:151]
	s_barrier
	ds_read_b128 v[178:181], v172 offset:49152
	ds_read_b128 v[182:185], v172 offset:50176
	ds_read_b128 v[204:207], v172 offset:51200
	ds_read_b128 v[208:211], v172 offset:52224
	ds_read_b128 v[212:215], v172 offset:53248
	ds_read_b128 v[216:219], v172 offset:54272
	ds_read_b128 v[220:223], v172 offset:55296
	ds_read_b128 v[224:227], v172 offset:56320
	global_load_lds_dwordx4 v[158:159], off
	v_lshl_add_u64 v[158:159], s[16:17], 0, v[148:149]
	s_mov_b32 m0, s67
	s_nop 0
	global_load_lds_dwordx4 v[158:159], off
	s_waitcnt vmcnt(10)
	s_barrier
	s_waitcnt lgkmcnt(0)
	s_setprio 1
	s_waitcnt lgkmcnt(0)
	v_mfma_f32_16x16x32_bf16 v[60:63], v[132:135], v[178:181], v[60:63]
	v_mfma_f32_16x16x32_bf16 v[56:59], v[140:143], v[178:181], v[56:59]
	v_mfma_f32_16x16x32_bf16 v[52:55], v[132:135], v[204:207], v[52:55]
	v_mfma_f32_16x16x32_bf16 v[40:43], v[140:143], v[204:207], v[40:43]
	v_mfma_f32_16x16x32_bf16 v[28:31], v[132:135], v[212:215], v[28:31]
	v_mfma_f32_16x16x32_bf16 v[24:27], v[140:143], v[212:215], v[24:27]
	v_mfma_f32_16x16x32_bf16 v[20:23], v[132:135], v[220:223], v[20:23]
	v_mfma_f32_16x16x32_bf16 v[8:11], v[140:143], v[220:223], v[8:11]
	v_mfma_f32_16x16x32_bf16 v[60:63], v[136:139], v[182:185], v[60:63]
	v_mfma_f32_16x16x32_bf16 v[56:59], v[174:177], v[182:185], v[56:59]
	v_mfma_f32_16x16x32_bf16 v[52:55], v[136:139], v[208:211], v[52:55]
	v_mfma_f32_16x16x32_bf16 v[40:43], v[174:177], v[208:211], v[40:43]
	v_mfma_f32_16x16x32_bf16 v[28:31], v[136:139], v[216:219], v[28:31]
	v_mfma_f32_16x16x32_bf16 v[24:27], v[174:177], v[216:219], v[24:27]
	v_mfma_f32_16x16x32_bf16 v[20:23], v[136:139], v[224:227], v[20:23]
	v_mfma_f32_16x16x32_bf16 v[8:11], v[174:177], v[224:227], v[8:11]
	s_setprio 0
	s_barrier
	s_add_u32 s14, s14, 0x100080
	s_addc_u32 s15, s15, 0
	s_add_i32 s10, s11, s5
	v_lshl_add_u64 v[132:133], s[14:15], 0, v[150:151]
	s_mov_b32 m0, s10
	s_nop 0
	global_load_lds_dwordx4 v[132:133], off
	v_lshl_add_u64 v[132:133], s[14:15], 0, v[148:149]
	s_add_i32 m0, s10, 0x2000
	s_nop 0
	global_load_lds_dwordx4 v[132:133], off
	v_add_u32_e32 v158, 0x10000, v171
	ds_read_b128 v[132:135], v158
	ds_read_b128 v[136:139], v158 offset:1024
	ds_read_b128 v[140:143], v158 offset:2048
	ds_read_b128 v[174:177], v158 offset:3072
	s_waitcnt vmcnt(6)
	s_barrier
; #define PG8_MMA(ai, bj, At, Bt) do { __builtin_amdgcn_s_setprio(1); _Pragma("unroll") for (int m = 0; m < 4; ++m) _Pragma("unroll") for (int n = 0; n < 2; ++n) _Pragma("unroll") for (int k = 0; k < 2; ++k) \
;         acc[ai][bj][m][n] = __builtin_amdgcn_mfma_f32_16x16x32_bf16(Bt[n][k], At[m][k], acc[ai][bj][m][n], 0, 0, 0); __builtin_amdgcn_s_setprio(0); } while (0)
; #define PG8_WAIT_V(n) asm volatile("s_waitcnt vmcnt(" #n ")" ::: "memory")
; #define PG8_BAR __builtin_amdgcn_s_barrier()
;     ...
;             PG8_WAIT_V(6); PG8_BAR; PG8_MMA(1, 1, At, B1); PG8_BAR;
;         }
;     __device__ __forceinline__ void operator()(const f32x4 (&acc)[2][2][4][2], const Unit& u, int wr, int wc, int fr, int fq, int lane) const {
;         const bool lat = u.pm < 128;
;         const int s = lat ? (u.pm >> 4) : 8;
;         const float* gate = modi + s * 6144 + 4096 + u.pn * BM + wc * 32 + 4 * fq;
;         const size_t r0 = lat ? (size_t)u.pm * BM : (size_t)(u.pm - 128) * BM;
;         const float* base = (lat ? baseL : baseC) + u.pn * BM + wc * 32 + 4 * fq;
;         float* out = (lat ? outL : outC) + u.pn * BM + wc * 32 + 4 * fq;
;         f32x4 gv[2][2];
; #pragma unroll
;         for (int bj = 0; bj < 2; ++bj)
; #pragma unroll
;             for (int n = 0; n < 2; ++n) gv[bj][n] = *(const f32x4*)(gate + bj * HALF + n * 16);
; #pragma unroll
;         for (int ai = 0; ai < 2; ++ai)
; #pragma unroll
;           for (int mh = 0; mh < 2; ++mh) {
;             f32x4 bs[2][2][2];
; #pragma unroll
;             for (int m2 = 0; m2 < 2; ++m2) {
;                 const size_t ro = (r0 + ai * HALF + wr * 64 + (mh * 2 + m2) * 16 + fr) * (size_t)D;
; #pragma unroll
;                 for (int bj = 0; bj < 2; ++bj)
; #pragma unroll
;                     for (int n = 0; n < 2; ++n) bs[m2][bj][n] = *(const f32x4*)(base + ro + bj * HALF + n * 16);
;             }
;             __builtin_amdgcn_sched_barrier(0);
; #pragma unroll
;             for (int m2 = 0; m2 < 2; ++m2) {
;                 const size_t ro = (r0 + ai * HALF + wr * 64 + (mh * 2 + m2) * 16 + fr) * (size_t)D;
; #pragma unroll
;                 for (int bj = 0; bj < 2; ++bj)
; #pragma unroll
;                     for (int n = 0; n < 2; ++n) *(f32x4*)(out + ro + bj * HALF + n * 16) = bs[m2][bj][n] + gv[bj][n] * acc[ai][bj][mh * 2 + m2][n];
;             }
;             __builtin_amdgcn_sched_barrier(0);
;           }
	s_setprio 1
	v_mfma_f32_16x16x32_bf16 v[48:51], v[228:231], v[178:181], v[48:51]
	v_mfma_f32_16x16x32_bf16 v[44:47], v[236:239], v[178:181], v[44:47]
	v_mfma_f32_16x16x32_bf16 v[36:39], v[228:231], v[204:207], v[36:39]
	v_mfma_f32_16x16x32_bf16 v[32:35], v[236:239], v[204:207], v[32:35]
	v_mfma_f32_16x16x32_bf16 v[16:19], v[228:231], v[212:215], v[16:19]
	v_mfma_f32_16x16x32_bf16 v[12:15], v[236:239], v[212:215], v[12:15]
	v_mfma_f32_16x16x32_bf16 v[4:7], v[228:231], v[220:223], v[4:7]
	v_mfma_f32_16x16x32_bf16 v[0:3], v[236:239], v[220:223], v[0:3]
	v_mfma_f32_16x16x32_bf16 v[48:51], v[232:235], v[182:185], v[48:51]
	v_mfma_f32_16x16x32_bf16 v[44:47], v[240:243], v[182:185], v[44:47]
	v_mfma_f32_16x16x32_bf16 v[36:39], v[232:235], v[208:211], v[36:39]
	v_mfma_f32_16x16x32_bf16 v[32:35], v[240:243], v[208:211], v[32:35]
	v_mfma_f32_16x16x32_bf16 v[16:19], v[232:235], v[216:219], v[16:19]
	v_mfma_f32_16x16x32_bf16 v[12:15], v[240:243], v[216:219], v[12:15]
	v_mfma_f32_16x16x32_bf16 v[4:7], v[232:235], v[224:227], v[4:7]
	v_mfma_f32_16x16x32_bf16 v[0:3], v[240:243], v[224:227], v[0:3]
	s_setprio 0
	s_add_i32 s71, s71, 2
	s_add_u32 s42, s42, 0x100
	s_addc_u32 s43, s43, 0
	s_cmp_gt_u32 s71, 61
	s_barrier
	s_cbranch_scc0 .LBB0_1229
	s_waitcnt lgkmcnt(0)
	s_cmpk_lt_i32 s9, 0x80
	s_cselect_b64 vcc, -1, 0
	s_cselect_b32 s3, s61, s53
	s_cselect_b32 s10, s60, s52
	s_add_i32 s0, s9, 0xffffff80
	s_cmpk_lt_i32 s9, 0x80
	s_cselect_b32 s0, s9, s0
	s_lshr_b32 s1, s9, 4
	s_cmpk_lt_i32 s9, 0x80
	s_mulk_i32 s1, 0x1800
	s_cselect_b32 s14, s1, 0xc000
	s_ashr_i32 s15, s14, 31
	s_lshl_b64 s[14:15], s[14:15], 2
	s_add_u32 s1, s6, s14
	s_addc_u32 s11, s7, s15
	s_lshl_b32 s8, s8, 8
	s_ashr_i32 s9, s8, 31
	s_lshl_b64 s[8:9], s[8:9], 2
	s_add_u32 s1, s1, s8
	s_addc_u32 s11, s11, s9
	s_add_u32 s14, s1, s22
	s_waitcnt vmcnt(0)
	v_cndmask_b32_e32 v129, v147, v145, vcc
	v_cndmask_b32_e32 v128, v146, v144, vcc
	s_addc_u32 s15, s11, 0
	s_ashr_i32 s1, s0, 31
	v_lshl_add_u64 v[128:129], v[128:129], 0, s[8:9]
	s_add_u32 s8, s10, s8
	s_addc_u32 s3, s3, s9
	s_add_u32 s8, s8, s22
	v_lshl_add_u64 v[130:131], s[14:15], 0, v[160:161]
	s_addc_u32 s9, s3, 0
	s_mov_b32 s3, 0x704000
	s_lshl_b64 s[0:1], s[0:1], 21
	s_mov_b64 s[14:15], 0x704000
	v_lshl_add_u64 v[168:169], v[128:129], 0, s[22:23]
	v_add_co_u32_e32 v128, vcc, s3, v130
	v_lshl_add_u64 v[224:225], s[0:1], 0, v[152:153]
	v_lshl_add_u64 v[158:159], v[130:131], 0, s[14:15]
	v_addc_co_u32_e32 v129, vcc, 0, v131, vcc
	v_lshl_add_u64 v[190:191], v[168:169], 0, v[160:161]
	v_or_b32_e32 v226, 0x20000, v224
	v_mov_b32_e32 v227, v225
	global_load_dwordx4 v[136:139], v[158:159], off offset:64
	global_load_dwordx4 v[132:135], v[158:159], off offset:512
	global_load_dwordx4 v[140:143], v[128:129], off
	s_nop 0
	global_load_dwordx4 v[128:131], v[158:159], off offset:576
	v_lshl_add_u64 v[168:169], v[190:191], 0, v[224:225]
	v_lshl_add_u64 v[158:159], v[190:191], 0, v[226:227]
	global_load_dwordx4 v[174:177], v[168:169], off
	global_load_dwordx4 v[178:181], v[168:169], off offset:64
	global_load_dwordx4 v[182:185], v[168:169], off offset:512
	global_load_dwordx4 v[204:207], v[168:169], off offset:576
	global_load_dwordx4 v[208:211], v[158:159], off
	global_load_dwordx4 v[212:215], v[158:159], off offset:64
	global_load_dwordx4 v[216:219], v[158:159], off offset:512
	global_load_dwordx4 v[220:223], v[158:159], off offset:576
	v_lshl_add_u64 v[228:229], s[8:9], 0, v[160:161]
	v_lshl_add_u64 v[158:159], v[228:229], 0, v[224:225]
	s_waitcnt vmcnt(0)
	v_pk_fma_f32 v[118:119], v[118:119], v[134:135], v[184:185]
	v_pk_fma_f32 v[116:117], v[116:117], v[132:133], v[182:183]
	v_pk_fma_f32 v[106:107], v[106:107], v[130:131], v[206:207]
	v_pk_fma_f32 v[104:105], v[104:105], v[128:129], v[204:205]
	global_store_dwordx4 v[158:159], v[116:119], off offset:512
	global_store_dwordx4 v[158:159], v[104:107], off offset:576
	v_pk_fma_f32 v[126:127], v[126:127], v[142:143], v[176:177]
	v_lshl_add_u64 v[116:117], v[228:229], 0, v[226:227]
	v_pk_fma_f32 v[106:107], v[114:115], v[142:143], v[210:211]
	v_pk_fma_f32 v[104:105], v[112:113], v[140:141], v[208:209]
	v_pk_fma_f32 v[124:125], v[124:125], v[140:141], v[174:175]
	v_pk_fma_f32 v[122:123], v[122:123], v[138:139], v[180:181]
	v_pk_fma_f32 v[120:121], v[120:121], v[136:137], v[178:179]
	global_store_dwordx4 v[116:117], v[104:107], off
	v_pk_fma_f32 v[102:103], v[102:103], v[134:135], v[218:219]
	v_pk_fma_f32 v[100:101], v[100:101], v[132:133], v[216:217]
	v_pk_fma_f32 v[106:107], v[110:111], v[138:139], v[214:215]
	v_pk_fma_f32 v[104:105], v[108:109], v[136:137], v[212:213]
	v_pk_fma_f32 v[98:99], v[98:99], v[130:131], v[222:223]
	v_pk_fma_f32 v[96:97], v[96:97], v[128:129], v[220:221]
	global_store_dwordx4 v[158:159], v[124:127], off
	global_store_dwordx4 v[158:159], v[120:123], off offset:64
	global_store_dwordx4 v[116:117], v[104:107], off offset:64
	global_store_dwordx4 v[116:117], v[100:103], off offset:512
	global_store_dwordx4 v[116:117], v[96:99], off offset:576
	v_or_b32_e32 v174, 0x40000, v224
	v_mov_b32_e32 v175, v225
	v_or_b32_e32 v224, 0x60000, v224
	v_lshl_add_u64 v[108:109], v[190:191], 0, v[174:175]
	v_lshl_add_u64 v[124:125], v[190:191], 0, v[224:225]
	global_load_dwordx4 v[96:99], v[108:109], off
	global_load_dwordx4 v[100:103], v[108:109], off offset:64
	global_load_dwordx4 v[104:107], v[108:109], off offset:512
	s_nop 0
	global_load_dwordx4 v[108:111], v[108:109], off offset:576
	s_nop 0
	global_load_dwordx4 v[112:115], v[124:125], off
	global_load_dwordx4 v[116:119], v[124:125], off offset:64
	global_load_dwordx4 v[120:123], v[124:125], off offset:512
	s_nop 0
	global_load_dwordx4 v[124:127], v[124:125], off offset:576
	v_lshl_add_u64 v[174:175], v[228:229], 0, v[174:175]
	s_waitcnt vmcnt(0)
;     ...
;         E(acc, cur, wr, wc, fr, fq, lane);
;         if (!has_next) break;
;     __device__ __forceinline__ void operator()(const f32x4 (&acc)[2][2][4][2], const Unit& u, int wr, int wc, int fr, int fq, int lane) const {
;     ...
; #pragma unroll
;         for (int ai = 0; ai < 2; ++ai)
; #pragma unroll
;           for (int mh = 0; mh < 2; ++mh) {
;             f32x4 bs[2][2][2];
; #pragma unroll
;             for (int m2 = 0; m2 < 2; ++m2) {
;                 const size_t ro = (r0 + ai * HALF + wr * 64 + (mh * 2 + m2) * 16 + fr) * (size_t)D;
; #pragma unroll
;                 for (int bj = 0; bj < 2; ++bj)
; #pragma unroll
;                     for (int n = 0; n < 2; ++n) bs[m2][bj][n] = *(const f32x4*)(base + ro + bj * HALF + n * 16);
;             }
;             __builtin_amdgcn_sched_barrier(0);
; #pragma unroll
;             for (int m2 = 0; m2 < 2; ++m2) {
;                 const size_t ro = (r0 + ai * HALF + wr * 64 + (mh * 2 + m2) * 16 + fr) * (size_t)D;
; #pragma unroll
;                 for (int bj = 0; bj < 2; ++bj)
; #pragma unroll
;                     for (int n = 0; n < 2; ++n) *(f32x4*)(out + ro + bj * HALF + n * 16) = bs[m2][bj][n] + gv[bj][n] * acc[ai][bj][mh * 2 + m2][n];
;             }
;             __builtin_amdgcn_sched_barrier(0);
;           }
	v_pk_fma_f32 v[82:83], v[82:83], v[134:135], v[106:107]
	v_pk_fma_f32 v[80:81], v[80:81], v[132:133], v[104:105]
	v_pk_fma_f32 v[74:75], v[74:75], v[130:131], v[110:111]
	v_pk_fma_f32 v[72:73], v[72:73], v[128:129], v[108:109]
	global_store_dwordx4 v[174:175], v[80:83], off offset:512
	global_store_dwordx4 v[174:175], v[72:75], off offset:576
	v_pk_fma_f32 v[94:95], v[94:95], v[142:143], v[98:99]
	v_lshl_add_u64 v[80:81], v[228:229], 0, v[224:225]
	v_pk_fma_f32 v[74:75], v[86:87], v[142:143], v[114:115]
	v_pk_fma_f32 v[72:73], v[84:85], v[140:141], v[112:113]
	v_pk_fma_f32 v[92:93], v[92:93], v[140:141], v[96:97]
	v_pk_fma_f32 v[90:91], v[90:91], v[138:139], v[102:103]
	v_pk_fma_f32 v[88:89], v[88:89], v[136:137], v[100:101]
	global_store_dwordx4 v[80:81], v[72:75], off
	v_pk_fma_f32 v[70:71], v[70:71], v[134:135], v[122:123]
	v_pk_fma_f32 v[68:69], v[68:69], v[132:133], v[120:121]
	v_pk_fma_f32 v[74:75], v[78:79], v[138:139], v[118:119]
	v_pk_fma_f32 v[72:73], v[76:77], v[136:137], v[116:117]
	v_pk_fma_f32 v[66:67], v[66:67], v[130:131], v[126:127]
	v_pk_fma_f32 v[64:65], v[64:65], v[128:129], v[124:125]
	global_store_dwordx4 v[174:175], v[92:95], off
	global_store_dwordx4 v[174:175], v[88:91], off offset:64
	global_store_dwordx4 v[80:81], v[72:75], off offset:64
	global_store_dwordx4 v[80:81], v[68:71], off offset:512
	global_store_dwordx4 v[80:81], v[64:67], off offset:576
	s_mov_b32 s3, 0x100000
	v_add_co_u32_e32 v72, vcc, s3, v168
	s_mov_b32 s8, 0x120000
	s_nop 0
	v_addc_co_u32_e32 v73, vcc, 0, v169, vcc
	s_mov_b64 s[0:1], 0x100000
	s_mov_b64 s[10:11], 0x120000
	v_add_co_u32_e32 v88, vcc, s8, v168
	v_lshl_add_u64 v[76:77], v[168:169], 0, s[0:1]
	v_lshl_add_u64 v[92:93], v[168:169], 0, s[10:11]
	v_addc_co_u32_e32 v89, vcc, 0, v169, vcc
	global_load_dwordx4 v[64:67], v[76:77], off offset:64
	global_load_dwordx4 v[68:71], v[76:77], off offset:512
	s_nop 0
	global_load_dwordx4 v[72:75], v[72:73], off
	s_nop 0
	global_load_dwordx4 v[76:79], v[76:77], off offset:576
	s_nop 0
	global_load_dwordx4 v[80:83], v[92:93], off offset:64
	global_load_dwordx4 v[84:87], v[92:93], off offset:512
	s_nop 0
	global_load_dwordx4 v[88:91], v[88:89], off
	s_nop 0
	global_load_dwordx4 v[92:95], v[92:93], off offset:576
	s_waitcnt vmcnt(0)
	v_pk_fma_f32 v[60:61], v[60:61], v[140:141], v[72:73]
	v_add_co_u32_e32 v72, vcc, s3, v158
	v_lshl_add_u64 v[96:97], v[158:159], 0, s[0:1]
	s_nop 0
	v_addc_co_u32_e32 v73, vcc, 0, v159, vcc
	v_pk_fma_f32 v[50:51], v[50:51], v[134:135], v[70:71]
	v_pk_fma_f32 v[48:49], v[48:49], v[132:133], v[68:69]
	global_store_dwordx4 v[96:97], v[48:51], off offset:512
	v_pk_fma_f32 v[46:47], v[46:47], v[130:131], v[78:79]
	v_pk_fma_f32 v[44:45], v[44:45], v[128:129], v[76:77]
	v_add_co_u32_e32 v50, vcc, s8, v158
	s_mov_b64 s[74:75], 0x100000
	v_pk_fma_f32 v[62:63], v[62:63], v[142:143], v[74:75]
	s_mov_b32 s76, 0x100000
	v_pk_fma_f32 v[58:59], v[58:59], v[138:139], v[66:67]
	v_pk_fma_f32 v[56:57], v[56:57], v[136:137], v[64:65]
	global_store_dwordx4 v[96:97], v[44:47], off offset:576
	v_lshl_add_u64 v[48:49], v[158:159], 0, s[10:11]
	s_mov_b32 s77, 0x120000
	v_pk_fma_f32 v[46:47], v[54:55], v[142:143], v[90:91]
	v_pk_fma_f32 v[44:45], v[52:53], v[140:141], v[88:89]
	v_addc_co_u32_e32 v51, vcc, 0, v159, vcc
	v_pk_fma_f32 v[42:43], v[42:43], v[138:139], v[82:83]
	v_pk_fma_f32 v[40:41], v[40:41], v[136:137], v[80:81]
	v_pk_fma_f32 v[38:39], v[38:39], v[134:135], v[86:87]
	v_pk_fma_f32 v[36:37], v[36:37], v[132:133], v[84:85]
	v_pk_fma_f32 v[34:35], v[34:35], v[130:131], v[94:95]
	v_pk_fma_f32 v[32:33], v[32:33], v[128:129], v[92:93]
	global_store_dwordx4 v[72:73], v[60:63], off
	global_store_dwordx4 v[96:97], v[56:59], off offset:64
	global_store_dwordx4 v[50:51], v[44:47], off
	global_store_dwordx4 v[48:49], v[40:43], off offset:64
	global_store_dwordx4 v[48:49], v[36:39], off offset:512
	global_store_dwordx4 v[48:49], v[32:35], off offset:576
	s_mov_b32 s0, 0x140000
	v_add_co_u32_e32 v40, vcc, s0, v168
	s_mov_b32 s1, 0x160000
	s_nop 0
	v_addc_co_u32_e32 v41, vcc, 0, v169, vcc
	s_mov_b64 s[8:9], 0x140000
	s_mov_b64 s[10:11], 0x160000
	v_add_co_u32_e32 v56, vcc, s1, v168
	v_lshl_add_u64 v[44:45], v[168:169], 0, s[8:9]
	v_lshl_add_u64 v[60:61], v[168:169], 0, s[10:11]
	v_addc_co_u32_e32 v57, vcc, 0, v169, vcc
	global_load_dwordx4 v[32:35], v[44:45], off offset:64
	global_load_dwordx4 v[36:39], v[44:45], off offset:512
	s_nop 0
	global_load_dwordx4 v[40:43], v[40:41], off
	s_nop 0
	global_load_dwordx4 v[44:47], v[44:45], off offset:576
	s_nop 0
	global_load_dwordx4 v[48:51], v[60:61], off offset:64
	global_load_dwordx4 v[52:55], v[60:61], off offset:512
	s_nop 0
	global_load_dwordx4 v[56:59], v[56:57], off
	s_nop 0
	global_load_dwordx4 v[60:63], v[60:61], off offset:576
	s_waitcnt vmcnt(0)
	v_pk_fma_f32 v[28:29], v[28:29], v[140:141], v[40:41]
	v_add_co_u32_e32 v40, vcc, s0, v158
	v_lshl_add_u64 v[64:65], v[158:159], 0, s[8:9]
	s_nop 0
	v_addc_co_u32_e32 v41, vcc, 0, v159, vcc
	v_pk_fma_f32 v[18:19], v[18:19], v[134:135], v[38:39]
	v_pk_fma_f32 v[16:17], v[16:17], v[132:133], v[36:37]
	global_store_dwordx4 v[64:65], v[16:19], off offset:512
	v_pk_fma_f32 v[14:15], v[14:15], v[130:131], v[46:47]
	v_pk_fma_f32 v[12:13], v[12:13], v[128:129], v[44:45]
	v_add_co_u32_e32 v18, vcc, s1, v158
	v_pk_fma_f32 v[30:31], v[30:31], v[142:143], v[42:43]
	s_mov_b32 s18, 0x140000
	v_pk_fma_f32 v[26:27], v[26:27], v[138:139], v[34:35]
	v_pk_fma_f32 v[24:25], v[24:25], v[136:137], v[32:33]
	global_store_dwordx4 v[64:65], v[12:15], off offset:576
	v_lshl_add_u64 v[16:17], v[158:159], 0, s[10:11]
	s_mov_b32 s54, 0x160000
	v_pk_fma_f32 v[14:15], v[22:23], v[142:143], v[58:59]
	v_pk_fma_f32 v[12:13], v[20:21], v[140:141], v[56:57]
	v_addc_co_u32_e32 v19, vcc, 0, v159, vcc
	v_pk_fma_f32 v[10:11], v[10:11], v[138:139], v[50:51]
	v_pk_fma_f32 v[8:9], v[8:9], v[136:137], v[48:49]
	v_pk_fma_f32 v[6:7], v[6:7], v[134:135], v[54:55]
	v_pk_fma_f32 v[4:5], v[4:5], v[132:133], v[52:53]
	v_pk_fma_f32 v[2:3], v[2:3], v[130:131], v[62:63]
	v_pk_fma_f32 v[0:1], v[0:1], v[128:129], v[60:61]
	global_store_dwordx4 v[40:41], v[28:31], off
	global_store_dwordx4 v[64:65], v[24:27], off offset:64
	global_store_dwordx4 v[18:19], v[12:15], off
	global_store_dwordx4 v[16:17], v[8:11], off offset:64
	global_store_dwordx4 v[16:17], v[4:7], off offset:512
	global_store_dwordx4 v[16:17], v[0:3], off offset:576
	s_and_b64 vcc, exec, s[40:41]
	s_mov_b32 s8, s2
	s_mov_b32 s9, s26
	s_mov_b64 s[20:21], s[38:39]
	s_mov_b64 s[0:1], s[36:37]
	s_cbranch_vccz .LBB0_1226
	s_waitcnt vmcnt(0)
	v_readlane_b32 s52, v255, 4
	s_cmpk_gt_u32 s4, 0xff
	v_readlane_b32 s53, v255, 5
	s_cbranch_scc1 .LBB0_1233
	s_barrier
